# barrier: non-leaders poll the top-level generation word directly
# baseline (speedup 1.0000x reference)
; __device__ __forceinline__ unsigned cvt_pk_bf16(float lo, float hi) { unsigned r; asm volatile("v_cvt_pk_bf16_f32 %0, %1, %2" : "=v"(r) : "v"(lo), "v"(hi)); return r; }
; template <bool BR, bool WH> ...
;     ...
;         if (WH) {
;             float s = 0.f;
; #pragma unroll
;             for (int j = 0; j < 4; ++j) s += (x[j][0] * x[j][0] + x[j][1] * x[j][1]) + (x[j][2] * x[j][2] + x[j][3] * x[j][3]);
;             const float rs = rsqrtf(wave_sum(s, lane) * (1.f / 1024.f) + EPS);
; #pragma unroll
;             for (int j = 0; j < 4; ++j) { const f32x4 gp = *(const f32x4*)(g_pre + 4 * lane + 256 * j), sc = *(const f32x4*)(mod_h + (size_t)mrow * 6144 + sc_off + 4 * lane + 256 * j),
;                     sh = *(const f32x4*)(mod_h + (size_t)mrow * 6144 + sh_off + 4 * lane + 256 * j);
;                 const f32x4 hv = ((x[j] * rs) * gp) * (sc + 1.0f) + sh;
;                 u32x2 w; w.x = cvt_pk_bf16(hv[0], hv[1]); w.y = cvt_pk_bf16(hv[2], hv[3]);
;                 *(u32x2*)(Hout + (size_t)row * 1024 + 4 * lane + 256 * j) = w; }
;         }
.Lnrm_A_ctx_loop:
	s_cmpk_lt_u32 s32, 0x400
	s_cbranch_scc0 .Lnrm_A_ctx_done
	s_lshl_b32 s97, s32, 12
	s_add_u32 s4, s48, s97
	s_addc_u32 s5, s49, 0
	s_lshl_b32 s97, s32, 11
	s_add_u32 s16, s56, s97
	s_addc_u32 s17, s57, 0
	s_add_u32 s16, s16, 0x2000000
	s_addc_u32 s17, s17, 0
	global_load_dwordx4 v[106:109], v0, s[4:5] offset:0 nt
	global_load_dwordx4 v[110:113], v0, s[4:5] offset:1024 nt
	global_load_dwordx4 v[114:117], v0, s[4:5] offset:2048 nt
	global_load_dwordx4 v[118:121], v0, s[4:5] offset:3072 nt
	s_mov_b32 s88, 0x18000
	global_load_dwordx4 v[192:195], v0, s[24:25] offset:0
	global_load_dwordx4 v[196:199], v0, s[24:25] offset:1024
	global_load_dwordx4 v[200:203], v0, s[24:25] offset:2048
	global_load_dwordx4 v[204:207], v0, s[24:25] offset:3072
	s_add_u32 s98, s88, s59
	s_add_u32 s98, s98, s40
	s_addc_u32 s99, s41, 0
	s_add_u32 s98, s98, 0x1600000
	s_addc_u32 s99, s99, 0
	global_load_dwordx4 v[208:211], v0, s[98:99] offset:0
	global_load_dwordx4 v[212:215], v0, s[98:99] offset:1024
	global_load_dwordx4 v[220:223], v0, s[98:99] offset:2048
	global_load_dwordx4 v[224:227], v0, s[98:99] offset:3072
	s_add_u32 s98, s88, s73
	s_add_u32 s98, s98, s40
	s_addc_u32 s99, s41, 0
	s_add_u32 s98, s98, 0x1600000
	s_addc_u32 s99, s99, 0
	global_load_dwordx4 v[228:231], v0, s[98:99] offset:0
	global_load_dwordx4 v[232:235], v0, s[98:99] offset:1024
	global_load_dwordx4 v[236:239], v0, s[98:99] offset:2048
	global_load_dwordx4 v[26:29], v0, s[98:99] offset:3072
	s_waitcnt vmcnt(0)
	v_pk_add_f32 v[208:209], v[208:209], 1.0 op_sel_hi:[1,0]
	v_pk_add_f32 v[210:211], v[210:211], 1.0 op_sel_hi:[1,0]
	v_pk_add_f32 v[212:213], v[212:213], 1.0 op_sel_hi:[1,0]
	v_pk_add_f32 v[214:215], v[214:215], 1.0 op_sel_hi:[1,0]
	v_pk_add_f32 v[220:221], v[220:221], 1.0 op_sel_hi:[1,0]
	v_pk_add_f32 v[222:223], v[222:223], 1.0 op_sel_hi:[1,0]
	v_pk_add_f32 v[224:225], v[224:225], 1.0 op_sel_hi:[1,0]
	v_pk_add_f32 v[226:227], v[226:227], 1.0 op_sel_hi:[1,0]
	v_mul_f32_e32 v6, v106, v106
	v_mul_f32_e32 v7, v107, v107
	v_fmac_f32_e32 v6, v108, v108
	v_fmac_f32_e32 v7, v109, v109
	v_fmac_f32_e32 v6, v110, v110
	v_fmac_f32_e32 v7, v111, v111
	v_fmac_f32_e32 v6, v112, v112
	v_fmac_f32_e32 v7, v113, v113
	v_fmac_f32_e32 v6, v114, v114
	v_fmac_f32_e32 v7, v115, v115
	v_fmac_f32_e32 v6, v116, v116
	v_fmac_f32_e32 v7, v117, v117
	v_fmac_f32_e32 v6, v118, v118
	v_fmac_f32_e32 v7, v119, v119
	v_fmac_f32_e32 v6, v120, v120
	v_fmac_f32_e32 v7, v121, v121
	v_add_f32_e32 v6, v6, v7
	s_nop 1
	v_add_f32_dpp v8, v6, v6 quad_perm:[1,0,3,2] row_mask:0xf bank_mask:0xf
	s_nop 1
	v_add_f32_dpp v8, v8, v8 quad_perm:[2,3,0,1] row_mask:0xf bank_mask:0xf
	s_nop 1
	v_add_f32_dpp v8, v8, v8 row_half_mirror row_mask:0xf bank_mask:0xf
	s_nop 1
	v_add_f32_dpp v8, v8, v8 row_mirror row_mask:0xf bank_mask:0xf
	s_nop 1
	v_add_f32_dpp v8, v8, v8 row_bcast:15 row_mask:0xa bank_mask:0xf
	s_nop 1
	v_add_f32_dpp v8, v8, v8 row_bcast:31 row_mask:0xc bank_mask:0xf
	s_nop 1
	v_readlane_b32 s84, v8, 63
	s_nop 1
	v_fma_f32 v4, s84, v2, v3
	v_rsq_f32_e32 v4, v4
	s_nop 0
	v_pk_mul_f32 v[34:35], v[106:107], v[4:5] op_sel_hi:[1,0]
	v_pk_mul_f32 v[36:37], v[108:109], v[4:5] op_sel_hi:[1,0]
	v_pk_mul_f32 v[38:39], v[110:111], v[4:5] op_sel_hi:[1,0]
	v_pk_mul_f32 v[40:41], v[112:113], v[4:5] op_sel_hi:[1,0]
	v_pk_mul_f32 v[42:43], v[114:115], v[4:5] op_sel_hi:[1,0]
	v_pk_mul_f32 v[44:45], v[116:117], v[4:5] op_sel_hi:[1,0]
	v_pk_mul_f32 v[46:47], v[118:119], v[4:5] op_sel_hi:[1,0]
	v_pk_mul_f32 v[48:49], v[120:121], v[4:5] op_sel_hi:[1,0]
	v_pk_mul_f32 v[34:35], v[34:35], v[192:193]
	v_pk_mul_f32 v[36:37], v[36:37], v[194:195]
	v_pk_mul_f32 v[38:39], v[38:39], v[196:197]
	v_pk_mul_f32 v[40:41], v[40:41], v[198:199]
	v_pk_mul_f32 v[42:43], v[42:43], v[200:201]
	v_pk_mul_f32 v[44:45], v[44:45], v[202:203]
	v_pk_mul_f32 v[46:47], v[46:47], v[204:205]
	v_pk_mul_f32 v[48:49], v[48:49], v[206:207]
	v_pk_fma_f32 v[34:35], v[34:35], v[208:209], v[228:229]
	v_pk_fma_f32 v[36:37], v[36:37], v[210:211], v[230:231]
	v_pk_fma_f32 v[38:39], v[38:39], v[212:213], v[232:233]
	v_pk_fma_f32 v[40:41], v[40:41], v[214:215], v[234:235]
	v_pk_fma_f32 v[42:43], v[42:43], v[220:221], v[236:237]
	v_pk_fma_f32 v[44:45], v[44:45], v[222:223], v[238:239]
	v_pk_fma_f32 v[46:47], v[46:47], v[224:225], v[26:27]
	v_pk_fma_f32 v[48:49], v[48:49], v[226:227], v[28:29]
	v_cvt_pk_bf16_f32 v50, v34, v35
	v_cvt_pk_bf16_f32 v51, v36, v37
	v_cvt_pk_bf16_f32 v52, v38, v39
	v_cvt_pk_bf16_f32 v53, v40, v41
	v_cvt_pk_bf16_f32 v54, v42, v43
	v_cvt_pk_bf16_f32 v55, v44, v45
	v_cvt_pk_bf16_f32 v56, v46, v47
	v_cvt_pk_bf16_f32 v57, v48, v49
	global_store_dwordx2 v1, v[50:51], s[16:17] offset:0
	global_store_dwordx2 v1, v[52:53], s[16:17] offset:512
	global_store_dwordx2 v1, v[54:55], s[16:17] offset:1024
	global_store_dwordx2 v1, v[56:57], s[16:17] offset:1536
	s_add_u32 s32, s32, s27
	s_branch .Lnrm_A_ctx_loop

; __device__ __forceinline__ unsigned cvt_pk_bf16(float lo, float hi) { unsigned r; asm volatile("v_cvt_pk_bf16_f32 %0, %1, %2" : "=v"(r) : "v"(lo), "v"(hi)); return r; }
; __device__ __forceinline__ float bflo(unsigned w) { return __uint_as_float(w << 16); }
; __device__ __forceinline__ float bfhi(unsigned w) { return __uint_as_float(w & 0xffff0000u); }
; template <bool BR, bool WH> ...
;     ...
;     for (int row = gw; row < nrows; row += NGW) {
;         const bool hn = row + NGW < nrows;
;         if (hn) NORM_LOAD(row + NGW, xn, bn);
;         const int mrow = row < ML ? (row >> 12) : 4;
;         f32x4 x[4];
; #pragma unroll
;         for (int j = 0; j < 4; ++j) x[j] = xc[j];
;         if (BR) {
;             f32x4 m[4]; float s = 0.f;
; #pragma unroll
;             for (int j = 0; j < 4; ++j) { m[j] = (f32x4){bflo(bc[j].x), bfhi(bc[j].x), bflo(bc[j].y), bfhi(bc[j].y)};
;                 s += (m[j][0] * m[j][0] + m[j][1] * m[j][1]) + (m[j][2] * m[j][2] + m[j][3] * m[j][3]); }
;             const float rs = rsqrtf(wave_sum(s, lane) * (1.f / 1024.f) + EPS);
;             float* xo = row < ML ? xout_lat + (size_t)row * 1024 : xout_ctx + (size_t)(row - ML) * 1024;
; #pragma unroll
;             for (int j = 0; j < 4; ++j) { const f32x4 gp = *(const f32x4*)(g_post + 4 * lane + 256 * j), ga = *(const f32x4*)(mod_g + (size_t)mrow * 6144 + gate_off + 4 * lane + 256 * j);
;                 x[j] = x[j] + ga * ((m[j] * rs) * gp); __builtin_nontemporal_store(x[j], (f32x4*)(xo + 4 * lane + 256 * j)); }
;         }
;         if (WH) {
;             float s = 0.f;
; #pragma unroll
;             for (int j = 0; j < 4; ++j) s += (x[j][0] * x[j][0] + x[j][1] * x[j][1]) + (x[j][2] * x[j][2] + x[j][3] * x[j][3]);
;             const float rs = rsqrtf(wave_sum(s, lane) * (1.f / 1024.f) + EPS);
; #pragma unroll
;             for (int j = 0; j < 4; ++j) { const f32x4 gp = *(const f32x4*)(g_pre + 4 * lane + 256 * j), sc = *(const f32x4*)(mod_h + (size_t)mrow * 6144 + sc_off + 4 * lane + 256 * j),
;                     sh = *(const f32x4*)(mod_h + (size_t)mrow * 6144 + sh_off + 4 * lane + 256 * j);
;                 const f32x4 hv = ((x[j] * rs) * gp) * (sc + 1.0f) + sh;
;                 u32x2 w; w.x = cvt_pk_bf16(hv[0], hv[1]); w.y = cvt_pk_bf16(hv[2], hv[3]);
;                 *(u32x2*)(Hout + (size_t)row * 1024 + 4 * lane + 256 * j) = w; }
;         }
.Lnrm_A_lat_loop:
	s_cmpk_lt_u32 s32, 0x800
	s_cbranch_scc0 .LBB0_8
	s_lshl_b32 s97, s32, 15
	s_add_u32 s4, s44, s97
	s_addc_u32 s5, s45, 0
	s_lshl_b32 s97, s32, 14
	s_add_u32 s16, s56, s97
	s_addc_u32 s17, s57, 0
	s_lshr_b32 s88, s32, 9
	s_mul_i32 s88, s88, 0x6000
	global_load_dwordx4 v[58:61], v0, s[4:5] offset:0 nt
	global_load_dwordx4 v[62:65], v0, s[4:5] offset:1024 nt
	global_load_dwordx4 v[66:69], v0, s[4:5] offset:2048 nt
	global_load_dwordx4 v[70:73], v0, s[4:5] offset:3072 nt
	s_add_u32 s4, s4, 0x1000
	s_addc_u32 s5, s5, 0
	global_load_dwordx4 v[192:195], v0, s[24:25] offset:0
	global_load_dwordx4 v[196:199], v0, s[24:25] offset:1024
	global_load_dwordx4 v[200:203], v0, s[24:25] offset:2048
	global_load_dwordx4 v[204:207], v0, s[24:25] offset:3072
	s_add_u32 s98, s88, s59
	s_add_u32 s98, s98, s40
	s_addc_u32 s99, s41, 0
	s_add_u32 s98, s98, 0x1600000
	s_addc_u32 s99, s99, 0
	global_load_dwordx4 v[208:211], v0, s[98:99] offset:0
	global_load_dwordx4 v[212:215], v0, s[98:99] offset:1024
	global_load_dwordx4 v[220:223], v0, s[98:99] offset:2048
	global_load_dwordx4 v[224:227], v0, s[98:99] offset:3072
	s_add_u32 s98, s88, s73
	s_add_u32 s98, s98, s40
	s_addc_u32 s99, s41, 0
	s_add_u32 s98, s98, 0x1600000
	s_addc_u32 s99, s99, 0
	global_load_dwordx4 v[228:231], v0, s[98:99] offset:0
	global_load_dwordx4 v[232:235], v0, s[98:99] offset:1024
	global_load_dwordx4 v[236:239], v0, s[98:99] offset:2048
	global_load_dwordx4 v[26:29], v0, s[98:99] offset:3072
	global_load_dwordx4 v[74:77], v0, s[4:5] offset:0 nt
	global_load_dwordx4 v[78:81], v0, s[4:5] offset:1024 nt
	global_load_dwordx4 v[82:85], v0, s[4:5] offset:2048 nt
	global_load_dwordx4 v[86:89], v0, s[4:5] offset:3072 nt
	s_add_u32 s4, s4, 0x1000
	s_addc_u32 s5, s5, 0
	global_load_dwordx4 v[90:93], v0, s[4:5] offset:0 nt
	global_load_dwordx4 v[94:97], v0, s[4:5] offset:1024 nt
	global_load_dwordx4 v[98:101], v0, s[4:5] offset:2048 nt
	global_load_dwordx4 v[102:105], v0, s[4:5] offset:3072 nt
	s_add_u32 s4, s4, 0x1000
	s_addc_u32 s5, s5, 0
	global_load_dwordx4 v[106:109], v0, s[4:5] offset:0 nt
	global_load_dwordx4 v[110:113], v0, s[4:5] offset:1024 nt
	global_load_dwordx4 v[114:117], v0, s[4:5] offset:2048 nt
	global_load_dwordx4 v[118:121], v0, s[4:5] offset:3072 nt
	s_add_u32 s4, s4, 0x1000
	s_addc_u32 s5, s5, 0
	s_waitcnt vmcnt(12)
	v_pk_add_f32 v[208:209], v[208:209], 1.0 op_sel_hi:[1,0]
	v_pk_add_f32 v[210:211], v[210:211], 1.0 op_sel_hi:[1,0]
	v_pk_add_f32 v[212:213], v[212:213], 1.0 op_sel_hi:[1,0]
	v_pk_add_f32 v[214:215], v[214:215], 1.0 op_sel_hi:[1,0]
	v_pk_add_f32 v[220:221], v[220:221], 1.0 op_sel_hi:[1,0]
	v_pk_add_f32 v[222:223], v[222:223], 1.0 op_sel_hi:[1,0]
	v_pk_add_f32 v[224:225], v[224:225], 1.0 op_sel_hi:[1,0]
	v_pk_add_f32 v[226:227], v[226:227], 1.0 op_sel_hi:[1,0]
	v_mul_f32_e32 v6, v58, v58
	v_mul_f32_e32 v7, v59, v59
	v_fmac_f32_e32 v6, v60, v60
	v_fmac_f32_e32 v7, v61, v61
	v_fmac_f32_e32 v6, v62, v62
	v_fmac_f32_e32 v7, v63, v63
	v_fmac_f32_e32 v6, v64, v64
	v_fmac_f32_e32 v7, v65, v65
	v_fmac_f32_e32 v6, v66, v66
	v_fmac_f32_e32 v7, v67, v67
	v_fmac_f32_e32 v6, v68, v68
	v_fmac_f32_e32 v7, v69, v69
	v_fmac_f32_e32 v6, v70, v70
	v_fmac_f32_e32 v7, v71, v71
	v_fmac_f32_e32 v6, v72, v72
	v_fmac_f32_e32 v7, v73, v73
	v_add_f32_e32 v6, v6, v7
	s_nop 1
	v_add_f32_dpp v8, v6, v6 quad_perm:[1,0,3,2] row_mask:0xf bank_mask:0xf
	s_nop 1
	v_add_f32_dpp v8, v8, v8 quad_perm:[2,3,0,1] row_mask:0xf bank_mask:0xf
	s_nop 1
	v_add_f32_dpp v8, v8, v8 row_half_mirror row_mask:0xf bank_mask:0xf
	s_nop 1
	v_add_f32_dpp v8, v8, v8 row_mirror row_mask:0xf bank_mask:0xf
	s_nop 1
	v_add_f32_dpp v8, v8, v8 row_bcast:15 row_mask:0xa bank_mask:0xf
	s_nop 1
	v_add_f32_dpp v8, v8, v8 row_bcast:31 row_mask:0xc bank_mask:0xf
	s_nop 1
	v_readlane_b32 s84, v8, 63
	s_nop 1
	v_fma_f32 v4, s84, v2, v3
	v_rsq_f32_e32 v4, v4
	s_nop 0
	v_pk_mul_f32 v[34:35], v[58:59], v[4:5] op_sel_hi:[1,0]
	v_pk_mul_f32 v[36:37], v[60:61], v[4:5] op_sel_hi:[1,0]
	v_pk_mul_f32 v[38:39], v[62:63], v[4:5] op_sel_hi:[1,0]
	v_pk_mul_f32 v[40:41], v[64:65], v[4:5] op_sel_hi:[1,0]
	v_pk_mul_f32 v[42:43], v[66:67], v[4:5] op_sel_hi:[1,0]
	v_pk_mul_f32 v[44:45], v[68:69], v[4:5] op_sel_hi:[1,0]
	v_pk_mul_f32 v[46:47], v[70:71], v[4:5] op_sel_hi:[1,0]
	v_pk_mul_f32 v[48:49], v[72:73], v[4:5] op_sel_hi:[1,0]
	v_pk_mul_f32 v[34:35], v[34:35], v[192:193]
	v_pk_mul_f32 v[36:37], v[36:37], v[194:195]
	v_pk_mul_f32 v[38:39], v[38:39], v[196:197]
	v_pk_mul_f32 v[40:41], v[40:41], v[198:199]
	v_pk_mul_f32 v[42:43], v[42:43], v[200:201]
	v_pk_mul_f32 v[44:45], v[44:45], v[202:203]
	v_pk_mul_f32 v[46:47], v[46:47], v[204:205]
	v_pk_mul_f32 v[48:49], v[48:49], v[206:207]
	v_pk_fma_f32 v[34:35], v[34:35], v[208:209], v[228:229]
	v_pk_fma_f32 v[36:37], v[36:37], v[210:211], v[230:231]
	v_pk_fma_f32 v[38:39], v[38:39], v[212:213], v[232:233]
	v_pk_fma_f32 v[40:41], v[40:41], v[214:215], v[234:235]
	v_pk_fma_f32 v[42:43], v[42:43], v[220:221], v[236:237]
	v_pk_fma_f32 v[44:45], v[44:45], v[222:223], v[238:239]
	v_pk_fma_f32 v[46:47], v[46:47], v[224:225], v[26:27]
	v_pk_fma_f32 v[48:49], v[48:49], v[226:227], v[28:29]
	v_cvt_pk_bf16_f32 v50, v34, v35
	v_cvt_pk_bf16_f32 v51, v36, v37
	v_cvt_pk_bf16_f32 v52, v38, v39
	v_cvt_pk_bf16_f32 v53, v40, v41
	v_cvt_pk_bf16_f32 v54, v42, v43
	v_cvt_pk_bf16_f32 v55, v44, v45
	v_cvt_pk_bf16_f32 v56, v46, v47
	v_cvt_pk_bf16_f32 v57, v48, v49
	global_store_dwordx2 v1, v[50:51], s[16:17] offset:0
	global_store_dwordx2 v1, v[52:53], s[16:17] offset:512
	global_store_dwordx2 v1, v[54:55], s[16:17] offset:1024
	global_store_dwordx2 v1, v[56:57], s[16:17] offset:1536
	s_add_u32 s16, s16, 0x800
	s_addc_u32 s17, s17, 0
	global_load_dwordx4 v[58:61], v0, s[4:5] offset:0 nt
	global_load_dwordx4 v[62:65], v0, s[4:5] offset:1024 nt
	global_load_dwordx4 v[66:69], v0, s[4:5] offset:2048 nt
	global_load_dwordx4 v[70:73], v0, s[4:5] offset:3072 nt
	s_add_u32 s4, s4, 0x1000
	s_addc_u32 s5, s5, 0
	s_waitcnt vmcnt(16)
; __device__ __forceinline__ unsigned cvt_pk_bf16(float lo, float hi) { unsigned r; asm volatile("v_cvt_pk_bf16_f32 %0, %1, %2" : "=v"(r) : "v"(lo), "v"(hi)); return r; }
; template <bool BR, bool WH> ...
;     ...
;         if (WH) {
;             float s = 0.f;
; #pragma unroll
;             for (int j = 0; j < 4; ++j) s += (x[j][0] * x[j][0] + x[j][1] * x[j][1]) + (x[j][2] * x[j][2] + x[j][3] * x[j][3]);
;             const float rs = rsqrtf(wave_sum(s, lane) * (1.f / 1024.f) + EPS);
; #pragma unroll
;             for (int j = 0; j < 4; ++j) { const f32x4 gp = *(const f32x4*)(g_pre + 4 * lane + 256 * j), sc = *(const f32x4*)(mod_h + (size_t)mrow * 6144 + sc_off + 4 * lane + 256 * j),
;                     sh = *(const f32x4*)(mod_h + (size_t)mrow * 6144 + sh_off + 4 * lane + 256 * j);
;                 const f32x4 hv = ((x[j] * rs) * gp) * (sc + 1.0f) + sh;
;                 u32x2 w; w.x = cvt_pk_bf16(hv[0], hv[1]); w.y = cvt_pk_bf16(hv[2], hv[3]);
;                 *(u32x2*)(Hout + (size_t)row * 1024 + 4 * lane + 256 * j) = w; }
;         }
	v_mul_f32_e32 v6, v74, v74
	v_mul_f32_e32 v7, v75, v75
	v_fmac_f32_e32 v6, v76, v76
	v_fmac_f32_e32 v7, v77, v77
	v_fmac_f32_e32 v6, v78, v78
	v_fmac_f32_e32 v7, v79, v79
	v_fmac_f32_e32 v6, v80, v80
	v_fmac_f32_e32 v7, v81, v81
	v_fmac_f32_e32 v6, v82, v82
	v_fmac_f32_e32 v7, v83, v83
	v_fmac_f32_e32 v6, v84, v84
	v_fmac_f32_e32 v7, v85, v85
	v_fmac_f32_e32 v6, v86, v86
	v_fmac_f32_e32 v7, v87, v87
	v_fmac_f32_e32 v6, v88, v88
	v_fmac_f32_e32 v7, v89, v89
	v_add_f32_e32 v6, v6, v7
	s_nop 1
	v_add_f32_dpp v8, v6, v6 quad_perm:[1,0,3,2] row_mask:0xf bank_mask:0xf
	s_nop 1
	v_add_f32_dpp v8, v8, v8 quad_perm:[2,3,0,1] row_mask:0xf bank_mask:0xf
	s_nop 1
	v_add_f32_dpp v8, v8, v8 row_half_mirror row_mask:0xf bank_mask:0xf
	s_nop 1
	v_add_f32_dpp v8, v8, v8 row_mirror row_mask:0xf bank_mask:0xf
	s_nop 1
	v_add_f32_dpp v8, v8, v8 row_bcast:15 row_mask:0xa bank_mask:0xf
	s_nop 1
	v_add_f32_dpp v8, v8, v8 row_bcast:31 row_mask:0xc bank_mask:0xf
	s_nop 1
	v_readlane_b32 s84, v8, 63
	s_nop 1
	v_fma_f32 v4, s84, v2, v3
	v_rsq_f32_e32 v4, v4
	s_nop 0
	v_pk_mul_f32 v[34:35], v[74:75], v[4:5] op_sel_hi:[1,0]
	v_pk_mul_f32 v[36:37], v[76:77], v[4:5] op_sel_hi:[1,0]
	v_pk_mul_f32 v[38:39], v[78:79], v[4:5] op_sel_hi:[1,0]
	v_pk_mul_f32 v[40:41], v[80:81], v[4:5] op_sel_hi:[1,0]
	v_pk_mul_f32 v[42:43], v[82:83], v[4:5] op_sel_hi:[1,0]
	v_pk_mul_f32 v[44:45], v[84:85], v[4:5] op_sel_hi:[1,0]
	v_pk_mul_f32 v[46:47], v[86:87], v[4:5] op_sel_hi:[1,0]
	v_pk_mul_f32 v[48:49], v[88:89], v[4:5] op_sel_hi:[1,0]
	v_pk_mul_f32 v[34:35], v[34:35], v[192:193]
	v_pk_mul_f32 v[36:37], v[36:37], v[194:195]
	v_pk_mul_f32 v[38:39], v[38:39], v[196:197]
	v_pk_mul_f32 v[40:41], v[40:41], v[198:199]
	v_pk_mul_f32 v[42:43], v[42:43], v[200:201]
	v_pk_mul_f32 v[44:45], v[44:45], v[202:203]
	v_pk_mul_f32 v[46:47], v[46:47], v[204:205]
	v_pk_mul_f32 v[48:49], v[48:49], v[206:207]
	v_pk_fma_f32 v[34:35], v[34:35], v[208:209], v[228:229]
	v_pk_fma_f32 v[36:37], v[36:37], v[210:211], v[230:231]
	v_pk_fma_f32 v[38:39], v[38:39], v[212:213], v[232:233]
	v_pk_fma_f32 v[40:41], v[40:41], v[214:215], v[234:235]
	v_pk_fma_f32 v[42:43], v[42:43], v[220:221], v[236:237]
	v_pk_fma_f32 v[44:45], v[44:45], v[222:223], v[238:239]
	v_pk_fma_f32 v[46:47], v[46:47], v[224:225], v[26:27]
	v_pk_fma_f32 v[48:49], v[48:49], v[226:227], v[28:29]
	v_cvt_pk_bf16_f32 v50, v34, v35
	v_cvt_pk_bf16_f32 v51, v36, v37
	v_cvt_pk_bf16_f32 v52, v38, v39
	v_cvt_pk_bf16_f32 v53, v40, v41
	v_cvt_pk_bf16_f32 v54, v42, v43
	v_cvt_pk_bf16_f32 v55, v44, v45
	v_cvt_pk_bf16_f32 v56, v46, v47
	v_cvt_pk_bf16_f32 v57, v48, v49
	global_store_dwordx2 v1, v[50:51], s[16:17] offset:0
	global_store_dwordx2 v1, v[52:53], s[16:17] offset:512
	global_store_dwordx2 v1, v[54:55], s[16:17] offset:1024
	global_store_dwordx2 v1, v[56:57], s[16:17] offset:1536
	s_add_u32 s16, s16, 0x800
	s_addc_u32 s17, s17, 0
	global_load_dwordx4 v[74:77], v0, s[4:5] offset:0 nt
	global_load_dwordx4 v[78:81], v0, s[4:5] offset:1024 nt
	global_load_dwordx4 v[82:85], v0, s[4:5] offset:2048 nt
	global_load_dwordx4 v[86:89], v0, s[4:5] offset:3072 nt
	s_add_u32 s4, s4, 0x1000
	s_addc_u32 s5, s5, 0
	s_waitcnt vmcnt(20)
	v_mul_f32_e32 v6, v90, v90
	v_mul_f32_e32 v7, v91, v91
	v_fmac_f32_e32 v6, v92, v92
	v_fmac_f32_e32 v7, v93, v93
	v_fmac_f32_e32 v6, v94, v94
	v_fmac_f32_e32 v7, v95, v95
	v_fmac_f32_e32 v6, v96, v96
	v_fmac_f32_e32 v7, v97, v97
	v_fmac_f32_e32 v6, v98, v98
	v_fmac_f32_e32 v7, v99, v99
	v_fmac_f32_e32 v6, v100, v100
	v_fmac_f32_e32 v7, v101, v101
	v_fmac_f32_e32 v6, v102, v102
	v_fmac_f32_e32 v7, v103, v103
	v_fmac_f32_e32 v6, v104, v104
	v_fmac_f32_e32 v7, v105, v105
	v_add_f32_e32 v6, v6, v7
	s_nop 1
	v_add_f32_dpp v8, v6, v6 quad_perm:[1,0,3,2] row_mask:0xf bank_mask:0xf
	s_nop 1
	v_add_f32_dpp v8, v8, v8 quad_perm:[2,3,0,1] row_mask:0xf bank_mask:0xf
	s_nop 1
	v_add_f32_dpp v8, v8, v8 row_half_mirror row_mask:0xf bank_mask:0xf
	s_nop 1
	v_add_f32_dpp v8, v8, v8 row_mirror row_mask:0xf bank_mask:0xf
	s_nop 1
	v_add_f32_dpp v8, v8, v8 row_bcast:15 row_mask:0xa bank_mask:0xf
	s_nop 1
	v_add_f32_dpp v8, v8, v8 row_bcast:31 row_mask:0xc bank_mask:0xf
	s_nop 1
	v_readlane_b32 s84, v8, 63
	s_nop 1
	v_fma_f32 v4, s84, v2, v3
	v_rsq_f32_e32 v4, v4
	s_nop 0
	v_pk_mul_f32 v[34:35], v[90:91], v[4:5] op_sel_hi:[1,0]
	v_pk_mul_f32 v[36:37], v[92:93], v[4:5] op_sel_hi:[1,0]
	v_pk_mul_f32 v[38:39], v[94:95], v[4:5] op_sel_hi:[1,0]
	v_pk_mul_f32 v[40:41], v[96:97], v[4:5] op_sel_hi:[1,0]
	v_pk_mul_f32 v[42:43], v[98:99], v[4:5] op_sel_hi:[1,0]
	v_pk_mul_f32 v[44:45], v[100:101], v[4:5] op_sel_hi:[1,0]
	v_pk_mul_f32 v[46:47], v[102:103], v[4:5] op_sel_hi:[1,0]
	v_pk_mul_f32 v[48:49], v[104:105], v[4:5] op_sel_hi:[1,0]
	v_pk_mul_f32 v[34:35], v[34:35], v[192:193]
	v_pk_mul_f32 v[36:37], v[36:37], v[194:195]
	v_pk_mul_f32 v[38:39], v[38:39], v[196:197]
	v_pk_mul_f32 v[40:41], v[40:41], v[198:199]
	v_pk_mul_f32 v[42:43], v[42:43], v[200:201]
	v_pk_mul_f32 v[44:45], v[44:45], v[202:203]
	v_pk_mul_f32 v[46:47], v[46:47], v[204:205]
	v_pk_mul_f32 v[48:49], v[48:49], v[206:207]
	v_pk_fma_f32 v[34:35], v[34:35], v[208:209], v[228:229]
	v_pk_fma_f32 v[36:37], v[36:37], v[210:211], v[230:231]
	v_pk_fma_f32 v[38:39], v[38:39], v[212:213], v[232:233]
	v_pk_fma_f32 v[40:41], v[40:41], v[214:215], v[234:235]
	v_pk_fma_f32 v[42:43], v[42:43], v[220:221], v[236:237]
	v_pk_fma_f32 v[44:45], v[44:45], v[222:223], v[238:239]
	v_pk_fma_f32 v[46:47], v[46:47], v[224:225], v[26:27]
	v_pk_fma_f32 v[48:49], v[48:49], v[226:227], v[28:29]
	v_cvt_pk_bf16_f32 v50, v34, v35
	v_cvt_pk_bf16_f32 v51, v36, v37
	v_cvt_pk_bf16_f32 v52, v38, v39
	v_cvt_pk_bf16_f32 v53, v40, v41
	v_cvt_pk_bf16_f32 v54, v42, v43
	v_cvt_pk_bf16_f32 v55, v44, v45
	v_cvt_pk_bf16_f32 v56, v46, v47
	v_cvt_pk_bf16_f32 v57, v48, v49
	global_store_dwordx2 v1, v[50:51], s[16:17] offset:0
	global_store_dwordx2 v1, v[52:53], s[16:17] offset:512
	global_store_dwordx2 v1, v[54:55], s[16:17] offset:1024
	global_store_dwordx2 v1, v[56:57], s[16:17] offset:1536
	s_add_u32 s16, s16, 0x800
	s_addc_u32 s17, s17, 0
	global_load_dwordx4 v[90:93], v0, s[4:5] offset:0 nt
	global_load_dwordx4 v[94:97], v0, s[4:5] offset:1024 nt
	global_load_dwordx4 v[98:101], v0, s[4:5] offset:2048 nt
	global_load_dwordx4 v[102:105], v0, s[4:5] offset:3072 nt
	s_add_u32 s4, s4, 0x1000
	s_addc_u32 s5, s5, 0
	s_waitcnt vmcnt(24)
; __device__ __forceinline__ unsigned cvt_pk_bf16(float lo, float hi) { unsigned r; asm volatile("v_cvt_pk_bf16_f32 %0, %1, %2" : "=v"(r) : "v"(lo), "v"(hi)); return r; }
; template <bool BR, bool WH> ...
;     ...
;         if (WH) {
;             float s = 0.f;
; #pragma unroll
;             for (int j = 0; j < 4; ++j) s += (x[j][0] * x[j][0] + x[j][1] * x[j][1]) + (x[j][2] * x[j][2] + x[j][3] * x[j][3]);
;             const float rs = rsqrtf(wave_sum(s, lane) * (1.f / 1024.f) + EPS);
; #pragma unroll
;             for (int j = 0; j < 4; ++j) { const f32x4 gp = *(const f32x4*)(g_pre + 4 * lane + 256 * j), sc = *(const f32x4*)(mod_h + (size_t)mrow * 6144 + sc_off + 4 * lane + 256 * j),
;                     sh = *(const f32x4*)(mod_h + (size_t)mrow * 6144 + sh_off + 4 * lane + 256 * j);
;                 const f32x4 hv = ((x[j] * rs) * gp) * (sc + 1.0f) + sh;
;                 u32x2 w; w.x = cvt_pk_bf16(hv[0], hv[1]); w.y = cvt_pk_bf16(hv[2], hv[3]);
;                 *(u32x2*)(Hout + (size_t)row * 1024 + 4 * lane + 256 * j) = w; }
;         }
	v_mul_f32_e32 v6, v106, v106
	v_mul_f32_e32 v7, v107, v107
	v_fmac_f32_e32 v6, v108, v108
	v_fmac_f32_e32 v7, v109, v109
	v_fmac_f32_e32 v6, v110, v110
	v_fmac_f32_e32 v7, v111, v111
	v_fmac_f32_e32 v6, v112, v112
	v_fmac_f32_e32 v7, v113, v113
	v_fmac_f32_e32 v6, v114, v114
	v_fmac_f32_e32 v7, v115, v115
	v_fmac_f32_e32 v6, v116, v116
	v_fmac_f32_e32 v7, v117, v117
	v_fmac_f32_e32 v6, v118, v118
	v_fmac_f32_e32 v7, v119, v119
	v_fmac_f32_e32 v6, v120, v120
	v_fmac_f32_e32 v7, v121, v121
	v_add_f32_e32 v6, v6, v7
	s_nop 1
	v_add_f32_dpp v8, v6, v6 quad_perm:[1,0,3,2] row_mask:0xf bank_mask:0xf
	s_nop 1
	v_add_f32_dpp v8, v8, v8 quad_perm:[2,3,0,1] row_mask:0xf bank_mask:0xf
	s_nop 1
	v_add_f32_dpp v8, v8, v8 row_half_mirror row_mask:0xf bank_mask:0xf
	s_nop 1
	v_add_f32_dpp v8, v8, v8 row_mirror row_mask:0xf bank_mask:0xf
	s_nop 1
	v_add_f32_dpp v8, v8, v8 row_bcast:15 row_mask:0xa bank_mask:0xf
	s_nop 1
	v_add_f32_dpp v8, v8, v8 row_bcast:31 row_mask:0xc bank_mask:0xf
	s_nop 1
	v_readlane_b32 s84, v8, 63
	s_nop 1
	v_fma_f32 v4, s84, v2, v3
	v_rsq_f32_e32 v4, v4
	s_nop 0
	v_pk_mul_f32 v[34:35], v[106:107], v[4:5] op_sel_hi:[1,0]
	v_pk_mul_f32 v[36:37], v[108:109], v[4:5] op_sel_hi:[1,0]
	v_pk_mul_f32 v[38:39], v[110:111], v[4:5] op_sel_hi:[1,0]
	v_pk_mul_f32 v[40:41], v[112:113], v[4:5] op_sel_hi:[1,0]
	v_pk_mul_f32 v[42:43], v[114:115], v[4:5] op_sel_hi:[1,0]
	v_pk_mul_f32 v[44:45], v[116:117], v[4:5] op_sel_hi:[1,0]
	v_pk_mul_f32 v[46:47], v[118:119], v[4:5] op_sel_hi:[1,0]
	v_pk_mul_f32 v[48:49], v[120:121], v[4:5] op_sel_hi:[1,0]
	v_pk_mul_f32 v[34:35], v[34:35], v[192:193]
	v_pk_mul_f32 v[36:37], v[36:37], v[194:195]
	v_pk_mul_f32 v[38:39], v[38:39], v[196:197]
	v_pk_mul_f32 v[40:41], v[40:41], v[198:199]
	v_pk_mul_f32 v[42:43], v[42:43], v[200:201]
	v_pk_mul_f32 v[44:45], v[44:45], v[202:203]
	v_pk_mul_f32 v[46:47], v[46:47], v[204:205]
	v_pk_mul_f32 v[48:49], v[48:49], v[206:207]
	v_pk_fma_f32 v[34:35], v[34:35], v[208:209], v[228:229]
	v_pk_fma_f32 v[36:37], v[36:37], v[210:211], v[230:231]
	v_pk_fma_f32 v[38:39], v[38:39], v[212:213], v[232:233]
	v_pk_fma_f32 v[40:41], v[40:41], v[214:215], v[234:235]
	v_pk_fma_f32 v[42:43], v[42:43], v[220:221], v[236:237]
	v_pk_fma_f32 v[44:45], v[44:45], v[222:223], v[238:239]
	v_pk_fma_f32 v[46:47], v[46:47], v[224:225], v[26:27]
	v_pk_fma_f32 v[48:49], v[48:49], v[226:227], v[28:29]
	v_cvt_pk_bf16_f32 v50, v34, v35
	v_cvt_pk_bf16_f32 v51, v36, v37
	v_cvt_pk_bf16_f32 v52, v38, v39
	v_cvt_pk_bf16_f32 v53, v40, v41
	v_cvt_pk_bf16_f32 v54, v42, v43
	v_cvt_pk_bf16_f32 v55, v44, v45
	v_cvt_pk_bf16_f32 v56, v46, v47
	v_cvt_pk_bf16_f32 v57, v48, v49
	global_store_dwordx2 v1, v[50:51], s[16:17] offset:0
	global_store_dwordx2 v1, v[52:53], s[16:17] offset:512
	global_store_dwordx2 v1, v[54:55], s[16:17] offset:1024
	global_store_dwordx2 v1, v[56:57], s[16:17] offset:1536
	s_add_u32 s16, s16, 0x800
	s_addc_u32 s17, s17, 0
	global_load_dwordx4 v[106:109], v0, s[4:5] offset:0 nt
	global_load_dwordx4 v[110:113], v0, s[4:5] offset:1024 nt
	global_load_dwordx4 v[114:117], v0, s[4:5] offset:2048 nt
	global_load_dwordx4 v[118:121], v0, s[4:5] offset:3072 nt
	s_add_u32 s4, s4, 0x1000
	s_addc_u32 s5, s5, 0
	s_waitcnt vmcnt(24)
	v_mul_f32_e32 v6, v58, v58
	v_mul_f32_e32 v7, v59, v59
	v_fmac_f32_e32 v6, v60, v60
	v_fmac_f32_e32 v7, v61, v61
	v_fmac_f32_e32 v6, v62, v62
	v_fmac_f32_e32 v7, v63, v63
	v_fmac_f32_e32 v6, v64, v64
	v_fmac_f32_e32 v7, v65, v65
	v_fmac_f32_e32 v6, v66, v66
	v_fmac_f32_e32 v7, v67, v67
	v_fmac_f32_e32 v6, v68, v68
	v_fmac_f32_e32 v7, v69, v69
	v_fmac_f32_e32 v6, v70, v70
	v_fmac_f32_e32 v7, v71, v71
	v_fmac_f32_e32 v6, v72, v72
	v_fmac_f32_e32 v7, v73, v73
	v_add_f32_e32 v6, v6, v7
	s_nop 1
	v_add_f32_dpp v8, v6, v6 quad_perm:[1,0,3,2] row_mask:0xf bank_mask:0xf
	s_nop 1
	v_add_f32_dpp v8, v8, v8 quad_perm:[2,3,0,1] row_mask:0xf bank_mask:0xf
	s_nop 1
	v_add_f32_dpp v8, v8, v8 row_half_mirror row_mask:0xf bank_mask:0xf
	s_nop 1
	v_add_f32_dpp v8, v8, v8 row_mirror row_mask:0xf bank_mask:0xf
	s_nop 1
	v_add_f32_dpp v8, v8, v8 row_bcast:15 row_mask:0xa bank_mask:0xf
	s_nop 1
	v_add_f32_dpp v8, v8, v8 row_bcast:31 row_mask:0xc bank_mask:0xf
	s_nop 1
	v_readlane_b32 s84, v8, 63
	s_nop 1
	v_fma_f32 v4, s84, v2, v3
	v_rsq_f32_e32 v4, v4
	s_nop 0
	v_pk_mul_f32 v[34:35], v[58:59], v[4:5] op_sel_hi:[1,0]
	v_pk_mul_f32 v[36:37], v[60:61], v[4:5] op_sel_hi:[1,0]
	v_pk_mul_f32 v[38:39], v[62:63], v[4:5] op_sel_hi:[1,0]
	v_pk_mul_f32 v[40:41], v[64:65], v[4:5] op_sel_hi:[1,0]
	v_pk_mul_f32 v[42:43], v[66:67], v[4:5] op_sel_hi:[1,0]
	v_pk_mul_f32 v[44:45], v[68:69], v[4:5] op_sel_hi:[1,0]
	v_pk_mul_f32 v[46:47], v[70:71], v[4:5] op_sel_hi:[1,0]
	v_pk_mul_f32 v[48:49], v[72:73], v[4:5] op_sel_hi:[1,0]
	v_pk_mul_f32 v[34:35], v[34:35], v[192:193]
	v_pk_mul_f32 v[36:37], v[36:37], v[194:195]
	v_pk_mul_f32 v[38:39], v[38:39], v[196:197]
	v_pk_mul_f32 v[40:41], v[40:41], v[198:199]
	v_pk_mul_f32 v[42:43], v[42:43], v[200:201]
	v_pk_mul_f32 v[44:45], v[44:45], v[202:203]
	v_pk_mul_f32 v[46:47], v[46:47], v[204:205]
	v_pk_mul_f32 v[48:49], v[48:49], v[206:207]
	v_pk_fma_f32 v[34:35], v[34:35], v[208:209], v[228:229]
	v_pk_fma_f32 v[36:37], v[36:37], v[210:211], v[230:231]
	v_pk_fma_f32 v[38:39], v[38:39], v[212:213], v[232:233]
	v_pk_fma_f32 v[40:41], v[40:41], v[214:215], v[234:235]
	v_pk_fma_f32 v[42:43], v[42:43], v[220:221], v[236:237]
	v_pk_fma_f32 v[44:45], v[44:45], v[222:223], v[238:239]
	v_pk_fma_f32 v[46:47], v[46:47], v[224:225], v[26:27]
	v_pk_fma_f32 v[48:49], v[48:49], v[226:227], v[28:29]
	v_cvt_pk_bf16_f32 v50, v34, v35
	v_cvt_pk_bf16_f32 v51, v36, v37
	v_cvt_pk_bf16_f32 v52, v38, v39
	v_cvt_pk_bf16_f32 v53, v40, v41
	v_cvt_pk_bf16_f32 v54, v42, v43
	v_cvt_pk_bf16_f32 v55, v44, v45
	v_cvt_pk_bf16_f32 v56, v46, v47
	v_cvt_pk_bf16_f32 v57, v48, v49
	global_store_dwordx2 v1, v[50:51], s[16:17] offset:0
	global_store_dwordx2 v1, v[52:53], s[16:17] offset:512
	global_store_dwordx2 v1, v[54:55], s[16:17] offset:1024
	global_store_dwordx2 v1, v[56:57], s[16:17] offset:1536
	s_add_u32 s16, s16, 0x800
	s_addc_u32 s17, s17, 0
	s_waitcnt vmcnt(20)
; __device__ __forceinline__ unsigned cvt_pk_bf16(float lo, float hi) { unsigned r; asm volatile("v_cvt_pk_bf16_f32 %0, %1, %2" : "=v"(r) : "v"(lo), "v"(hi)); return r; }
; template <bool BR, bool WH> ...
;     ...
;         if (WH) {
;             float s = 0.f;
; #pragma unroll
;             for (int j = 0; j < 4; ++j) s += (x[j][0] * x[j][0] + x[j][1] * x[j][1]) + (x[j][2] * x[j][2] + x[j][3] * x[j][3]);
;             const float rs = rsqrtf(wave_sum(s, lane) * (1.f / 1024.f) + EPS);
; #pragma unroll
;             for (int j = 0; j < 4; ++j) { const f32x4 gp = *(const f32x4*)(g_pre + 4 * lane + 256 * j), sc = *(const f32x4*)(mod_h + (size_t)mrow * 6144 + sc_off + 4 * lane + 256 * j),
;                     sh = *(const f32x4*)(mod_h + (size_t)mrow * 6144 + sh_off + 4 * lane + 256 * j);
;                 const f32x4 hv = ((x[j] * rs) * gp) * (sc + 1.0f) + sh;
;                 u32x2 w; w.x = cvt_pk_bf16(hv[0], hv[1]); w.y = cvt_pk_bf16(hv[2], hv[3]);
;                 *(u32x2*)(Hout + (size_t)row * 1024 + 4 * lane + 256 * j) = w; }
;         }
	v_mul_f32_e32 v6, v74, v74
	v_mul_f32_e32 v7, v75, v75
	v_fmac_f32_e32 v6, v76, v76
	v_fmac_f32_e32 v7, v77, v77
	v_fmac_f32_e32 v6, v78, v78
	v_fmac_f32_e32 v7, v79, v79
	v_fmac_f32_e32 v6, v80, v80
	v_fmac_f32_e32 v7, v81, v81
	v_fmac_f32_e32 v6, v82, v82
	v_fmac_f32_e32 v7, v83, v83
	v_fmac_f32_e32 v6, v84, v84
	v_fmac_f32_e32 v7, v85, v85
	v_fmac_f32_e32 v6, v86, v86
	v_fmac_f32_e32 v7, v87, v87
	v_fmac_f32_e32 v6, v88, v88
	v_fmac_f32_e32 v7, v89, v89
	v_add_f32_e32 v6, v6, v7
	s_nop 1
	v_add_f32_dpp v8, v6, v6 quad_perm:[1,0,3,2] row_mask:0xf bank_mask:0xf
	s_nop 1
	v_add_f32_dpp v8, v8, v8 quad_perm:[2,3,0,1] row_mask:0xf bank_mask:0xf
	s_nop 1
	v_add_f32_dpp v8, v8, v8 row_half_mirror row_mask:0xf bank_mask:0xf
	s_nop 1
	v_add_f32_dpp v8, v8, v8 row_mirror row_mask:0xf bank_mask:0xf
	s_nop 1
	v_add_f32_dpp v8, v8, v8 row_bcast:15 row_mask:0xa bank_mask:0xf
	s_nop 1
	v_add_f32_dpp v8, v8, v8 row_bcast:31 row_mask:0xc bank_mask:0xf
	s_nop 1
	v_readlane_b32 s84, v8, 63
	s_nop 1
	v_fma_f32 v4, s84, v2, v3
	v_rsq_f32_e32 v4, v4
	s_nop 0
	v_pk_mul_f32 v[34:35], v[74:75], v[4:5] op_sel_hi:[1,0]
	v_pk_mul_f32 v[36:37], v[76:77], v[4:5] op_sel_hi:[1,0]
	v_pk_mul_f32 v[38:39], v[78:79], v[4:5] op_sel_hi:[1,0]
	v_pk_mul_f32 v[40:41], v[80:81], v[4:5] op_sel_hi:[1,0]
	v_pk_mul_f32 v[42:43], v[82:83], v[4:5] op_sel_hi:[1,0]
	v_pk_mul_f32 v[44:45], v[84:85], v[4:5] op_sel_hi:[1,0]
	v_pk_mul_f32 v[46:47], v[86:87], v[4:5] op_sel_hi:[1,0]
	v_pk_mul_f32 v[48:49], v[88:89], v[4:5] op_sel_hi:[1,0]
	v_pk_mul_f32 v[34:35], v[34:35], v[192:193]
	v_pk_mul_f32 v[36:37], v[36:37], v[194:195]
	v_pk_mul_f32 v[38:39], v[38:39], v[196:197]
	v_pk_mul_f32 v[40:41], v[40:41], v[198:199]
	v_pk_mul_f32 v[42:43], v[42:43], v[200:201]
	v_pk_mul_f32 v[44:45], v[44:45], v[202:203]
	v_pk_mul_f32 v[46:47], v[46:47], v[204:205]
	v_pk_mul_f32 v[48:49], v[48:49], v[206:207]
	v_pk_fma_f32 v[34:35], v[34:35], v[208:209], v[228:229]
	v_pk_fma_f32 v[36:37], v[36:37], v[210:211], v[230:231]
	v_pk_fma_f32 v[38:39], v[38:39], v[212:213], v[232:233]
	v_pk_fma_f32 v[40:41], v[40:41], v[214:215], v[234:235]
	v_pk_fma_f32 v[42:43], v[42:43], v[220:221], v[236:237]
	v_pk_fma_f32 v[44:45], v[44:45], v[222:223], v[238:239]
	v_pk_fma_f32 v[46:47], v[46:47], v[224:225], v[26:27]
	v_pk_fma_f32 v[48:49], v[48:49], v[226:227], v[28:29]
	v_cvt_pk_bf16_f32 v50, v34, v35
	v_cvt_pk_bf16_f32 v51, v36, v37
	v_cvt_pk_bf16_f32 v52, v38, v39
	v_cvt_pk_bf16_f32 v53, v40, v41
	v_cvt_pk_bf16_f32 v54, v42, v43
	v_cvt_pk_bf16_f32 v55, v44, v45
	v_cvt_pk_bf16_f32 v56, v46, v47
	v_cvt_pk_bf16_f32 v57, v48, v49
	global_store_dwordx2 v1, v[50:51], s[16:17] offset:0
	global_store_dwordx2 v1, v[52:53], s[16:17] offset:512
	global_store_dwordx2 v1, v[54:55], s[16:17] offset:1024
	global_store_dwordx2 v1, v[56:57], s[16:17] offset:1536
	s_add_u32 s16, s16, 0x800
	s_addc_u32 s17, s17, 0
	s_waitcnt vmcnt(16)
	v_mul_f32_e32 v6, v90, v90
	v_mul_f32_e32 v7, v91, v91
	v_fmac_f32_e32 v6, v92, v92
	v_fmac_f32_e32 v7, v93, v93
	v_fmac_f32_e32 v6, v94, v94
	v_fmac_f32_e32 v7, v95, v95
	v_fmac_f32_e32 v6, v96, v96
	v_fmac_f32_e32 v7, v97, v97
	v_fmac_f32_e32 v6, v98, v98
	v_fmac_f32_e32 v7, v99, v99
	v_fmac_f32_e32 v6, v100, v100
	v_fmac_f32_e32 v7, v101, v101
	v_fmac_f32_e32 v6, v102, v102
	v_fmac_f32_e32 v7, v103, v103
	v_fmac_f32_e32 v6, v104, v104
	v_fmac_f32_e32 v7, v105, v105
	v_add_f32_e32 v6, v6, v7
	s_nop 1
	v_add_f32_dpp v8, v6, v6 quad_perm:[1,0,3,2] row_mask:0xf bank_mask:0xf
	s_nop 1
	v_add_f32_dpp v8, v8, v8 quad_perm:[2,3,0,1] row_mask:0xf bank_mask:0xf
	s_nop 1
	v_add_f32_dpp v8, v8, v8 row_half_mirror row_mask:0xf bank_mask:0xf
	s_nop 1
	v_add_f32_dpp v8, v8, v8 row_mirror row_mask:0xf bank_mask:0xf
	s_nop 1
	v_add_f32_dpp v8, v8, v8 row_bcast:15 row_mask:0xa bank_mask:0xf
	s_nop 1
	v_add_f32_dpp v8, v8, v8 row_bcast:31 row_mask:0xc bank_mask:0xf
	s_nop 1
	v_readlane_b32 s84, v8, 63
	s_nop 1
	v_fma_f32 v4, s84, v2, v3
	v_rsq_f32_e32 v4, v4
	s_nop 0
	v_pk_mul_f32 v[34:35], v[90:91], v[4:5] op_sel_hi:[1,0]
	v_pk_mul_f32 v[36:37], v[92:93], v[4:5] op_sel_hi:[1,0]
	v_pk_mul_f32 v[38:39], v[94:95], v[4:5] op_sel_hi:[1,0]
	v_pk_mul_f32 v[40:41], v[96:97], v[4:5] op_sel_hi:[1,0]
	v_pk_mul_f32 v[42:43], v[98:99], v[4:5] op_sel_hi:[1,0]
	v_pk_mul_f32 v[44:45], v[100:101], v[4:5] op_sel_hi:[1,0]
	v_pk_mul_f32 v[46:47], v[102:103], v[4:5] op_sel_hi:[1,0]
	v_pk_mul_f32 v[48:49], v[104:105], v[4:5] op_sel_hi:[1,0]
	v_pk_mul_f32 v[34:35], v[34:35], v[192:193]
	v_pk_mul_f32 v[36:37], v[36:37], v[194:195]
	v_pk_mul_f32 v[38:39], v[38:39], v[196:197]
	v_pk_mul_f32 v[40:41], v[40:41], v[198:199]
	v_pk_mul_f32 v[42:43], v[42:43], v[200:201]
	v_pk_mul_f32 v[44:45], v[44:45], v[202:203]
	v_pk_mul_f32 v[46:47], v[46:47], v[204:205]
	v_pk_mul_f32 v[48:49], v[48:49], v[206:207]
	v_pk_fma_f32 v[34:35], v[34:35], v[208:209], v[228:229]
	v_pk_fma_f32 v[36:37], v[36:37], v[210:211], v[230:231]
	v_pk_fma_f32 v[38:39], v[38:39], v[212:213], v[232:233]
	v_pk_fma_f32 v[40:41], v[40:41], v[214:215], v[234:235]
	v_pk_fma_f32 v[42:43], v[42:43], v[220:221], v[236:237]
	v_pk_fma_f32 v[44:45], v[44:45], v[222:223], v[238:239]
	v_pk_fma_f32 v[46:47], v[46:47], v[224:225], v[26:27]
	v_pk_fma_f32 v[48:49], v[48:49], v[226:227], v[28:29]
	v_cvt_pk_bf16_f32 v50, v34, v35
	v_cvt_pk_bf16_f32 v51, v36, v37
	v_cvt_pk_bf16_f32 v52, v38, v39
	v_cvt_pk_bf16_f32 v53, v40, v41
	v_cvt_pk_bf16_f32 v54, v42, v43
	v_cvt_pk_bf16_f32 v55, v44, v45
	v_cvt_pk_bf16_f32 v56, v46, v47
	v_cvt_pk_bf16_f32 v57, v48, v49
	global_store_dwordx2 v1, v[50:51], s[16:17] offset:0
	global_store_dwordx2 v1, v[52:53], s[16:17] offset:512
	global_store_dwordx2 v1, v[54:55], s[16:17] offset:1024
	global_store_dwordx2 v1, v[56:57], s[16:17] offset:1536
	s_add_u32 s16, s16, 0x800
	s_addc_u32 s17, s17, 0
	s_waitcnt vmcnt(12)
; __device__ __forceinline__ unsigned cvt_pk_bf16(float lo, float hi) { unsigned r; asm volatile("v_cvt_pk_bf16_f32 %0, %1, %2" : "=v"(r) : "v"(lo), "v"(hi)); return r; }
; template <bool BR, bool WH> ...
;     ...
;         if (WH) {
;             float s = 0.f;
; #pragma unroll
;             for (int j = 0; j < 4; ++j) s += (x[j][0] * x[j][0] + x[j][1] * x[j][1]) + (x[j][2] * x[j][2] + x[j][3] * x[j][3]);
;             const float rs = rsqrtf(wave_sum(s, lane) * (1.f / 1024.f) + EPS);
; #pragma unroll
;             for (int j = 0; j < 4; ++j) { const f32x4 gp = *(const f32x4*)(g_pre + 4 * lane + 256 * j), sc = *(const f32x4*)(mod_h + (size_t)mrow * 6144 + sc_off + 4 * lane + 256 * j),
;                     sh = *(const f32x4*)(mod_h + (size_t)mrow * 6144 + sh_off + 4 * lane + 256 * j);
;                 const f32x4 hv = ((x[j] * rs) * gp) * (sc + 1.0f) + sh;
;                 u32x2 w; w.x = cvt_pk_bf16(hv[0], hv[1]); w.y = cvt_pk_bf16(hv[2], hv[3]);
;                 *(u32x2*)(Hout + (size_t)row * 1024 + 4 * lane + 256 * j) = w; }
;         }
	v_mul_f32_e32 v6, v106, v106
	v_mul_f32_e32 v7, v107, v107
	v_fmac_f32_e32 v6, v108, v108
	v_fmac_f32_e32 v7, v109, v109
	v_fmac_f32_e32 v6, v110, v110
	v_fmac_f32_e32 v7, v111, v111
	v_fmac_f32_e32 v6, v112, v112
	v_fmac_f32_e32 v7, v113, v113
	v_fmac_f32_e32 v6, v114, v114
	v_fmac_f32_e32 v7, v115, v115
	v_fmac_f32_e32 v6, v116, v116
	v_fmac_f32_e32 v7, v117, v117
	v_fmac_f32_e32 v6, v118, v118
	v_fmac_f32_e32 v7, v119, v119
	v_fmac_f32_e32 v6, v120, v120
	v_fmac_f32_e32 v7, v121, v121
	v_add_f32_e32 v6, v6, v7
	s_nop 1
	v_add_f32_dpp v8, v6, v6 quad_perm:[1,0,3,2] row_mask:0xf bank_mask:0xf
	s_nop 1
	v_add_f32_dpp v8, v8, v8 quad_perm:[2,3,0,1] row_mask:0xf bank_mask:0xf
	s_nop 1
	v_add_f32_dpp v8, v8, v8 row_half_mirror row_mask:0xf bank_mask:0xf
	s_nop 1
	v_add_f32_dpp v8, v8, v8 row_mirror row_mask:0xf bank_mask:0xf
	s_nop 1
	v_add_f32_dpp v8, v8, v8 row_bcast:15 row_mask:0xa bank_mask:0xf
	s_nop 1
	v_add_f32_dpp v8, v8, v8 row_bcast:31 row_mask:0xc bank_mask:0xf
	s_nop 1
	v_readlane_b32 s84, v8, 63
	s_nop 1
	v_fma_f32 v4, s84, v2, v3
	v_rsq_f32_e32 v4, v4
	s_nop 0
	v_pk_mul_f32 v[34:35], v[106:107], v[4:5] op_sel_hi:[1,0]
	v_pk_mul_f32 v[36:37], v[108:109], v[4:5] op_sel_hi:[1,0]
	v_pk_mul_f32 v[38:39], v[110:111], v[4:5] op_sel_hi:[1,0]
	v_pk_mul_f32 v[40:41], v[112:113], v[4:5] op_sel_hi:[1,0]
	v_pk_mul_f32 v[42:43], v[114:115], v[4:5] op_sel_hi:[1,0]
	v_pk_mul_f32 v[44:45], v[116:117], v[4:5] op_sel_hi:[1,0]
	v_pk_mul_f32 v[46:47], v[118:119], v[4:5] op_sel_hi:[1,0]
	v_pk_mul_f32 v[48:49], v[120:121], v[4:5] op_sel_hi:[1,0]
	v_pk_mul_f32 v[34:35], v[34:35], v[192:193]
	v_pk_mul_f32 v[36:37], v[36:37], v[194:195]
	v_pk_mul_f32 v[38:39], v[38:39], v[196:197]
	v_pk_mul_f32 v[40:41], v[40:41], v[198:199]
	v_pk_mul_f32 v[42:43], v[42:43], v[200:201]
	v_pk_mul_f32 v[44:45], v[44:45], v[202:203]
	v_pk_mul_f32 v[46:47], v[46:47], v[204:205]
	v_pk_mul_f32 v[48:49], v[48:49], v[206:207]
	v_pk_fma_f32 v[34:35], v[34:35], v[208:209], v[228:229]
	v_pk_fma_f32 v[36:37], v[36:37], v[210:211], v[230:231]
	v_pk_fma_f32 v[38:39], v[38:39], v[212:213], v[232:233]
	v_pk_fma_f32 v[40:41], v[40:41], v[214:215], v[234:235]
	v_pk_fma_f32 v[42:43], v[42:43], v[220:221], v[236:237]
	v_pk_fma_f32 v[44:45], v[44:45], v[222:223], v[238:239]
	v_pk_fma_f32 v[46:47], v[46:47], v[224:225], v[26:27]
	v_pk_fma_f32 v[48:49], v[48:49], v[226:227], v[28:29]
	v_cvt_pk_bf16_f32 v50, v34, v35
	v_cvt_pk_bf16_f32 v51, v36, v37
	v_cvt_pk_bf16_f32 v52, v38, v39
	v_cvt_pk_bf16_f32 v53, v40, v41
	v_cvt_pk_bf16_f32 v54, v42, v43
	v_cvt_pk_bf16_f32 v55, v44, v45
	v_cvt_pk_bf16_f32 v56, v46, v47
	v_cvt_pk_bf16_f32 v57, v48, v49
	global_store_dwordx2 v1, v[50:51], s[16:17] offset:0
	global_store_dwordx2 v1, v[52:53], s[16:17] offset:512
	global_store_dwordx2 v1, v[54:55], s[16:17] offset:1024
	global_store_dwordx2 v1, v[56:57], s[16:17] offset:1536
	s_add_u32 s16, s16, 0x800
	s_addc_u32 s17, s17, 0
	s_add_u32 s32, s32, s27
	s_branch .Lnrm_A_lat_loop

; __device__ __forceinline__ float bflo(unsigned w) { return __uint_as_float(w << 16); }
; __device__ __forceinline__ float bfhi(unsigned w) { return __uint_as_float(w & 0xffff0000u); }
; template <bool BR, bool WH> ...
;     ...
;     if (gw >= nrows) return;
;     NORM_LOAD(gw, xc, bc);
;     for (int row = gw; row < nrows; row += NGW) {
;         const bool hn = row + NGW < nrows;
;         if (hn) NORM_LOAD(row + NGW, xn, bn);
;         const int mrow = row < ML ? (row >> 12) : 4;
;         f32x4 x[4];
; #pragma unroll
;         for (int j = 0; j < 4; ++j) x[j] = xc[j];
;         if (BR) {
;             f32x4 m[4]; float s = 0.f;
; #pragma unroll
;             for (int j = 0; j < 4; ++j) { m[j] = (f32x4){bflo(bc[j].x), bfhi(bc[j].x), bflo(bc[j].y), bfhi(bc[j].y)};
;                 s += (m[j][0] * m[j][0] + m[j][1] * m[j][1]) + (m[j][2] * m[j][2] + m[j][3] * m[j][3]); }
;             const float rs = rsqrtf(wave_sum(s, lane) * (1.f / 1024.f) + EPS);
;             float* xo = row < ML ? xout_lat + (size_t)row * 1024 : xout_ctx + (size_t)(row - ML) * 1024;
; #pragma unroll
;             for (int j = 0; j < 4; ++j) { const f32x4 gp = *(const f32x4*)(g_post + 4 * lane + 256 * j), ga = *(const f32x4*)(mod_g + (size_t)mrow * 6144 + gate_off + 4 * lane + 256 * j);
;                 x[j] = x[j] + ga * ((m[j] * rs) * gp); __builtin_nontemporal_store(x[j], (f32x4*)(xo + 4 * lane + 256 * j)); }
;         }
.Lnrm_B_ctx_loop:
	s_cmpk_lt_u32 s32, 0x400
	s_cbranch_scc0 .Lnrm_B_ctx_done
	s_lshl_b32 s97, s32, 12
	s_add_u32 s4, s48, s97
	s_addc_u32 s5, s49, 0
	s_lshl_b32 s97, s32, 12
	s_add_u32 s14, s40, s97
	s_addc_u32 s15, s41, 0
	s_add_u32 s14, s14, 0x1200000
	s_addc_u32 s15, s15, 0
	s_lshl_b32 s97, s32, 11
	s_add_u32 s16, s56, s97
	s_addc_u32 s17, s57, 0
	s_add_u32 s16, s16, 0x2000000
	s_addc_u32 s17, s17, 0
	global_load_dwordx4 v[106:109], v0, s[4:5] offset:0 nt
	global_load_dwordx4 v[110:113], v0, s[4:5] offset:1024 nt
	global_load_dwordx4 v[114:117], v0, s[4:5] offset:2048 nt
	global_load_dwordx4 v[118:121], v0, s[4:5] offset:3072 nt
	s_lshl_b32 s97, s32, 11
	s_add_u32 s12, s54, s97
	s_addc_u32 s13, s55, 0
	s_add_u32 s12, s12, 0x2200000
	s_addc_u32 s13, s13, 0
	global_load_dwordx2 v[58:59], v1, s[12:13] offset:0
	global_load_dwordx2 v[60:61], v1, s[12:13] offset:512
	global_load_dwordx2 v[62:63], v1, s[12:13] offset:1024
	global_load_dwordx2 v[64:65], v1, s[12:13] offset:1536
	s_add_u32 s12, s12, 0x200000
	s_addc_u32 s13, s13, 0
	global_load_dwordx2 v[66:67], v1, s[12:13] offset:0
	global_load_dwordx2 v[68:69], v1, s[12:13] offset:512
	global_load_dwordx2 v[70:71], v1, s[12:13] offset:1024
	global_load_dwordx2 v[72:73], v1, s[12:13] offset:1536
	s_add_u32 s12, s12, 0x200000
	s_addc_u32 s13, s13, 0
	global_load_dwordx2 v[74:75], v1, s[12:13] offset:0
	global_load_dwordx2 v[76:77], v1, s[12:13] offset:512
	global_load_dwordx2 v[78:79], v1, s[12:13] offset:1024
	global_load_dwordx2 v[80:81], v1, s[12:13] offset:1536
	s_add_u32 s12, s12, 0x200000
	s_addc_u32 s13, s13, 0
	global_load_dwordx2 v[82:83], v1, s[12:13] offset:0
	global_load_dwordx2 v[84:85], v1, s[12:13] offset:512
	global_load_dwordx2 v[86:87], v1, s[12:13] offset:1024
	global_load_dwordx2 v[88:89], v1, s[12:13] offset:1536
	s_mov_b32 s88, 0x18000
	global_load_dwordx4 v[154:157], v0, s[90:91] offset:0
	global_load_dwordx4 v[158:161], v0, s[90:91] offset:1024
	global_load_dwordx4 v[162:165], v0, s[90:91] offset:2048
	global_load_dwordx4 v[166:169], v0, s[90:91] offset:3072
	s_add_u32 s98, s88, s8
	s_add_u32 s98, s98, s40
	s_addc_u32 s99, s41, 0
	s_add_u32 s98, s98, 0x1600000
	s_addc_u32 s99, s99, 0
	global_load_dwordx4 v[176:179], v0, s[98:99] offset:0
	global_load_dwordx4 v[180:183], v0, s[98:99] offset:1024
	global_load_dwordx4 v[184:187], v0, s[98:99] offset:2048
	global_load_dwordx4 v[188:191], v0, s[98:99] offset:3072
	global_load_dwordx4 v[192:195], v0, s[24:25] offset:0
	global_load_dwordx4 v[196:199], v0, s[24:25] offset:1024
	global_load_dwordx4 v[200:203], v0, s[24:25] offset:2048
	global_load_dwordx4 v[204:207], v0, s[24:25] offset:3072
	s_add_u32 s98, s88, s59
	s_add_u32 s98, s98, s40
	s_addc_u32 s99, s41, 0
	s_add_u32 s98, s98, 0x1600000
	s_addc_u32 s99, s99, 0
	global_load_dwordx4 v[208:211], v0, s[98:99] offset:0
	global_load_dwordx4 v[212:215], v0, s[98:99] offset:1024
	global_load_dwordx4 v[220:223], v0, s[98:99] offset:2048
	global_load_dwordx4 v[224:227], v0, s[98:99] offset:3072
	s_add_u32 s98, s88, s73
	s_add_u32 s98, s98, s40
	s_addc_u32 s99, s41, 0
	s_add_u32 s98, s98, 0x1600000
	s_addc_u32 s99, s99, 0
	global_load_dwordx4 v[228:231], v0, s[98:99] offset:0
	global_load_dwordx4 v[232:235], v0, s[98:99] offset:1024
	global_load_dwordx4 v[236:239], v0, s[98:99] offset:2048
	global_load_dwordx4 v[26:29], v0, s[98:99] offset:3072
	s_waitcnt vmcnt(0)
	v_pk_add_f32 v[208:209], v[208:209], 1.0 op_sel_hi:[1,0]
	v_pk_add_f32 v[210:211], v[210:211], 1.0 op_sel_hi:[1,0]
	v_pk_add_f32 v[212:213], v[212:213], 1.0 op_sel_hi:[1,0]
	v_pk_add_f32 v[214:215], v[214:215], 1.0 op_sel_hi:[1,0]
	v_pk_add_f32 v[220:221], v[220:221], 1.0 op_sel_hi:[1,0]
	v_pk_add_f32 v[222:223], v[222:223], 1.0 op_sel_hi:[1,0]
	v_pk_add_f32 v[224:225], v[224:225], 1.0 op_sel_hi:[1,0]
	v_pk_add_f32 v[226:227], v[226:227], 1.0 op_sel_hi:[1,0]
	v_lshlrev_b32_e32 v10, 16, v58
	v_and_b32_e32 v11, 0xffff0000, v58
	v_lshlrev_b32_e32 v12, 16, v59
	v_and_b32_e32 v13, 0xffff0000, v59
	v_lshlrev_b32_e32 v34, 16, v66
	v_and_b32_e32 v35, 0xffff0000, v66
	v_lshlrev_b32_e32 v36, 16, v67
	v_and_b32_e32 v37, 0xffff0000, v67
	v_add_f32_e32 v10, v10, v34
	v_add_f32_e32 v11, v11, v35
	v_add_f32_e32 v12, v12, v36
	v_add_f32_e32 v13, v13, v37
	v_lshlrev_b32_e32 v34, 16, v74
	v_and_b32_e32 v35, 0xffff0000, v74
	v_lshlrev_b32_e32 v36, 16, v75
	v_and_b32_e32 v37, 0xffff0000, v75
	v_add_f32_e32 v10, v10, v34
	v_add_f32_e32 v11, v11, v35
	v_add_f32_e32 v12, v12, v36
	v_add_f32_e32 v13, v13, v37
	v_lshlrev_b32_e32 v34, 16, v82
	v_and_b32_e32 v35, 0xffff0000, v82
	v_lshlrev_b32_e32 v36, 16, v83
	v_and_b32_e32 v37, 0xffff0000, v83
	v_add_f32_e32 v10, v10, v34
	v_add_f32_e32 v11, v11, v35
	v_add_f32_e32 v12, v12, v36
	v_add_f32_e32 v13, v13, v37
	v_cvt_pk_bf16_f32 v146, v10, v11
	v_cvt_pk_bf16_f32 v147, v12, v13
	v_lshlrev_b32_e32 v10, 16, v60
	v_and_b32_e32 v11, 0xffff0000, v60
	v_lshlrev_b32_e32 v12, 16, v61
	v_and_b32_e32 v13, 0xffff0000, v61
	v_lshlrev_b32_e32 v34, 16, v68
	v_and_b32_e32 v35, 0xffff0000, v68
	v_lshlrev_b32_e32 v36, 16, v69
	v_and_b32_e32 v37, 0xffff0000, v69
	v_add_f32_e32 v10, v10, v34
	v_add_f32_e32 v11, v11, v35
	v_add_f32_e32 v12, v12, v36
	v_add_f32_e32 v13, v13, v37
	v_lshlrev_b32_e32 v34, 16, v76
	v_and_b32_e32 v35, 0xffff0000, v76
	v_lshlrev_b32_e32 v36, 16, v77
	v_and_b32_e32 v37, 0xffff0000, v77
	v_add_f32_e32 v10, v10, v34
	v_add_f32_e32 v11, v11, v35
	v_add_f32_e32 v12, v12, v36
	v_add_f32_e32 v13, v13, v37
	v_lshlrev_b32_e32 v34, 16, v84
	v_and_b32_e32 v35, 0xffff0000, v84
	v_lshlrev_b32_e32 v36, 16, v85
	v_and_b32_e32 v37, 0xffff0000, v85
	v_add_f32_e32 v10, v10, v34
	v_add_f32_e32 v11, v11, v35
; __device__ __forceinline__ float bflo(unsigned w) { return __uint_as_float(w << 16); }
; __device__ __forceinline__ float bfhi(unsigned w) { return __uint_as_float(w & 0xffff0000u); }
; template <bool BR, bool WH> ...
;     ...
;     if (gw >= nrows) return;
;     NORM_LOAD(gw, xc, bc);
;     for (int row = gw; row < nrows; row += NGW) {
;         const bool hn = row + NGW < nrows;
;         if (hn) NORM_LOAD(row + NGW, xn, bn);
;         const int mrow = row < ML ? (row >> 12) : 4;
;         f32x4 x[4];
; #pragma unroll
;         for (int j = 0; j < 4; ++j) x[j] = xc[j];
;         if (BR) {
;             f32x4 m[4]; float s = 0.f;
; #pragma unroll
;             for (int j = 0; j < 4; ++j) { m[j] = (f32x4){bflo(bc[j].x), bfhi(bc[j].x), bflo(bc[j].y), bfhi(bc[j].y)};
;                 s += (m[j][0] * m[j][0] + m[j][1] * m[j][1]) + (m[j][2] * m[j][2] + m[j][3] * m[j][3]); }
;             const float rs = rsqrtf(wave_sum(s, lane) * (1.f / 1024.f) + EPS);
	v_add_f32_e32 v12, v12, v36
	v_add_f32_e32 v13, v13, v37
	v_cvt_pk_bf16_f32 v148, v10, v11
	v_cvt_pk_bf16_f32 v149, v12, v13
	v_lshlrev_b32_e32 v10, 16, v62
	v_and_b32_e32 v11, 0xffff0000, v62
	v_lshlrev_b32_e32 v12, 16, v63
	v_and_b32_e32 v13, 0xffff0000, v63
	v_lshlrev_b32_e32 v34, 16, v70
	v_and_b32_e32 v35, 0xffff0000, v70
	v_lshlrev_b32_e32 v36, 16, v71
	v_and_b32_e32 v37, 0xffff0000, v71
	v_add_f32_e32 v10, v10, v34
	v_add_f32_e32 v11, v11, v35
	v_add_f32_e32 v12, v12, v36
	v_add_f32_e32 v13, v13, v37
	v_lshlrev_b32_e32 v34, 16, v78
	v_and_b32_e32 v35, 0xffff0000, v78
	v_lshlrev_b32_e32 v36, 16, v79
	v_and_b32_e32 v37, 0xffff0000, v79
	v_add_f32_e32 v10, v10, v34
	v_add_f32_e32 v11, v11, v35
	v_add_f32_e32 v12, v12, v36
	v_add_f32_e32 v13, v13, v37
	v_lshlrev_b32_e32 v34, 16, v86
	v_and_b32_e32 v35, 0xffff0000, v86
	v_lshlrev_b32_e32 v36, 16, v87
	v_and_b32_e32 v37, 0xffff0000, v87
	v_add_f32_e32 v10, v10, v34
	v_add_f32_e32 v11, v11, v35
	v_add_f32_e32 v12, v12, v36
	v_add_f32_e32 v13, v13, v37
	v_cvt_pk_bf16_f32 v150, v10, v11
	v_cvt_pk_bf16_f32 v151, v12, v13
	v_lshlrev_b32_e32 v10, 16, v64
	v_and_b32_e32 v11, 0xffff0000, v64
	v_lshlrev_b32_e32 v12, 16, v65
	v_and_b32_e32 v13, 0xffff0000, v65
	v_lshlrev_b32_e32 v34, 16, v72
	v_and_b32_e32 v35, 0xffff0000, v72
	v_lshlrev_b32_e32 v36, 16, v73
	v_and_b32_e32 v37, 0xffff0000, v73
	v_add_f32_e32 v10, v10, v34
	v_add_f32_e32 v11, v11, v35
	v_add_f32_e32 v12, v12, v36
	v_add_f32_e32 v13, v13, v37
	v_lshlrev_b32_e32 v34, 16, v80
	v_and_b32_e32 v35, 0xffff0000, v80
	v_lshlrev_b32_e32 v36, 16, v81
	v_and_b32_e32 v37, 0xffff0000, v81
	v_add_f32_e32 v10, v10, v34
	v_add_f32_e32 v11, v11, v35
	v_add_f32_e32 v12, v12, v36
	v_add_f32_e32 v13, v13, v37
	v_lshlrev_b32_e32 v34, 16, v88
	v_and_b32_e32 v35, 0xffff0000, v88
	v_lshlrev_b32_e32 v36, 16, v89
	v_and_b32_e32 v37, 0xffff0000, v89
	v_add_f32_e32 v10, v10, v34
	v_add_f32_e32 v11, v11, v35
	v_add_f32_e32 v12, v12, v36
	v_add_f32_e32 v13, v13, v37
	v_cvt_pk_bf16_f32 v152, v10, v11
	v_cvt_pk_bf16_f32 v153, v12, v13
	v_lshlrev_b32_e32 v10, 16, v146
	v_and_b32_e32 v11, 0xffff0000, v146
	v_lshlrev_b32_e32 v12, 16, v147
	v_and_b32_e32 v13, 0xffff0000, v147
	v_lshlrev_b32_e32 v14, 16, v148
	v_and_b32_e32 v15, 0xffff0000, v148
	v_lshlrev_b32_e32 v16, 16, v149
	v_and_b32_e32 v17, 0xffff0000, v149
	v_lshlrev_b32_e32 v18, 16, v150
	v_and_b32_e32 v19, 0xffff0000, v150
	v_lshlrev_b32_e32 v20, 16, v151
	v_and_b32_e32 v21, 0xffff0000, v151
	v_lshlrev_b32_e32 v22, 16, v152
	v_and_b32_e32 v23, 0xffff0000, v152
	v_lshlrev_b32_e32 v24, 16, v153
	v_and_b32_e32 v25, 0xffff0000, v153
	v_mul_f32_e32 v6, v10, v10
	v_mul_f32_e32 v7, v11, v11
	v_fmac_f32_e32 v6, v12, v12
	v_fmac_f32_e32 v7, v13, v13
	v_fmac_f32_e32 v6, v14, v14
	v_fmac_f32_e32 v7, v15, v15
	v_fmac_f32_e32 v6, v16, v16
	v_fmac_f32_e32 v7, v17, v17
	v_fmac_f32_e32 v6, v18, v18
	v_fmac_f32_e32 v7, v19, v19
	v_fmac_f32_e32 v6, v20, v20
	v_fmac_f32_e32 v7, v21, v21
	v_fmac_f32_e32 v6, v22, v22
	v_fmac_f32_e32 v7, v23, v23
	v_fmac_f32_e32 v6, v24, v24
	v_fmac_f32_e32 v7, v25, v25
	v_add_f32_e32 v6, v6, v7
	s_nop 1
	v_add_f32_dpp v8, v6, v6 quad_perm:[1,0,3,2] row_mask:0xf bank_mask:0xf
	s_nop 1
	v_add_f32_dpp v8, v8, v8 quad_perm:[2,3,0,1] row_mask:0xf bank_mask:0xf
	s_nop 1
	v_add_f32_dpp v8, v8, v8 row_half_mirror row_mask:0xf bank_mask:0xf
	s_nop 1
	v_add_f32_dpp v8, v8, v8 row_mirror row_mask:0xf bank_mask:0xf
	s_nop 1
	v_add_f32_dpp v8, v8, v8 row_bcast:15 row_mask:0xa bank_mask:0xf
	s_nop 1
	v_add_f32_dpp v8, v8, v8 row_bcast:31 row_mask:0xc bank_mask:0xf
	s_nop 1
	v_readlane_b32 s84, v8, 63
	s_nop 1
	v_fma_f32 v4, s84, v2, v3
	v_rsq_f32_e32 v4, v4
	s_nop 0
	v_pk_mul_f32 v[34:35], v[10:11], v[4:5] op_sel_hi:[1,0]
	v_pk_mul_f32 v[36:37], v[12:13], v[4:5] op_sel_hi:[1,0]
	v_pk_mul_f32 v[38:39], v[14:15], v[4:5] op_sel_hi:[1,0]
	v_pk_mul_f32 v[40:41], v[16:17], v[4:5] op_sel_hi:[1,0]
	v_pk_mul_f32 v[42:43], v[18:19], v[4:5] op_sel_hi:[1,0]
	v_pk_mul_f32 v[44:45], v[20:21], v[4:5] op_sel_hi:[1,0]
	v_pk_mul_f32 v[46:47], v[22:23], v[4:5] op_sel_hi:[1,0]
; __device__ __forceinline__ unsigned cvt_pk_bf16(float lo, float hi) { unsigned r; asm volatile("v_cvt_pk_bf16_f32 %0, %1, %2" : "=v"(r) : "v"(lo), "v"(hi)); return r; }
; template <bool BR, bool WH> ...
;     ...
;             const float rs = rsqrtf(wave_sum(s, lane) * (1.f / 1024.f) + EPS);
;             float* xo = row < ML ? xout_lat + (size_t)row * 1024 : xout_ctx + (size_t)(row - ML) * 1024;
; #pragma unroll
;             for (int j = 0; j < 4; ++j) { const f32x4 gp = *(const f32x4*)(g_post + 4 * lane + 256 * j), ga = *(const f32x4*)(mod_g + (size_t)mrow * 6144 + gate_off + 4 * lane + 256 * j);
;                 x[j] = x[j] + ga * ((m[j] * rs) * gp); __builtin_nontemporal_store(x[j], (f32x4*)(xo + 4 * lane + 256 * j)); }
;         }
;         if (WH) {
;             float s = 0.f;
; #pragma unroll
;             for (int j = 0; j < 4; ++j) s += (x[j][0] * x[j][0] + x[j][1] * x[j][1]) + (x[j][2] * x[j][2] + x[j][3] * x[j][3]);
;             const float rs = rsqrtf(wave_sum(s, lane) * (1.f / 1024.f) + EPS);
; #pragma unroll
;             for (int j = 0; j < 4; ++j) { const f32x4 gp = *(const f32x4*)(g_pre + 4 * lane + 256 * j), sc = *(const f32x4*)(mod_h + (size_t)mrow * 6144 + sc_off + 4 * lane + 256 * j),
;                     sh = *(const f32x4*)(mod_h + (size_t)mrow * 6144 + sh_off + 4 * lane + 256 * j);
;                 const f32x4 hv = ((x[j] * rs) * gp) * (sc + 1.0f) + sh;
;                 u32x2 w; w.x = cvt_pk_bf16(hv[0], hv[1]); w.y = cvt_pk_bf16(hv[2], hv[3]);
;                 *(u32x2*)(Hout + (size_t)row * 1024 + 4 * lane + 256 * j) = w; }
;         }
	v_pk_mul_f32 v[48:49], v[24:25], v[4:5] op_sel_hi:[1,0]
	v_pk_mul_f32 v[34:35], v[34:35], v[154:155]
	v_pk_mul_f32 v[36:37], v[36:37], v[156:157]
	v_pk_mul_f32 v[38:39], v[38:39], v[158:159]
	v_pk_mul_f32 v[40:41], v[40:41], v[160:161]
	v_pk_mul_f32 v[42:43], v[42:43], v[162:163]
	v_pk_mul_f32 v[44:45], v[44:45], v[164:165]
	v_pk_mul_f32 v[46:47], v[46:47], v[166:167]
	v_pk_mul_f32 v[48:49], v[48:49], v[168:169]
	v_pk_fma_f32 v[106:107], v[176:177], v[34:35], v[106:107]
	v_pk_fma_f32 v[108:109], v[178:179], v[36:37], v[108:109]
	v_pk_fma_f32 v[110:111], v[180:181], v[38:39], v[110:111]
	v_pk_fma_f32 v[112:113], v[182:183], v[40:41], v[112:113]
	v_pk_fma_f32 v[114:115], v[184:185], v[42:43], v[114:115]
	v_pk_fma_f32 v[116:117], v[186:187], v[44:45], v[116:117]
	v_pk_fma_f32 v[118:119], v[188:189], v[46:47], v[118:119]
	v_pk_fma_f32 v[120:121], v[190:191], v[48:49], v[120:121]
	global_store_dwordx4 v0, v[106:109], s[14:15] offset:0 nt
	global_store_dwordx4 v0, v[110:113], s[14:15] offset:1024 nt
	global_store_dwordx4 v0, v[114:117], s[14:15] offset:2048 nt
	global_store_dwordx4 v0, v[118:121], s[14:15] offset:3072 nt
	v_mul_f32_e32 v6, v106, v106
	v_mul_f32_e32 v7, v107, v107
	v_fmac_f32_e32 v6, v108, v108
	v_fmac_f32_e32 v7, v109, v109
	v_fmac_f32_e32 v6, v110, v110
	v_fmac_f32_e32 v7, v111, v111
	v_fmac_f32_e32 v6, v112, v112
	v_fmac_f32_e32 v7, v113, v113
	v_fmac_f32_e32 v6, v114, v114
	v_fmac_f32_e32 v7, v115, v115
	v_fmac_f32_e32 v6, v116, v116
	v_fmac_f32_e32 v7, v117, v117
	v_fmac_f32_e32 v6, v118, v118
	v_fmac_f32_e32 v7, v119, v119
	v_fmac_f32_e32 v6, v120, v120
	v_fmac_f32_e32 v7, v121, v121
	v_add_f32_e32 v6, v6, v7
	s_nop 1
	v_add_f32_dpp v8, v6, v6 quad_perm:[1,0,3,2] row_mask:0xf bank_mask:0xf
	s_nop 1
	v_add_f32_dpp v8, v8, v8 quad_perm:[2,3,0,1] row_mask:0xf bank_mask:0xf
	s_nop 1
	v_add_f32_dpp v8, v8, v8 row_half_mirror row_mask:0xf bank_mask:0xf
	s_nop 1
	v_add_f32_dpp v8, v8, v8 row_mirror row_mask:0xf bank_mask:0xf
	s_nop 1
	v_add_f32_dpp v8, v8, v8 row_bcast:15 row_mask:0xa bank_mask:0xf
	s_nop 1
	v_add_f32_dpp v8, v8, v8 row_bcast:31 row_mask:0xc bank_mask:0xf
	s_nop 1
	v_readlane_b32 s84, v8, 63
	s_nop 1
	v_fma_f32 v4, s84, v2, v3
	v_rsq_f32_e32 v4, v4
	s_nop 0
	v_pk_mul_f32 v[34:35], v[106:107], v[4:5] op_sel_hi:[1,0]
	v_pk_mul_f32 v[36:37], v[108:109], v[4:5] op_sel_hi:[1,0]
	v_pk_mul_f32 v[38:39], v[110:111], v[4:5] op_sel_hi:[1,0]
	v_pk_mul_f32 v[40:41], v[112:113], v[4:5] op_sel_hi:[1,0]
	v_pk_mul_f32 v[42:43], v[114:115], v[4:5] op_sel_hi:[1,0]
	v_pk_mul_f32 v[44:45], v[116:117], v[4:5] op_sel_hi:[1,0]
	v_pk_mul_f32 v[46:47], v[118:119], v[4:5] op_sel_hi:[1,0]
	v_pk_mul_f32 v[48:49], v[120:121], v[4:5] op_sel_hi:[1,0]
	v_pk_mul_f32 v[34:35], v[34:35], v[192:193]
	v_pk_mul_f32 v[36:37], v[36:37], v[194:195]
	v_pk_mul_f32 v[38:39], v[38:39], v[196:197]
	v_pk_mul_f32 v[40:41], v[40:41], v[198:199]
	v_pk_mul_f32 v[42:43], v[42:43], v[200:201]
	v_pk_mul_f32 v[44:45], v[44:45], v[202:203]
	v_pk_mul_f32 v[46:47], v[46:47], v[204:205]
	v_pk_mul_f32 v[48:49], v[48:49], v[206:207]
	v_pk_fma_f32 v[34:35], v[34:35], v[208:209], v[228:229]
	v_pk_fma_f32 v[36:37], v[36:37], v[210:211], v[230:231]
	v_pk_fma_f32 v[38:39], v[38:39], v[212:213], v[232:233]
	v_pk_fma_f32 v[40:41], v[40:41], v[214:215], v[234:235]
	v_pk_fma_f32 v[42:43], v[42:43], v[220:221], v[236:237]
	v_pk_fma_f32 v[44:45], v[44:45], v[222:223], v[238:239]
	v_pk_fma_f32 v[46:47], v[46:47], v[224:225], v[26:27]
	v_pk_fma_f32 v[48:49], v[48:49], v[226:227], v[28:29]
	v_cvt_pk_bf16_f32 v50, v34, v35
	v_cvt_pk_bf16_f32 v51, v36, v37
	v_cvt_pk_bf16_f32 v52, v38, v39
	v_cvt_pk_bf16_f32 v53, v40, v41
	v_cvt_pk_bf16_f32 v54, v42, v43
	v_cvt_pk_bf16_f32 v55, v44, v45
	v_cvt_pk_bf16_f32 v56, v46, v47
	v_cvt_pk_bf16_f32 v57, v48, v49
	global_store_dwordx2 v1, v[50:51], s[16:17] offset:0
	global_store_dwordx2 v1, v[52:53], s[16:17] offset:512
	global_store_dwordx2 v1, v[54:55], s[16:17] offset:1024
	global_store_dwordx2 v1, v[56:57], s[16:17] offset:1536
	s_add_u32 s32, s32, s27
	s_branch .Lnrm_B_ctx_loop

; template <bool BR, bool WH> ...
;     ...
;     if (gw >= nrows) return;
;     NORM_LOAD(gw, xc, bc);
;     for (int row = gw; row < nrows; row += NGW) {
;         const bool hn = row + NGW < nrows;
;         if (hn) NORM_LOAD(row + NGW, xn, bn);
.Lnrm_B_lat_loop:
	s_cmpk_lt_u32 s32, 0x800
	s_cbranch_scc0 .Lnrm_ret
	s_lshl_b32 s97, s32, 15
	s_add_u32 s4, s44, s97
	s_addc_u32 s5, s45, 0
	s_lshl_b32 s97, s32, 14
	s_add_u32 s12, s54, s97
	s_addc_u32 s13, s55, 0
	s_lshl_b32 s97, s32, 15
	s_add_u32 s14, s42, s97
	s_addc_u32 s15, s43, 0
	s_lshl_b32 s97, s32, 14
	s_add_u32 s16, s56, s97
	s_addc_u32 s17, s57, 0
	s_lshr_b32 s88, s32, 9
	s_mul_i32 s88, s88, 0x6000
	global_load_dwordx4 v[58:61], v0, s[4:5] offset:0 nt
	global_load_dwordx4 v[62:65], v0, s[4:5] offset:1024 nt
	global_load_dwordx4 v[66:69], v0, s[4:5] offset:2048 nt
	global_load_dwordx4 v[70:73], v0, s[4:5] offset:3072 nt
	global_load_dwordx2 v[122:123], v1, s[12:13] offset:0 nt
	global_load_dwordx2 v[124:125], v1, s[12:13] offset:512 nt
	global_load_dwordx2 v[126:127], v1, s[12:13] offset:1024 nt
	global_load_dwordx2 v[128:129], v1, s[12:13] offset:1536 nt
	s_add_u32 s4, s4, 0x1000
	s_addc_u32 s5, s5, 0
	s_add_u32 s12, s12, 0x800
	s_addc_u32 s13, s13, 0
	global_load_dwordx4 v[154:157], v0, s[90:91] offset:0
	global_load_dwordx4 v[158:161], v0, s[90:91] offset:1024
	global_load_dwordx4 v[162:165], v0, s[90:91] offset:2048
	global_load_dwordx4 v[166:169], v0, s[90:91] offset:3072
	s_add_u32 s98, s88, s8
	s_add_u32 s98, s98, s40
	s_addc_u32 s99, s41, 0
	s_add_u32 s98, s98, 0x1600000
	s_addc_u32 s99, s99, 0
	global_load_dwordx4 v[176:179], v0, s[98:99] offset:0
	global_load_dwordx4 v[180:183], v0, s[98:99] offset:1024
	global_load_dwordx4 v[184:187], v0, s[98:99] offset:2048
	global_load_dwordx4 v[188:191], v0, s[98:99] offset:3072
	global_load_dwordx4 v[192:195], v0, s[24:25] offset:0
	global_load_dwordx4 v[196:199], v0, s[24:25] offset:1024
	global_load_dwordx4 v[200:203], v0, s[24:25] offset:2048
	global_load_dwordx4 v[204:207], v0, s[24:25] offset:3072
	s_add_u32 s98, s88, s59
	s_add_u32 s98, s98, s40
	s_addc_u32 s99, s41, 0
	s_add_u32 s98, s98, 0x1600000
	s_addc_u32 s99, s99, 0
	global_load_dwordx4 v[208:211], v0, s[98:99] offset:0
	global_load_dwordx4 v[212:215], v0, s[98:99] offset:1024
	global_load_dwordx4 v[220:223], v0, s[98:99] offset:2048
	global_load_dwordx4 v[224:227], v0, s[98:99] offset:3072
	s_add_u32 s98, s88, s73
	s_add_u32 s98, s98, s40
	s_addc_u32 s99, s41, 0
	s_add_u32 s98, s98, 0x1600000
	s_addc_u32 s99, s99, 0
	global_load_dwordx4 v[228:231], v0, s[98:99] offset:0
	global_load_dwordx4 v[232:235], v0, s[98:99] offset:1024
	global_load_dwordx4 v[236:239], v0, s[98:99] offset:2048
	global_load_dwordx4 v[26:29], v0, s[98:99] offset:3072
	global_load_dwordx4 v[74:77], v0, s[4:5] offset:0 nt
	global_load_dwordx4 v[78:81], v0, s[4:5] offset:1024 nt
	global_load_dwordx4 v[82:85], v0, s[4:5] offset:2048 nt
	global_load_dwordx4 v[86:89], v0, s[4:5] offset:3072 nt
	global_load_dwordx2 v[130:131], v1, s[12:13] offset:0 nt
	global_load_dwordx2 v[132:133], v1, s[12:13] offset:512 nt
	global_load_dwordx2 v[134:135], v1, s[12:13] offset:1024 nt
	global_load_dwordx2 v[136:137], v1, s[12:13] offset:1536 nt
	s_add_u32 s4, s4, 0x1000
	s_addc_u32 s5, s5, 0
	s_add_u32 s12, s12, 0x800
	s_addc_u32 s13, s13, 0
	global_load_dwordx4 v[90:93], v0, s[4:5] offset:0 nt
	global_load_dwordx4 v[94:97], v0, s[4:5] offset:1024 nt
	global_load_dwordx4 v[98:101], v0, s[4:5] offset:2048 nt
	global_load_dwordx4 v[102:105], v0, s[4:5] offset:3072 nt
	global_load_dwordx2 v[138:139], v1, s[12:13] offset:0 nt
	global_load_dwordx2 v[140:141], v1, s[12:13] offset:512 nt
	global_load_dwordx2 v[142:143], v1, s[12:13] offset:1024 nt
	global_load_dwordx2 v[144:145], v1, s[12:13] offset:1536 nt
	s_add_u32 s4, s4, 0x1000
	s_addc_u32 s5, s5, 0
	s_add_u32 s12, s12, 0x800
	s_addc_u32 s13, s13, 0
	global_load_dwordx4 v[106:109], v0, s[4:5] offset:0 nt
	global_load_dwordx4 v[110:113], v0, s[4:5] offset:1024 nt
	global_load_dwordx4 v[114:117], v0, s[4:5] offset:2048 nt
	global_load_dwordx4 v[118:121], v0, s[4:5] offset:3072 nt
	global_load_dwordx2 v[146:147], v1, s[12:13] offset:0 nt
	global_load_dwordx2 v[148:149], v1, s[12:13] offset:512 nt
	global_load_dwordx2 v[150:151], v1, s[12:13] offset:1024 nt
	global_load_dwordx2 v[152:153], v1, s[12:13] offset:1536 nt
	s_add_u32 s4, s4, 0x1000
	s_addc_u32 s5, s5, 0
	s_add_u32 s12, s12, 0x800
	s_addc_u32 s13, s13, 0
	s_waitcnt vmcnt(24)
; __device__ __forceinline__ unsigned cvt_pk_bf16(float lo, float hi) { unsigned r; asm volatile("v_cvt_pk_bf16_f32 %0, %1, %2" : "=v"(r) : "v"(lo), "v"(hi)); return r; }
; __device__ __forceinline__ float bflo(unsigned w) { return __uint_as_float(w << 16); }
; __device__ __forceinline__ float bfhi(unsigned w) { return __uint_as_float(w & 0xffff0000u); }
; template <bool BR, bool WH> ...
;     ...
;         if (BR) {
;             f32x4 m[4]; float s = 0.f;
; #pragma unroll
;             for (int j = 0; j < 4; ++j) { m[j] = (f32x4){bflo(bc[j].x), bfhi(bc[j].x), bflo(bc[j].y), bfhi(bc[j].y)};
;                 s += (m[j][0] * m[j][0] + m[j][1] * m[j][1]) + (m[j][2] * m[j][2] + m[j][3] * m[j][3]); }
;             const float rs = rsqrtf(wave_sum(s, lane) * (1.f / 1024.f) + EPS);
;             float* xo = row < ML ? xout_lat + (size_t)row * 1024 : xout_ctx + (size_t)(row - ML) * 1024;
; #pragma unroll
;             for (int j = 0; j < 4; ++j) { const f32x4 gp = *(const f32x4*)(g_post + 4 * lane + 256 * j), ga = *(const f32x4*)(mod_g + (size_t)mrow * 6144 + gate_off + 4 * lane + 256 * j);
;                 x[j] = x[j] + ga * ((m[j] * rs) * gp); __builtin_nontemporal_store(x[j], (f32x4*)(xo + 4 * lane + 256 * j)); }
;         }
;         if (WH) {
;             float s = 0.f;
; #pragma unroll
;             for (int j = 0; j < 4; ++j) s += (x[j][0] * x[j][0] + x[j][1] * x[j][1]) + (x[j][2] * x[j][2] + x[j][3] * x[j][3]);
;             const float rs = rsqrtf(wave_sum(s, lane) * (1.f / 1024.f) + EPS);
; #pragma unroll
;             for (int j = 0; j < 4; ++j) { const f32x4 gp = *(const f32x4*)(g_pre + 4 * lane + 256 * j), sc = *(const f32x4*)(mod_h + (size_t)mrow * 6144 + sc_off + 4 * lane + 256 * j),
;                     sh = *(const f32x4*)(mod_h + (size_t)mrow * 6144 + sh_off + 4 * lane + 256 * j);
;                 const f32x4 hv = ((x[j] * rs) * gp) * (sc + 1.0f) + sh;
;                 u32x2 w; w.x = cvt_pk_bf16(hv[0], hv[1]); w.y = cvt_pk_bf16(hv[2], hv[3]);
;                 *(u32x2*)(Hout + (size_t)row * 1024 + 4 * lane + 256 * j) = w; }
;         }
	v_pk_add_f32 v[208:209], v[208:209], 1.0 op_sel_hi:[1,0]
	v_pk_add_f32 v[210:211], v[210:211], 1.0 op_sel_hi:[1,0]
	v_pk_add_f32 v[212:213], v[212:213], 1.0 op_sel_hi:[1,0]
	v_pk_add_f32 v[214:215], v[214:215], 1.0 op_sel_hi:[1,0]
	v_pk_add_f32 v[220:221], v[220:221], 1.0 op_sel_hi:[1,0]
	v_pk_add_f32 v[222:223], v[222:223], 1.0 op_sel_hi:[1,0]
	v_pk_add_f32 v[224:225], v[224:225], 1.0 op_sel_hi:[1,0]
	v_pk_add_f32 v[226:227], v[226:227], 1.0 op_sel_hi:[1,0]
	v_lshlrev_b32_e32 v10, 16, v122
	v_and_b32_e32 v11, 0xffff0000, v122
	v_lshlrev_b32_e32 v12, 16, v123
	v_and_b32_e32 v13, 0xffff0000, v123
	v_lshlrev_b32_e32 v14, 16, v124
	v_and_b32_e32 v15, 0xffff0000, v124
	v_lshlrev_b32_e32 v16, 16, v125
	v_and_b32_e32 v17, 0xffff0000, v125
	v_lshlrev_b32_e32 v18, 16, v126
	v_and_b32_e32 v19, 0xffff0000, v126
	v_lshlrev_b32_e32 v20, 16, v127
	v_and_b32_e32 v21, 0xffff0000, v127
	v_lshlrev_b32_e32 v22, 16, v128
	v_and_b32_e32 v23, 0xffff0000, v128
	v_lshlrev_b32_e32 v24, 16, v129
	v_and_b32_e32 v25, 0xffff0000, v129
	v_mul_f32_e32 v6, v10, v10
	v_mul_f32_e32 v7, v11, v11
	v_fmac_f32_e32 v6, v12, v12
	v_fmac_f32_e32 v7, v13, v13
	v_fmac_f32_e32 v6, v14, v14
	v_fmac_f32_e32 v7, v15, v15
	v_fmac_f32_e32 v6, v16, v16
	v_fmac_f32_e32 v7, v17, v17
	v_fmac_f32_e32 v6, v18, v18
	v_fmac_f32_e32 v7, v19, v19
	v_fmac_f32_e32 v6, v20, v20
	v_fmac_f32_e32 v7, v21, v21
	v_fmac_f32_e32 v6, v22, v22
	v_fmac_f32_e32 v7, v23, v23
	v_fmac_f32_e32 v6, v24, v24
	v_fmac_f32_e32 v7, v25, v25
	v_add_f32_e32 v6, v6, v7
	s_nop 1
	v_add_f32_dpp v8, v6, v6 quad_perm:[1,0,3,2] row_mask:0xf bank_mask:0xf
	s_nop 1
	v_add_f32_dpp v8, v8, v8 quad_perm:[2,3,0,1] row_mask:0xf bank_mask:0xf
	s_nop 1
	v_add_f32_dpp v8, v8, v8 row_half_mirror row_mask:0xf bank_mask:0xf
	s_nop 1
	v_add_f32_dpp v8, v8, v8 row_mirror row_mask:0xf bank_mask:0xf
	s_nop 1
	v_add_f32_dpp v8, v8, v8 row_bcast:15 row_mask:0xa bank_mask:0xf
	s_nop 1
	v_add_f32_dpp v8, v8, v8 row_bcast:31 row_mask:0xc bank_mask:0xf
	s_nop 1
	v_readlane_b32 s84, v8, 63
	s_nop 1
	v_fma_f32 v4, s84, v2, v3
	v_rsq_f32_e32 v4, v4
	s_nop 0
	v_pk_mul_f32 v[34:35], v[10:11], v[4:5] op_sel_hi:[1,0]
	v_pk_mul_f32 v[36:37], v[12:13], v[4:5] op_sel_hi:[1,0]
	v_pk_mul_f32 v[38:39], v[14:15], v[4:5] op_sel_hi:[1,0]
	v_pk_mul_f32 v[40:41], v[16:17], v[4:5] op_sel_hi:[1,0]
	v_pk_mul_f32 v[42:43], v[18:19], v[4:5] op_sel_hi:[1,0]
	v_pk_mul_f32 v[44:45], v[20:21], v[4:5] op_sel_hi:[1,0]
	v_pk_mul_f32 v[46:47], v[22:23], v[4:5] op_sel_hi:[1,0]
	v_pk_mul_f32 v[48:49], v[24:25], v[4:5] op_sel_hi:[1,0]
	v_pk_mul_f32 v[34:35], v[34:35], v[154:155]
	v_pk_mul_f32 v[36:37], v[36:37], v[156:157]
	v_pk_mul_f32 v[38:39], v[38:39], v[158:159]
	v_pk_mul_f32 v[40:41], v[40:41], v[160:161]
	v_pk_mul_f32 v[42:43], v[42:43], v[162:163]
	v_pk_mul_f32 v[44:45], v[44:45], v[164:165]
	v_pk_mul_f32 v[46:47], v[46:47], v[166:167]
	v_pk_mul_f32 v[48:49], v[48:49], v[168:169]
	v_pk_fma_f32 v[58:59], v[176:177], v[34:35], v[58:59]
	v_pk_fma_f32 v[60:61], v[178:179], v[36:37], v[60:61]
	v_pk_fma_f32 v[62:63], v[180:181], v[38:39], v[62:63]
	v_pk_fma_f32 v[64:65], v[182:183], v[40:41], v[64:65]
	v_pk_fma_f32 v[66:67], v[184:185], v[42:43], v[66:67]
	v_pk_fma_f32 v[68:69], v[186:187], v[44:45], v[68:69]
	v_pk_fma_f32 v[70:71], v[188:189], v[46:47], v[70:71]
	v_pk_fma_f32 v[72:73], v[190:191], v[48:49], v[72:73]
	global_store_dwordx4 v0, v[58:61], s[14:15] offset:0 nt
	global_store_dwordx4 v0, v[62:65], s[14:15] offset:1024 nt
	global_store_dwordx4 v0, v[66:69], s[14:15] offset:2048 nt
	global_store_dwordx4 v0, v[70:73], s[14:15] offset:3072 nt
	s_add_u32 s14, s14, 0x1000
	s_addc_u32 s15, s15, 0
	v_mul_f32_e32 v6, v58, v58
	v_mul_f32_e32 v7, v59, v59
	v_fmac_f32_e32 v6, v60, v60
	v_fmac_f32_e32 v7, v61, v61
	v_fmac_f32_e32 v6, v62, v62
	v_fmac_f32_e32 v7, v63, v63
	v_fmac_f32_e32 v6, v64, v64
	v_fmac_f32_e32 v7, v65, v65
	v_fmac_f32_e32 v6, v66, v66
	v_fmac_f32_e32 v7, v67, v67
	v_fmac_f32_e32 v6, v68, v68
	v_fmac_f32_e32 v7, v69, v69
	v_fmac_f32_e32 v6, v70, v70
	v_fmac_f32_e32 v7, v71, v71
	v_fmac_f32_e32 v6, v72, v72
	v_fmac_f32_e32 v7, v73, v73
	v_add_f32_e32 v6, v6, v7
	s_nop 1
	v_add_f32_dpp v8, v6, v6 quad_perm:[1,0,3,2] row_mask:0xf bank_mask:0xf
	s_nop 1
	v_add_f32_dpp v8, v8, v8 quad_perm:[2,3,0,1] row_mask:0xf bank_mask:0xf
	s_nop 1
	v_add_f32_dpp v8, v8, v8 row_half_mirror row_mask:0xf bank_mask:0xf
	s_nop 1
	v_add_f32_dpp v8, v8, v8 row_mirror row_mask:0xf bank_mask:0xf
	s_nop 1
	v_add_f32_dpp v8, v8, v8 row_bcast:15 row_mask:0xa bank_mask:0xf
	s_nop 1
	v_add_f32_dpp v8, v8, v8 row_bcast:31 row_mask:0xc bank_mask:0xf
	s_nop 1
	v_readlane_b32 s84, v8, 63
	s_nop 1
	v_fma_f32 v4, s84, v2, v3
	v_rsq_f32_e32 v4, v4
	s_nop 0
	v_pk_mul_f32 v[34:35], v[58:59], v[4:5] op_sel_hi:[1,0]
	v_pk_mul_f32 v[36:37], v[60:61], v[4:5] op_sel_hi:[1,0]
	v_pk_mul_f32 v[38:39], v[62:63], v[4:5] op_sel_hi:[1,0]
	v_pk_mul_f32 v[40:41], v[64:65], v[4:5] op_sel_hi:[1,0]
	v_pk_mul_f32 v[42:43], v[66:67], v[4:5] op_sel_hi:[1,0]
	v_pk_mul_f32 v[44:45], v[68:69], v[4:5] op_sel_hi:[1,0]
	v_pk_mul_f32 v[46:47], v[70:71], v[4:5] op_sel_hi:[1,0]
	v_pk_mul_f32 v[48:49], v[72:73], v[4:5] op_sel_hi:[1,0]
	v_pk_mul_f32 v[34:35], v[34:35], v[192:193]
	v_pk_mul_f32 v[36:37], v[36:37], v[194:195]
	v_pk_mul_f32 v[38:39], v[38:39], v[196:197]
	v_pk_mul_f32 v[40:41], v[40:41], v[198:199]
	v_pk_mul_f32 v[42:43], v[42:43], v[200:201]
	v_pk_mul_f32 v[44:45], v[44:45], v[202:203]
	v_pk_mul_f32 v[46:47], v[46:47], v[204:205]
	v_pk_mul_f32 v[48:49], v[48:49], v[206:207]
	v_pk_fma_f32 v[34:35], v[34:35], v[208:209], v[228:229]
	v_pk_fma_f32 v[36:37], v[36:37], v[210:211], v[230:231]
; __device__ __forceinline__ unsigned cvt_pk_bf16(float lo, float hi) { unsigned r; asm volatile("v_cvt_pk_bf16_f32 %0, %1, %2" : "=v"(r) : "v"(lo), "v"(hi)); return r; }
; __device__ __forceinline__ float bflo(unsigned w) { return __uint_as_float(w << 16); }
; __device__ __forceinline__ float bfhi(unsigned w) { return __uint_as_float(w & 0xffff0000u); }
; template <bool BR, bool WH> ...
;     ...
;         if (BR) {
;             f32x4 m[4]; float s = 0.f;
; #pragma unroll
;             for (int j = 0; j < 4; ++j) { m[j] = (f32x4){bflo(bc[j].x), bfhi(bc[j].x), bflo(bc[j].y), bfhi(bc[j].y)};
;                 s += (m[j][0] * m[j][0] + m[j][1] * m[j][1]) + (m[j][2] * m[j][2] + m[j][3] * m[j][3]); }
;             const float rs = rsqrtf(wave_sum(s, lane) * (1.f / 1024.f) + EPS);
;             float* xo = row < ML ? xout_lat + (size_t)row * 1024 : xout_ctx + (size_t)(row - ML) * 1024;
; #pragma unroll
;             for (int j = 0; j < 4; ++j) { const f32x4 gp = *(const f32x4*)(g_post + 4 * lane + 256 * j), ga = *(const f32x4*)(mod_g + (size_t)mrow * 6144 + gate_off + 4 * lane + 256 * j);
;                 x[j] = x[j] + ga * ((m[j] * rs) * gp); __builtin_nontemporal_store(x[j], (f32x4*)(xo + 4 * lane + 256 * j)); }
;         }
;         if (WH) {
;             float s = 0.f;
; #pragma unroll
;             for (int j = 0; j < 4; ++j) s += (x[j][0] * x[j][0] + x[j][1] * x[j][1]) + (x[j][2] * x[j][2] + x[j][3] * x[j][3]);
;             const float rs = rsqrtf(wave_sum(s, lane) * (1.f / 1024.f) + EPS);
; #pragma unroll
;             for (int j = 0; j < 4; ++j) { const f32x4 gp = *(const f32x4*)(g_pre + 4 * lane + 256 * j), sc = *(const f32x4*)(mod_h + (size_t)mrow * 6144 + sc_off + 4 * lane + 256 * j),
;                     sh = *(const f32x4*)(mod_h + (size_t)mrow * 6144 + sh_off + 4 * lane + 256 * j);
;                 const f32x4 hv = ((x[j] * rs) * gp) * (sc + 1.0f) + sh;
;                 u32x2 w; w.x = cvt_pk_bf16(hv[0], hv[1]); w.y = cvt_pk_bf16(hv[2], hv[3]);
;                 *(u32x2*)(Hout + (size_t)row * 1024 + 4 * lane + 256 * j) = w; }
;         }
	v_pk_fma_f32 v[38:39], v[38:39], v[212:213], v[232:233]
	v_pk_fma_f32 v[40:41], v[40:41], v[214:215], v[234:235]
	v_pk_fma_f32 v[42:43], v[42:43], v[220:221], v[236:237]
	v_pk_fma_f32 v[44:45], v[44:45], v[222:223], v[238:239]
	v_pk_fma_f32 v[46:47], v[46:47], v[224:225], v[26:27]
	v_pk_fma_f32 v[48:49], v[48:49], v[226:227], v[28:29]
	v_cvt_pk_bf16_f32 v50, v34, v35
	v_cvt_pk_bf16_f32 v51, v36, v37
	v_cvt_pk_bf16_f32 v52, v38, v39
	v_cvt_pk_bf16_f32 v53, v40, v41
	v_cvt_pk_bf16_f32 v54, v42, v43
	v_cvt_pk_bf16_f32 v55, v44, v45
	v_cvt_pk_bf16_f32 v56, v46, v47
	v_cvt_pk_bf16_f32 v57, v48, v49
	global_store_dwordx2 v1, v[50:51], s[16:17] offset:0
	global_store_dwordx2 v1, v[52:53], s[16:17] offset:512
	global_store_dwordx2 v1, v[54:55], s[16:17] offset:1024
	global_store_dwordx2 v1, v[56:57], s[16:17] offset:1536
	s_add_u32 s16, s16, 0x800
	s_addc_u32 s17, s17, 0
	global_load_dwordx4 v[58:61], v0, s[4:5] offset:0 nt
	global_load_dwordx4 v[62:65], v0, s[4:5] offset:1024 nt
	global_load_dwordx4 v[66:69], v0, s[4:5] offset:2048 nt
	global_load_dwordx4 v[70:73], v0, s[4:5] offset:3072 nt
	global_load_dwordx2 v[122:123], v1, s[12:13] offset:0 nt
	global_load_dwordx2 v[124:125], v1, s[12:13] offset:512 nt
	global_load_dwordx2 v[126:127], v1, s[12:13] offset:1024 nt
	global_load_dwordx2 v[128:129], v1, s[12:13] offset:1536 nt
	s_add_u32 s4, s4, 0x1000
	s_addc_u32 s5, s5, 0
	s_add_u32 s12, s12, 0x800
	s_addc_u32 s13, s13, 0
	s_waitcnt vmcnt(32)
	v_lshlrev_b32_e32 v10, 16, v130
	v_and_b32_e32 v11, 0xffff0000, v130
	v_lshlrev_b32_e32 v12, 16, v131
	v_and_b32_e32 v13, 0xffff0000, v131
	v_lshlrev_b32_e32 v14, 16, v132
	v_and_b32_e32 v15, 0xffff0000, v132
	v_lshlrev_b32_e32 v16, 16, v133
	v_and_b32_e32 v17, 0xffff0000, v133
	v_lshlrev_b32_e32 v18, 16, v134
	v_and_b32_e32 v19, 0xffff0000, v134
	v_lshlrev_b32_e32 v20, 16, v135
	v_and_b32_e32 v21, 0xffff0000, v135
	v_lshlrev_b32_e32 v22, 16, v136
	v_and_b32_e32 v23, 0xffff0000, v136
	v_lshlrev_b32_e32 v24, 16, v137
	v_and_b32_e32 v25, 0xffff0000, v137
	v_mul_f32_e32 v6, v10, v10
	v_mul_f32_e32 v7, v11, v11
	v_fmac_f32_e32 v6, v12, v12
	v_fmac_f32_e32 v7, v13, v13
	v_fmac_f32_e32 v6, v14, v14
	v_fmac_f32_e32 v7, v15, v15
	v_fmac_f32_e32 v6, v16, v16
	v_fmac_f32_e32 v7, v17, v17
	v_fmac_f32_e32 v6, v18, v18
	v_fmac_f32_e32 v7, v19, v19
	v_fmac_f32_e32 v6, v20, v20
	v_fmac_f32_e32 v7, v21, v21
	v_fmac_f32_e32 v6, v22, v22
	v_fmac_f32_e32 v7, v23, v23
	v_fmac_f32_e32 v6, v24, v24
	v_fmac_f32_e32 v7, v25, v25
	v_add_f32_e32 v6, v6, v7
	s_nop 1
	v_add_f32_dpp v8, v6, v6 quad_perm:[1,0,3,2] row_mask:0xf bank_mask:0xf
	s_nop 1
	v_add_f32_dpp v8, v8, v8 quad_perm:[2,3,0,1] row_mask:0xf bank_mask:0xf
	s_nop 1
	v_add_f32_dpp v8, v8, v8 row_half_mirror row_mask:0xf bank_mask:0xf
	s_nop 1
	v_add_f32_dpp v8, v8, v8 row_mirror row_mask:0xf bank_mask:0xf
	s_nop 1
	v_add_f32_dpp v8, v8, v8 row_bcast:15 row_mask:0xa bank_mask:0xf
	s_nop 1
	v_add_f32_dpp v8, v8, v8 row_bcast:31 row_mask:0xc bank_mask:0xf
	s_nop 1
	v_readlane_b32 s84, v8, 63
	s_nop 1
	v_fma_f32 v4, s84, v2, v3
	v_rsq_f32_e32 v4, v4
	s_nop 0
	v_pk_mul_f32 v[34:35], v[10:11], v[4:5] op_sel_hi:[1,0]
	v_pk_mul_f32 v[36:37], v[12:13], v[4:5] op_sel_hi:[1,0]
	v_pk_mul_f32 v[38:39], v[14:15], v[4:5] op_sel_hi:[1,0]
	v_pk_mul_f32 v[40:41], v[16:17], v[4:5] op_sel_hi:[1,0]
	v_pk_mul_f32 v[42:43], v[18:19], v[4:5] op_sel_hi:[1,0]
	v_pk_mul_f32 v[44:45], v[20:21], v[4:5] op_sel_hi:[1,0]
	v_pk_mul_f32 v[46:47], v[22:23], v[4:5] op_sel_hi:[1,0]
	v_pk_mul_f32 v[48:49], v[24:25], v[4:5] op_sel_hi:[1,0]
	v_pk_mul_f32 v[34:35], v[34:35], v[154:155]
	v_pk_mul_f32 v[36:37], v[36:37], v[156:157]
	v_pk_mul_f32 v[38:39], v[38:39], v[158:159]
	v_pk_mul_f32 v[40:41], v[40:41], v[160:161]
	v_pk_mul_f32 v[42:43], v[42:43], v[162:163]
	v_pk_mul_f32 v[44:45], v[44:45], v[164:165]
	v_pk_mul_f32 v[46:47], v[46:47], v[166:167]
	v_pk_mul_f32 v[48:49], v[48:49], v[168:169]
	v_pk_fma_f32 v[74:75], v[176:177], v[34:35], v[74:75]
	v_pk_fma_f32 v[76:77], v[178:179], v[36:37], v[76:77]
	v_pk_fma_f32 v[78:79], v[180:181], v[38:39], v[78:79]
	v_pk_fma_f32 v[80:81], v[182:183], v[40:41], v[80:81]
	v_pk_fma_f32 v[82:83], v[184:185], v[42:43], v[82:83]
	v_pk_fma_f32 v[84:85], v[186:187], v[44:45], v[84:85]
	v_pk_fma_f32 v[86:87], v[188:189], v[46:47], v[86:87]
	v_pk_fma_f32 v[88:89], v[190:191], v[48:49], v[88:89]
	global_store_dwordx4 v0, v[74:77], s[14:15] offset:0 nt
	global_store_dwordx4 v0, v[78:81], s[14:15] offset:1024 nt
	global_store_dwordx4 v0, v[82:85], s[14:15] offset:2048 nt
	global_store_dwordx4 v0, v[86:89], s[14:15] offset:3072 nt
	s_add_u32 s14, s14, 0x1000
	s_addc_u32 s15, s15, 0
	v_mul_f32_e32 v6, v74, v74
	v_mul_f32_e32 v7, v75, v75
	v_fmac_f32_e32 v6, v76, v76
	v_fmac_f32_e32 v7, v77, v77
	v_fmac_f32_e32 v6, v78, v78
	v_fmac_f32_e32 v7, v79, v79
	v_fmac_f32_e32 v6, v80, v80
	v_fmac_f32_e32 v7, v81, v81
	v_fmac_f32_e32 v6, v82, v82
	v_fmac_f32_e32 v7, v83, v83
	v_fmac_f32_e32 v6, v84, v84
	v_fmac_f32_e32 v7, v85, v85
	v_fmac_f32_e32 v6, v86, v86
	v_fmac_f32_e32 v7, v87, v87
	v_fmac_f32_e32 v6, v88, v88
	v_fmac_f32_e32 v7, v89, v89
	v_add_f32_e32 v6, v6, v7
	s_nop 1
	v_add_f32_dpp v8, v6, v6 quad_perm:[1,0,3,2] row_mask:0xf bank_mask:0xf
	s_nop 1
	v_add_f32_dpp v8, v8, v8 quad_perm:[2,3,0,1] row_mask:0xf bank_mask:0xf
	s_nop 1
	v_add_f32_dpp v8, v8, v8 row_half_mirror row_mask:0xf bank_mask:0xf
	s_nop 1
	v_add_f32_dpp v8, v8, v8 row_mirror row_mask:0xf bank_mask:0xf
	s_nop 1
	v_add_f32_dpp v8, v8, v8 row_bcast:15 row_mask:0xa bank_mask:0xf
	s_nop 1
	v_add_f32_dpp v8, v8, v8 row_bcast:31 row_mask:0xc bank_mask:0xf
	s_nop 1
	v_readlane_b32 s84, v8, 63
	s_nop 1
	v_fma_f32 v4, s84, v2, v3
; __device__ __forceinline__ unsigned cvt_pk_bf16(float lo, float hi) { unsigned r; asm volatile("v_cvt_pk_bf16_f32 %0, %1, %2" : "=v"(r) : "v"(lo), "v"(hi)); return r; }
; __device__ __forceinline__ float bflo(unsigned w) { return __uint_as_float(w << 16); }
; __device__ __forceinline__ float bfhi(unsigned w) { return __uint_as_float(w & 0xffff0000u); }
; template <bool BR, bool WH> ...
;     ...
;         if (BR) {
;             f32x4 m[4]; float s = 0.f;
; #pragma unroll
;             for (int j = 0; j < 4; ++j) { m[j] = (f32x4){bflo(bc[j].x), bfhi(bc[j].x), bflo(bc[j].y), bfhi(bc[j].y)};
;                 s += (m[j][0] * m[j][0] + m[j][1] * m[j][1]) + (m[j][2] * m[j][2] + m[j][3] * m[j][3]); }
;             const float rs = rsqrtf(wave_sum(s, lane) * (1.f / 1024.f) + EPS);
;             float* xo = row < ML ? xout_lat + (size_t)row * 1024 : xout_ctx + (size_t)(row - ML) * 1024;
; #pragma unroll
;             for (int j = 0; j < 4; ++j) { const f32x4 gp = *(const f32x4*)(g_post + 4 * lane + 256 * j), ga = *(const f32x4*)(mod_g + (size_t)mrow * 6144 + gate_off + 4 * lane + 256 * j);
;                 x[j] = x[j] + ga * ((m[j] * rs) * gp); __builtin_nontemporal_store(x[j], (f32x4*)(xo + 4 * lane + 256 * j)); }
;         }
;         if (WH) {
;             float s = 0.f;
; #pragma unroll
;             for (int j = 0; j < 4; ++j) s += (x[j][0] * x[j][0] + x[j][1] * x[j][1]) + (x[j][2] * x[j][2] + x[j][3] * x[j][3]);
;             const float rs = rsqrtf(wave_sum(s, lane) * (1.f / 1024.f) + EPS);
; #pragma unroll
;             for (int j = 0; j < 4; ++j) { const f32x4 gp = *(const f32x4*)(g_pre + 4 * lane + 256 * j), sc = *(const f32x4*)(mod_h + (size_t)mrow * 6144 + sc_off + 4 * lane + 256 * j),
;                     sh = *(const f32x4*)(mod_h + (size_t)mrow * 6144 + sh_off + 4 * lane + 256 * j);
;                 const f32x4 hv = ((x[j] * rs) * gp) * (sc + 1.0f) + sh;
;                 u32x2 w; w.x = cvt_pk_bf16(hv[0], hv[1]); w.y = cvt_pk_bf16(hv[2], hv[3]);
;                 *(u32x2*)(Hout + (size_t)row * 1024 + 4 * lane + 256 * j) = w; }
;         }
	v_rsq_f32_e32 v4, v4
	s_nop 0
	v_pk_mul_f32 v[34:35], v[74:75], v[4:5] op_sel_hi:[1,0]
	v_pk_mul_f32 v[36:37], v[76:77], v[4:5] op_sel_hi:[1,0]
	v_pk_mul_f32 v[38:39], v[78:79], v[4:5] op_sel_hi:[1,0]
	v_pk_mul_f32 v[40:41], v[80:81], v[4:5] op_sel_hi:[1,0]
	v_pk_mul_f32 v[42:43], v[82:83], v[4:5] op_sel_hi:[1,0]
	v_pk_mul_f32 v[44:45], v[84:85], v[4:5] op_sel_hi:[1,0]
	v_pk_mul_f32 v[46:47], v[86:87], v[4:5] op_sel_hi:[1,0]
	v_pk_mul_f32 v[48:49], v[88:89], v[4:5] op_sel_hi:[1,0]
	v_pk_mul_f32 v[34:35], v[34:35], v[192:193]
	v_pk_mul_f32 v[36:37], v[36:37], v[194:195]
	v_pk_mul_f32 v[38:39], v[38:39], v[196:197]
	v_pk_mul_f32 v[40:41], v[40:41], v[198:199]
	v_pk_mul_f32 v[42:43], v[42:43], v[200:201]
	v_pk_mul_f32 v[44:45], v[44:45], v[202:203]
	v_pk_mul_f32 v[46:47], v[46:47], v[204:205]
	v_pk_mul_f32 v[48:49], v[48:49], v[206:207]
	v_pk_fma_f32 v[34:35], v[34:35], v[208:209], v[228:229]
	v_pk_fma_f32 v[36:37], v[36:37], v[210:211], v[230:231]
	v_pk_fma_f32 v[38:39], v[38:39], v[212:213], v[232:233]
	v_pk_fma_f32 v[40:41], v[40:41], v[214:215], v[234:235]
	v_pk_fma_f32 v[42:43], v[42:43], v[220:221], v[236:237]
	v_pk_fma_f32 v[44:45], v[44:45], v[222:223], v[238:239]
	v_pk_fma_f32 v[46:47], v[46:47], v[224:225], v[26:27]
	v_pk_fma_f32 v[48:49], v[48:49], v[226:227], v[28:29]
	v_cvt_pk_bf16_f32 v50, v34, v35
	v_cvt_pk_bf16_f32 v51, v36, v37
	v_cvt_pk_bf16_f32 v52, v38, v39
	v_cvt_pk_bf16_f32 v53, v40, v41
	v_cvt_pk_bf16_f32 v54, v42, v43
	v_cvt_pk_bf16_f32 v55, v44, v45
	v_cvt_pk_bf16_f32 v56, v46, v47
	v_cvt_pk_bf16_f32 v57, v48, v49
	global_store_dwordx2 v1, v[50:51], s[16:17] offset:0
	global_store_dwordx2 v1, v[52:53], s[16:17] offset:512
	global_store_dwordx2 v1, v[54:55], s[16:17] offset:1024
	global_store_dwordx2 v1, v[56:57], s[16:17] offset:1536
	s_add_u32 s16, s16, 0x800
	s_addc_u32 s17, s17, 0
	global_load_dwordx4 v[74:77], v0, s[4:5] offset:0 nt
	global_load_dwordx4 v[78:81], v0, s[4:5] offset:1024 nt
	global_load_dwordx4 v[82:85], v0, s[4:5] offset:2048 nt
	global_load_dwordx4 v[86:89], v0, s[4:5] offset:3072 nt
	global_load_dwordx2 v[130:131], v1, s[12:13] offset:0 nt
	global_load_dwordx2 v[132:133], v1, s[12:13] offset:512 nt
	global_load_dwordx2 v[134:135], v1, s[12:13] offset:1024 nt
	global_load_dwordx2 v[136:137], v1, s[12:13] offset:1536 nt
	s_add_u32 s4, s4, 0x1000
	s_addc_u32 s5, s5, 0
	s_add_u32 s12, s12, 0x800
	s_addc_u32 s13, s13, 0
	s_waitcnt vmcnt(40)
	v_lshlrev_b32_e32 v10, 16, v138
	v_and_b32_e32 v11, 0xffff0000, v138
	v_lshlrev_b32_e32 v12, 16, v139
	v_and_b32_e32 v13, 0xffff0000, v139
	v_lshlrev_b32_e32 v14, 16, v140
	v_and_b32_e32 v15, 0xffff0000, v140
	v_lshlrev_b32_e32 v16, 16, v141
	v_and_b32_e32 v17, 0xffff0000, v141
	v_lshlrev_b32_e32 v18, 16, v142
	v_and_b32_e32 v19, 0xffff0000, v142
	v_lshlrev_b32_e32 v20, 16, v143
	v_and_b32_e32 v21, 0xffff0000, v143
	v_lshlrev_b32_e32 v22, 16, v144
	v_and_b32_e32 v23, 0xffff0000, v144
	v_lshlrev_b32_e32 v24, 16, v145
	v_and_b32_e32 v25, 0xffff0000, v145
	v_mul_f32_e32 v6, v10, v10
	v_mul_f32_e32 v7, v11, v11
	v_fmac_f32_e32 v6, v12, v12
	v_fmac_f32_e32 v7, v13, v13
	v_fmac_f32_e32 v6, v14, v14
	v_fmac_f32_e32 v7, v15, v15
	v_fmac_f32_e32 v6, v16, v16
	v_fmac_f32_e32 v7, v17, v17
	v_fmac_f32_e32 v6, v18, v18
	v_fmac_f32_e32 v7, v19, v19
	v_fmac_f32_e32 v6, v20, v20
	v_fmac_f32_e32 v7, v21, v21
	v_fmac_f32_e32 v6, v22, v22
	v_fmac_f32_e32 v7, v23, v23
	v_fmac_f32_e32 v6, v24, v24
	v_fmac_f32_e32 v7, v25, v25
	v_add_f32_e32 v6, v6, v7
	s_nop 1
	v_add_f32_dpp v8, v6, v6 quad_perm:[1,0,3,2] row_mask:0xf bank_mask:0xf
	s_nop 1
	v_add_f32_dpp v8, v8, v8 quad_perm:[2,3,0,1] row_mask:0xf bank_mask:0xf
	s_nop 1
	v_add_f32_dpp v8, v8, v8 row_half_mirror row_mask:0xf bank_mask:0xf
	s_nop 1
	v_add_f32_dpp v8, v8, v8 row_mirror row_mask:0xf bank_mask:0xf
	s_nop 1
	v_add_f32_dpp v8, v8, v8 row_bcast:15 row_mask:0xa bank_mask:0xf
	s_nop 1
	v_add_f32_dpp v8, v8, v8 row_bcast:31 row_mask:0xc bank_mask:0xf
	s_nop 1
	v_readlane_b32 s84, v8, 63
	s_nop 1
	v_fma_f32 v4, s84, v2, v3
	v_rsq_f32_e32 v4, v4
	s_nop 0
	v_pk_mul_f32 v[34:35], v[10:11], v[4:5] op_sel_hi:[1,0]
	v_pk_mul_f32 v[36:37], v[12:13], v[4:5] op_sel_hi:[1,0]
	v_pk_mul_f32 v[38:39], v[14:15], v[4:5] op_sel_hi:[1,0]
	v_pk_mul_f32 v[40:41], v[16:17], v[4:5] op_sel_hi:[1,0]
	v_pk_mul_f32 v[42:43], v[18:19], v[4:5] op_sel_hi:[1,0]
	v_pk_mul_f32 v[44:45], v[20:21], v[4:5] op_sel_hi:[1,0]
	v_pk_mul_f32 v[46:47], v[22:23], v[4:5] op_sel_hi:[1,0]
	v_pk_mul_f32 v[48:49], v[24:25], v[4:5] op_sel_hi:[1,0]
	v_pk_mul_f32 v[34:35], v[34:35], v[154:155]
	v_pk_mul_f32 v[36:37], v[36:37], v[156:157]
	v_pk_mul_f32 v[38:39], v[38:39], v[158:159]
	v_pk_mul_f32 v[40:41], v[40:41], v[160:161]
	v_pk_mul_f32 v[42:43], v[42:43], v[162:163]
	v_pk_mul_f32 v[44:45], v[44:45], v[164:165]
	v_pk_mul_f32 v[46:47], v[46:47], v[166:167]
	v_pk_mul_f32 v[48:49], v[48:49], v[168:169]
	v_pk_fma_f32 v[90:91], v[176:177], v[34:35], v[90:91]
	v_pk_fma_f32 v[92:93], v[178:179], v[36:37], v[92:93]
	v_pk_fma_f32 v[94:95], v[180:181], v[38:39], v[94:95]
	v_pk_fma_f32 v[96:97], v[182:183], v[40:41], v[96:97]
	v_pk_fma_f32 v[98:99], v[184:185], v[42:43], v[98:99]
	v_pk_fma_f32 v[100:101], v[186:187], v[44:45], v[100:101]
	v_pk_fma_f32 v[102:103], v[188:189], v[46:47], v[102:103]
	v_pk_fma_f32 v[104:105], v[190:191], v[48:49], v[104:105]
	global_store_dwordx4 v0, v[90:93], s[14:15] offset:0 nt
	global_store_dwordx4 v0, v[94:97], s[14:15] offset:1024 nt
	global_store_dwordx4 v0, v[98:101], s[14:15] offset:2048 nt
	global_store_dwordx4 v0, v[102:105], s[14:15] offset:3072 nt
	s_add_u32 s14, s14, 0x1000
	s_addc_u32 s15, s15, 0
	v_mul_f32_e32 v6, v90, v90
; __device__ __forceinline__ unsigned cvt_pk_bf16(float lo, float hi) { unsigned r; asm volatile("v_cvt_pk_bf16_f32 %0, %1, %2" : "=v"(r) : "v"(lo), "v"(hi)); return r; }
; __device__ __forceinline__ float bflo(unsigned w) { return __uint_as_float(w << 16); }
; __device__ __forceinline__ float bfhi(unsigned w) { return __uint_as_float(w & 0xffff0000u); }
; template <bool BR, bool WH> ...
;     ...
;         if (BR) {
;             f32x4 m[4]; float s = 0.f;
; #pragma unroll
;             for (int j = 0; j < 4; ++j) { m[j] = (f32x4){bflo(bc[j].x), bfhi(bc[j].x), bflo(bc[j].y), bfhi(bc[j].y)};
;                 s += (m[j][0] * m[j][0] + m[j][1] * m[j][1]) + (m[j][2] * m[j][2] + m[j][3] * m[j][3]); }
;             const float rs = rsqrtf(wave_sum(s, lane) * (1.f / 1024.f) + EPS);
;             float* xo = row < ML ? xout_lat + (size_t)row * 1024 : xout_ctx + (size_t)(row - ML) * 1024;
; #pragma unroll
;             for (int j = 0; j < 4; ++j) { const f32x4 gp = *(const f32x4*)(g_post + 4 * lane + 256 * j), ga = *(const f32x4*)(mod_g + (size_t)mrow * 6144 + gate_off + 4 * lane + 256 * j);
;                 x[j] = x[j] + ga * ((m[j] * rs) * gp); __builtin_nontemporal_store(x[j], (f32x4*)(xo + 4 * lane + 256 * j)); }
;         }
;         if (WH) {
;             float s = 0.f;
; #pragma unroll
;             for (int j = 0; j < 4; ++j) s += (x[j][0] * x[j][0] + x[j][1] * x[j][1]) + (x[j][2] * x[j][2] + x[j][3] * x[j][3]);
;             const float rs = rsqrtf(wave_sum(s, lane) * (1.f / 1024.f) + EPS);
; #pragma unroll
;             for (int j = 0; j < 4; ++j) { const f32x4 gp = *(const f32x4*)(g_pre + 4 * lane + 256 * j), sc = *(const f32x4*)(mod_h + (size_t)mrow * 6144 + sc_off + 4 * lane + 256 * j),
;                     sh = *(const f32x4*)(mod_h + (size_t)mrow * 6144 + sh_off + 4 * lane + 256 * j);
;                 const f32x4 hv = ((x[j] * rs) * gp) * (sc + 1.0f) + sh;
;                 u32x2 w; w.x = cvt_pk_bf16(hv[0], hv[1]); w.y = cvt_pk_bf16(hv[2], hv[3]);
;                 *(u32x2*)(Hout + (size_t)row * 1024 + 4 * lane + 256 * j) = w; }
;         }
	v_mul_f32_e32 v7, v91, v91
	v_fmac_f32_e32 v6, v92, v92
	v_fmac_f32_e32 v7, v93, v93
	v_fmac_f32_e32 v6, v94, v94
	v_fmac_f32_e32 v7, v95, v95
	v_fmac_f32_e32 v6, v96, v96
	v_fmac_f32_e32 v7, v97, v97
	v_fmac_f32_e32 v6, v98, v98
	v_fmac_f32_e32 v7, v99, v99
	v_fmac_f32_e32 v6, v100, v100
	v_fmac_f32_e32 v7, v101, v101
	v_fmac_f32_e32 v6, v102, v102
	v_fmac_f32_e32 v7, v103, v103
	v_fmac_f32_e32 v6, v104, v104
	v_fmac_f32_e32 v7, v105, v105
	v_add_f32_e32 v6, v6, v7
	s_nop 1
	v_add_f32_dpp v8, v6, v6 quad_perm:[1,0,3,2] row_mask:0xf bank_mask:0xf
	s_nop 1
	v_add_f32_dpp v8, v8, v8 quad_perm:[2,3,0,1] row_mask:0xf bank_mask:0xf
	s_nop 1
	v_add_f32_dpp v8, v8, v8 row_half_mirror row_mask:0xf bank_mask:0xf
	s_nop 1
	v_add_f32_dpp v8, v8, v8 row_mirror row_mask:0xf bank_mask:0xf
	s_nop 1
	v_add_f32_dpp v8, v8, v8 row_bcast:15 row_mask:0xa bank_mask:0xf
	s_nop 1
	v_add_f32_dpp v8, v8, v8 row_bcast:31 row_mask:0xc bank_mask:0xf
	s_nop 1
	v_readlane_b32 s84, v8, 63
	s_nop 1
	v_fma_f32 v4, s84, v2, v3
	v_rsq_f32_e32 v4, v4
	s_nop 0
	v_pk_mul_f32 v[34:35], v[90:91], v[4:5] op_sel_hi:[1,0]
	v_pk_mul_f32 v[36:37], v[92:93], v[4:5] op_sel_hi:[1,0]
	v_pk_mul_f32 v[38:39], v[94:95], v[4:5] op_sel_hi:[1,0]
	v_pk_mul_f32 v[40:41], v[96:97], v[4:5] op_sel_hi:[1,0]
	v_pk_mul_f32 v[42:43], v[98:99], v[4:5] op_sel_hi:[1,0]
	v_pk_mul_f32 v[44:45], v[100:101], v[4:5] op_sel_hi:[1,0]
	v_pk_mul_f32 v[46:47], v[102:103], v[4:5] op_sel_hi:[1,0]
	v_pk_mul_f32 v[48:49], v[104:105], v[4:5] op_sel_hi:[1,0]
	v_pk_mul_f32 v[34:35], v[34:35], v[192:193]
	v_pk_mul_f32 v[36:37], v[36:37], v[194:195]
	v_pk_mul_f32 v[38:39], v[38:39], v[196:197]
	v_pk_mul_f32 v[40:41], v[40:41], v[198:199]
	v_pk_mul_f32 v[42:43], v[42:43], v[200:201]
	v_pk_mul_f32 v[44:45], v[44:45], v[202:203]
	v_pk_mul_f32 v[46:47], v[46:47], v[204:205]
	v_pk_mul_f32 v[48:49], v[48:49], v[206:207]
	v_pk_fma_f32 v[34:35], v[34:35], v[208:209], v[228:229]
	v_pk_fma_f32 v[36:37], v[36:37], v[210:211], v[230:231]
	v_pk_fma_f32 v[38:39], v[38:39], v[212:213], v[232:233]
	v_pk_fma_f32 v[40:41], v[40:41], v[214:215], v[234:235]
	v_pk_fma_f32 v[42:43], v[42:43], v[220:221], v[236:237]
	v_pk_fma_f32 v[44:45], v[44:45], v[222:223], v[238:239]
	v_pk_fma_f32 v[46:47], v[46:47], v[224:225], v[26:27]
	v_pk_fma_f32 v[48:49], v[48:49], v[226:227], v[28:29]
	v_cvt_pk_bf16_f32 v50, v34, v35
	v_cvt_pk_bf16_f32 v51, v36, v37
	v_cvt_pk_bf16_f32 v52, v38, v39
	v_cvt_pk_bf16_f32 v53, v40, v41
	v_cvt_pk_bf16_f32 v54, v42, v43
	v_cvt_pk_bf16_f32 v55, v44, v45
	v_cvt_pk_bf16_f32 v56, v46, v47
	v_cvt_pk_bf16_f32 v57, v48, v49
	global_store_dwordx2 v1, v[50:51], s[16:17] offset:0
	global_store_dwordx2 v1, v[52:53], s[16:17] offset:512
	global_store_dwordx2 v1, v[54:55], s[16:17] offset:1024
	global_store_dwordx2 v1, v[56:57], s[16:17] offset:1536
	s_add_u32 s16, s16, 0x800
	s_addc_u32 s17, s17, 0
	global_load_dwordx4 v[90:93], v0, s[4:5] offset:0 nt
	global_load_dwordx4 v[94:97], v0, s[4:5] offset:1024 nt
	global_load_dwordx4 v[98:101], v0, s[4:5] offset:2048 nt
	global_load_dwordx4 v[102:105], v0, s[4:5] offset:3072 nt
	global_load_dwordx2 v[138:139], v1, s[12:13] offset:0 nt
	global_load_dwordx2 v[140:141], v1, s[12:13] offset:512 nt
	global_load_dwordx2 v[142:143], v1, s[12:13] offset:1024 nt
	global_load_dwordx2 v[144:145], v1, s[12:13] offset:1536 nt
	s_add_u32 s4, s4, 0x1000
	s_addc_u32 s5, s5, 0
	s_add_u32 s12, s12, 0x800
	s_addc_u32 s13, s13, 0
	s_waitcnt vmcnt(48)
	v_lshlrev_b32_e32 v10, 16, v146
	v_and_b32_e32 v11, 0xffff0000, v146
	v_lshlrev_b32_e32 v12, 16, v147
	v_and_b32_e32 v13, 0xffff0000, v147
	v_lshlrev_b32_e32 v14, 16, v148
	v_and_b32_e32 v15, 0xffff0000, v148
	v_lshlrev_b32_e32 v16, 16, v149
	v_and_b32_e32 v17, 0xffff0000, v149
	v_lshlrev_b32_e32 v18, 16, v150
	v_and_b32_e32 v19, 0xffff0000, v150
	v_lshlrev_b32_e32 v20, 16, v151
	v_and_b32_e32 v21, 0xffff0000, v151
	v_lshlrev_b32_e32 v22, 16, v152
	v_and_b32_e32 v23, 0xffff0000, v152
	v_lshlrev_b32_e32 v24, 16, v153
	v_and_b32_e32 v25, 0xffff0000, v153
	v_mul_f32_e32 v6, v10, v10
	v_mul_f32_e32 v7, v11, v11
	v_fmac_f32_e32 v6, v12, v12
	v_fmac_f32_e32 v7, v13, v13
	v_fmac_f32_e32 v6, v14, v14
	v_fmac_f32_e32 v7, v15, v15
	v_fmac_f32_e32 v6, v16, v16
	v_fmac_f32_e32 v7, v17, v17
	v_fmac_f32_e32 v6, v18, v18
	v_fmac_f32_e32 v7, v19, v19
	v_fmac_f32_e32 v6, v20, v20
	v_fmac_f32_e32 v7, v21, v21
	v_fmac_f32_e32 v6, v22, v22
	v_fmac_f32_e32 v7, v23, v23
	v_fmac_f32_e32 v6, v24, v24
	v_fmac_f32_e32 v7, v25, v25
	v_add_f32_e32 v6, v6, v7
	s_nop 1
	v_add_f32_dpp v8, v6, v6 quad_perm:[1,0,3,2] row_mask:0xf bank_mask:0xf
	s_nop 1
	v_add_f32_dpp v8, v8, v8 quad_perm:[2,3,0,1] row_mask:0xf bank_mask:0xf
	s_nop 1
	v_add_f32_dpp v8, v8, v8 row_half_mirror row_mask:0xf bank_mask:0xf
	s_nop 1
	v_add_f32_dpp v8, v8, v8 row_mirror row_mask:0xf bank_mask:0xf
	s_nop 1
	v_add_f32_dpp v8, v8, v8 row_bcast:15 row_mask:0xa bank_mask:0xf
	s_nop 1
	v_add_f32_dpp v8, v8, v8 row_bcast:31 row_mask:0xc bank_mask:0xf
	s_nop 1
	v_readlane_b32 s84, v8, 63
	s_nop 1
	v_fma_f32 v4, s84, v2, v3
	v_rsq_f32_e32 v4, v4
	s_nop 0
	v_pk_mul_f32 v[34:35], v[10:11], v[4:5] op_sel_hi:[1,0]
	v_pk_mul_f32 v[36:37], v[12:13], v[4:5] op_sel_hi:[1,0]
	v_pk_mul_f32 v[38:39], v[14:15], v[4:5] op_sel_hi:[1,0]
	v_pk_mul_f32 v[40:41], v[16:17], v[4:5] op_sel_hi:[1,0]
	v_pk_mul_f32 v[42:43], v[18:19], v[4:5] op_sel_hi:[1,0]
	v_pk_mul_f32 v[44:45], v[20:21], v[4:5] op_sel_hi:[1,0]
	v_pk_mul_f32 v[46:47], v[22:23], v[4:5] op_sel_hi:[1,0]
	v_pk_mul_f32 v[48:49], v[24:25], v[4:5] op_sel_hi:[1,0]
	v_pk_mul_f32 v[34:35], v[34:35], v[154:155]
	v_pk_mul_f32 v[36:37], v[36:37], v[156:157]
	v_pk_mul_f32 v[38:39], v[38:39], v[158:159]
; __device__ __forceinline__ unsigned cvt_pk_bf16(float lo, float hi) { unsigned r; asm volatile("v_cvt_pk_bf16_f32 %0, %1, %2" : "=v"(r) : "v"(lo), "v"(hi)); return r; }
; __device__ __forceinline__ float bflo(unsigned w) { return __uint_as_float(w << 16); }
; __device__ __forceinline__ float bfhi(unsigned w) { return __uint_as_float(w & 0xffff0000u); }
; template <bool BR, bool WH> ...
;     ...
;         if (BR) {
;             f32x4 m[4]; float s = 0.f;
; #pragma unroll
;             for (int j = 0; j < 4; ++j) { m[j] = (f32x4){bflo(bc[j].x), bfhi(bc[j].x), bflo(bc[j].y), bfhi(bc[j].y)};
;                 s += (m[j][0] * m[j][0] + m[j][1] * m[j][1]) + (m[j][2] * m[j][2] + m[j][3] * m[j][3]); }
;             const float rs = rsqrtf(wave_sum(s, lane) * (1.f / 1024.f) + EPS);
;             float* xo = row < ML ? xout_lat + (size_t)row * 1024 : xout_ctx + (size_t)(row - ML) * 1024;
; #pragma unroll
;             for (int j = 0; j < 4; ++j) { const f32x4 gp = *(const f32x4*)(g_post + 4 * lane + 256 * j), ga = *(const f32x4*)(mod_g + (size_t)mrow * 6144 + gate_off + 4 * lane + 256 * j);
;                 x[j] = x[j] + ga * ((m[j] * rs) * gp); __builtin_nontemporal_store(x[j], (f32x4*)(xo + 4 * lane + 256 * j)); }
;         }
;         if (WH) {
;             float s = 0.f;
; #pragma unroll
;             for (int j = 0; j < 4; ++j) s += (x[j][0] * x[j][0] + x[j][1] * x[j][1]) + (x[j][2] * x[j][2] + x[j][3] * x[j][3]);
;             const float rs = rsqrtf(wave_sum(s, lane) * (1.f / 1024.f) + EPS);
; #pragma unroll
;             for (int j = 0; j < 4; ++j) { const f32x4 gp = *(const f32x4*)(g_pre + 4 * lane + 256 * j), sc = *(const f32x4*)(mod_h + (size_t)mrow * 6144 + sc_off + 4 * lane + 256 * j),
;                     sh = *(const f32x4*)(mod_h + (size_t)mrow * 6144 + sh_off + 4 * lane + 256 * j);
;                 const f32x4 hv = ((x[j] * rs) * gp) * (sc + 1.0f) + sh;
;                 u32x2 w; w.x = cvt_pk_bf16(hv[0], hv[1]); w.y = cvt_pk_bf16(hv[2], hv[3]);
;                 *(u32x2*)(Hout + (size_t)row * 1024 + 4 * lane + 256 * j) = w; }
;         }
	v_pk_mul_f32 v[40:41], v[40:41], v[160:161]
	v_pk_mul_f32 v[42:43], v[42:43], v[162:163]
	v_pk_mul_f32 v[44:45], v[44:45], v[164:165]
	v_pk_mul_f32 v[46:47], v[46:47], v[166:167]
	v_pk_mul_f32 v[48:49], v[48:49], v[168:169]
	v_pk_fma_f32 v[106:107], v[176:177], v[34:35], v[106:107]
	v_pk_fma_f32 v[108:109], v[178:179], v[36:37], v[108:109]
	v_pk_fma_f32 v[110:111], v[180:181], v[38:39], v[110:111]
	v_pk_fma_f32 v[112:113], v[182:183], v[40:41], v[112:113]
	v_pk_fma_f32 v[114:115], v[184:185], v[42:43], v[114:115]
	v_pk_fma_f32 v[116:117], v[186:187], v[44:45], v[116:117]
	v_pk_fma_f32 v[118:119], v[188:189], v[46:47], v[118:119]
	v_pk_fma_f32 v[120:121], v[190:191], v[48:49], v[120:121]
	global_store_dwordx4 v0, v[106:109], s[14:15] offset:0 nt
	global_store_dwordx4 v0, v[110:113], s[14:15] offset:1024 nt
	global_store_dwordx4 v0, v[114:117], s[14:15] offset:2048 nt
	global_store_dwordx4 v0, v[118:121], s[14:15] offset:3072 nt
	s_add_u32 s14, s14, 0x1000
	s_addc_u32 s15, s15, 0
	v_mul_f32_e32 v6, v106, v106
	v_mul_f32_e32 v7, v107, v107
	v_fmac_f32_e32 v6, v108, v108
	v_fmac_f32_e32 v7, v109, v109
	v_fmac_f32_e32 v6, v110, v110
	v_fmac_f32_e32 v7, v111, v111
	v_fmac_f32_e32 v6, v112, v112
	v_fmac_f32_e32 v7, v113, v113
	v_fmac_f32_e32 v6, v114, v114
	v_fmac_f32_e32 v7, v115, v115
	v_fmac_f32_e32 v6, v116, v116
	v_fmac_f32_e32 v7, v117, v117
	v_fmac_f32_e32 v6, v118, v118
	v_fmac_f32_e32 v7, v119, v119
	v_fmac_f32_e32 v6, v120, v120
	v_fmac_f32_e32 v7, v121, v121
	v_add_f32_e32 v6, v6, v7
	s_nop 1
	v_add_f32_dpp v8, v6, v6 quad_perm:[1,0,3,2] row_mask:0xf bank_mask:0xf
	s_nop 1
	v_add_f32_dpp v8, v8, v8 quad_perm:[2,3,0,1] row_mask:0xf bank_mask:0xf
	s_nop 1
	v_add_f32_dpp v8, v8, v8 row_half_mirror row_mask:0xf bank_mask:0xf
	s_nop 1
	v_add_f32_dpp v8, v8, v8 row_mirror row_mask:0xf bank_mask:0xf
	s_nop 1
	v_add_f32_dpp v8, v8, v8 row_bcast:15 row_mask:0xa bank_mask:0xf
	s_nop 1
	v_add_f32_dpp v8, v8, v8 row_bcast:31 row_mask:0xc bank_mask:0xf
	s_nop 1
	v_readlane_b32 s84, v8, 63
	s_nop 1
	v_fma_f32 v4, s84, v2, v3
	v_rsq_f32_e32 v4, v4
	s_nop 0
	v_pk_mul_f32 v[34:35], v[106:107], v[4:5] op_sel_hi:[1,0]
	v_pk_mul_f32 v[36:37], v[108:109], v[4:5] op_sel_hi:[1,0]
	v_pk_mul_f32 v[38:39], v[110:111], v[4:5] op_sel_hi:[1,0]
	v_pk_mul_f32 v[40:41], v[112:113], v[4:5] op_sel_hi:[1,0]
	v_pk_mul_f32 v[42:43], v[114:115], v[4:5] op_sel_hi:[1,0]
	v_pk_mul_f32 v[44:45], v[116:117], v[4:5] op_sel_hi:[1,0]
	v_pk_mul_f32 v[46:47], v[118:119], v[4:5] op_sel_hi:[1,0]
	v_pk_mul_f32 v[48:49], v[120:121], v[4:5] op_sel_hi:[1,0]
	v_pk_mul_f32 v[34:35], v[34:35], v[192:193]
	v_pk_mul_f32 v[36:37], v[36:37], v[194:195]
	v_pk_mul_f32 v[38:39], v[38:39], v[196:197]
	v_pk_mul_f32 v[40:41], v[40:41], v[198:199]
	v_pk_mul_f32 v[42:43], v[42:43], v[200:201]
	v_pk_mul_f32 v[44:45], v[44:45], v[202:203]
	v_pk_mul_f32 v[46:47], v[46:47], v[204:205]
	v_pk_mul_f32 v[48:49], v[48:49], v[206:207]
	v_pk_fma_f32 v[34:35], v[34:35], v[208:209], v[228:229]
	v_pk_fma_f32 v[36:37], v[36:37], v[210:211], v[230:231]
	v_pk_fma_f32 v[38:39], v[38:39], v[212:213], v[232:233]
	v_pk_fma_f32 v[40:41], v[40:41], v[214:215], v[234:235]
	v_pk_fma_f32 v[42:43], v[42:43], v[220:221], v[236:237]
	v_pk_fma_f32 v[44:45], v[44:45], v[222:223], v[238:239]
	v_pk_fma_f32 v[46:47], v[46:47], v[224:225], v[26:27]
	v_pk_fma_f32 v[48:49], v[48:49], v[226:227], v[28:29]
	v_cvt_pk_bf16_f32 v50, v34, v35
	v_cvt_pk_bf16_f32 v51, v36, v37
	v_cvt_pk_bf16_f32 v52, v38, v39
	v_cvt_pk_bf16_f32 v53, v40, v41
	v_cvt_pk_bf16_f32 v54, v42, v43
	v_cvt_pk_bf16_f32 v55, v44, v45
	v_cvt_pk_bf16_f32 v56, v46, v47
	v_cvt_pk_bf16_f32 v57, v48, v49
	global_store_dwordx2 v1, v[50:51], s[16:17] offset:0
	global_store_dwordx2 v1, v[52:53], s[16:17] offset:512
	global_store_dwordx2 v1, v[54:55], s[16:17] offset:1024
	global_store_dwordx2 v1, v[56:57], s[16:17] offset:1536
	s_add_u32 s16, s16, 0x800
	s_addc_u32 s17, s17, 0
	global_load_dwordx4 v[106:109], v0, s[4:5] offset:0 nt
	global_load_dwordx4 v[110:113], v0, s[4:5] offset:1024 nt
	global_load_dwordx4 v[114:117], v0, s[4:5] offset:2048 nt
	global_load_dwordx4 v[118:121], v0, s[4:5] offset:3072 nt
	global_load_dwordx2 v[146:147], v1, s[12:13] offset:0 nt
	global_load_dwordx2 v[148:149], v1, s[12:13] offset:512 nt
	global_load_dwordx2 v[150:151], v1, s[12:13] offset:1024 nt
	global_load_dwordx2 v[152:153], v1, s[12:13] offset:1536 nt
	s_add_u32 s4, s4, 0x1000
	s_addc_u32 s5, s5, 0
	s_add_u32 s12, s12, 0x800
	s_addc_u32 s13, s13, 0
	s_waitcnt vmcnt(48)
; __device__ __forceinline__ unsigned cvt_pk_bf16(float lo, float hi) { unsigned r; asm volatile("v_cvt_pk_bf16_f32 %0, %1, %2" : "=v"(r) : "v"(lo), "v"(hi)); return r; }
; __device__ __forceinline__ float bflo(unsigned w) { return __uint_as_float(w << 16); }
; __device__ __forceinline__ float bfhi(unsigned w) { return __uint_as_float(w & 0xffff0000u); }
; template <bool BR, bool WH> ...
;     ...
;         if (BR) {
;             f32x4 m[4]; float s = 0.f;
; #pragma unroll
;             for (int j = 0; j < 4; ++j) { m[j] = (f32x4){bflo(bc[j].x), bfhi(bc[j].x), bflo(bc[j].y), bfhi(bc[j].y)};
;                 s += (m[j][0] * m[j][0] + m[j][1] * m[j][1]) + (m[j][2] * m[j][2] + m[j][3] * m[j][3]); }
;             const float rs = rsqrtf(wave_sum(s, lane) * (1.f / 1024.f) + EPS);
;             float* xo = row < ML ? xout_lat + (size_t)row * 1024 : xout_ctx + (size_t)(row - ML) * 1024;
; #pragma unroll
;             for (int j = 0; j < 4; ++j) { const f32x4 gp = *(const f32x4*)(g_post + 4 * lane + 256 * j), ga = *(const f32x4*)(mod_g + (size_t)mrow * 6144 + gate_off + 4 * lane + 256 * j);
;                 x[j] = x[j] + ga * ((m[j] * rs) * gp); __builtin_nontemporal_store(x[j], (f32x4*)(xo + 4 * lane + 256 * j)); }
;         }
;         if (WH) {
;             float s = 0.f;
; #pragma unroll
;             for (int j = 0; j < 4; ++j) s += (x[j][0] * x[j][0] + x[j][1] * x[j][1]) + (x[j][2] * x[j][2] + x[j][3] * x[j][3]);
;             const float rs = rsqrtf(wave_sum(s, lane) * (1.f / 1024.f) + EPS);
; #pragma unroll
;             for (int j = 0; j < 4; ++j) { const f32x4 gp = *(const f32x4*)(g_pre + 4 * lane + 256 * j), sc = *(const f32x4*)(mod_h + (size_t)mrow * 6144 + sc_off + 4 * lane + 256 * j),
;                     sh = *(const f32x4*)(mod_h + (size_t)mrow * 6144 + sh_off + 4 * lane + 256 * j);
;                 const f32x4 hv = ((x[j] * rs) * gp) * (sc + 1.0f) + sh;
;                 u32x2 w; w.x = cvt_pk_bf16(hv[0], hv[1]); w.y = cvt_pk_bf16(hv[2], hv[3]);
;                 *(u32x2*)(Hout + (size_t)row * 1024 + 4 * lane + 256 * j) = w; }
;         }
	v_lshlrev_b32_e32 v10, 16, v122
	v_and_b32_e32 v11, 0xffff0000, v122
	v_lshlrev_b32_e32 v12, 16, v123
	v_and_b32_e32 v13, 0xffff0000, v123
	v_lshlrev_b32_e32 v14, 16, v124
	v_and_b32_e32 v15, 0xffff0000, v124
	v_lshlrev_b32_e32 v16, 16, v125
	v_and_b32_e32 v17, 0xffff0000, v125
	v_lshlrev_b32_e32 v18, 16, v126
	v_and_b32_e32 v19, 0xffff0000, v126
	v_lshlrev_b32_e32 v20, 16, v127
	v_and_b32_e32 v21, 0xffff0000, v127
	v_lshlrev_b32_e32 v22, 16, v128
	v_and_b32_e32 v23, 0xffff0000, v128
	v_lshlrev_b32_e32 v24, 16, v129
	v_and_b32_e32 v25, 0xffff0000, v129
	v_mul_f32_e32 v6, v10, v10
	v_mul_f32_e32 v7, v11, v11
	v_fmac_f32_e32 v6, v12, v12
	v_fmac_f32_e32 v7, v13, v13
	v_fmac_f32_e32 v6, v14, v14
	v_fmac_f32_e32 v7, v15, v15
	v_fmac_f32_e32 v6, v16, v16
	v_fmac_f32_e32 v7, v17, v17
	v_fmac_f32_e32 v6, v18, v18
	v_fmac_f32_e32 v7, v19, v19
	v_fmac_f32_e32 v6, v20, v20
	v_fmac_f32_e32 v7, v21, v21
	v_fmac_f32_e32 v6, v22, v22
	v_fmac_f32_e32 v7, v23, v23
	v_fmac_f32_e32 v6, v24, v24
	v_fmac_f32_e32 v7, v25, v25
	v_add_f32_e32 v6, v6, v7
	s_nop 1
	v_add_f32_dpp v8, v6, v6 quad_perm:[1,0,3,2] row_mask:0xf bank_mask:0xf
	s_nop 1
	v_add_f32_dpp v8, v8, v8 quad_perm:[2,3,0,1] row_mask:0xf bank_mask:0xf
	s_nop 1
	v_add_f32_dpp v8, v8, v8 row_half_mirror row_mask:0xf bank_mask:0xf
	s_nop 1
	v_add_f32_dpp v8, v8, v8 row_mirror row_mask:0xf bank_mask:0xf
	s_nop 1
	v_add_f32_dpp v8, v8, v8 row_bcast:15 row_mask:0xa bank_mask:0xf
	s_nop 1
	v_add_f32_dpp v8, v8, v8 row_bcast:31 row_mask:0xc bank_mask:0xf
	s_nop 1
	v_readlane_b32 s84, v8, 63
	s_nop 1
	v_fma_f32 v4, s84, v2, v3
	v_rsq_f32_e32 v4, v4
	s_nop 0
	v_pk_mul_f32 v[34:35], v[10:11], v[4:5] op_sel_hi:[1,0]
	v_pk_mul_f32 v[36:37], v[12:13], v[4:5] op_sel_hi:[1,0]
	v_pk_mul_f32 v[38:39], v[14:15], v[4:5] op_sel_hi:[1,0]
	v_pk_mul_f32 v[40:41], v[16:17], v[4:5] op_sel_hi:[1,0]
	v_pk_mul_f32 v[42:43], v[18:19], v[4:5] op_sel_hi:[1,0]
	v_pk_mul_f32 v[44:45], v[20:21], v[4:5] op_sel_hi:[1,0]
	v_pk_mul_f32 v[46:47], v[22:23], v[4:5] op_sel_hi:[1,0]
	v_pk_mul_f32 v[48:49], v[24:25], v[4:5] op_sel_hi:[1,0]
	v_pk_mul_f32 v[34:35], v[34:35], v[154:155]
	v_pk_mul_f32 v[36:37], v[36:37], v[156:157]
	v_pk_mul_f32 v[38:39], v[38:39], v[158:159]
	v_pk_mul_f32 v[40:41], v[40:41], v[160:161]
	v_pk_mul_f32 v[42:43], v[42:43], v[162:163]
	v_pk_mul_f32 v[44:45], v[44:45], v[164:165]
	v_pk_mul_f32 v[46:47], v[46:47], v[166:167]
	v_pk_mul_f32 v[48:49], v[48:49], v[168:169]
	v_pk_fma_f32 v[58:59], v[176:177], v[34:35], v[58:59]
	v_pk_fma_f32 v[60:61], v[178:179], v[36:37], v[60:61]
	v_pk_fma_f32 v[62:63], v[180:181], v[38:39], v[62:63]
	v_pk_fma_f32 v[64:65], v[182:183], v[40:41], v[64:65]
	v_pk_fma_f32 v[66:67], v[184:185], v[42:43], v[66:67]
	v_pk_fma_f32 v[68:69], v[186:187], v[44:45], v[68:69]
	v_pk_fma_f32 v[70:71], v[188:189], v[46:47], v[70:71]
	v_pk_fma_f32 v[72:73], v[190:191], v[48:49], v[72:73]
	global_store_dwordx4 v0, v[58:61], s[14:15] offset:0 nt
	global_store_dwordx4 v0, v[62:65], s[14:15] offset:1024 nt
	global_store_dwordx4 v0, v[66:69], s[14:15] offset:2048 nt
	global_store_dwordx4 v0, v[70:73], s[14:15] offset:3072 nt
	s_add_u32 s14, s14, 0x1000
	s_addc_u32 s15, s15, 0
	v_mul_f32_e32 v6, v58, v58
	v_mul_f32_e32 v7, v59, v59
	v_fmac_f32_e32 v6, v60, v60
	v_fmac_f32_e32 v7, v61, v61
	v_fmac_f32_e32 v6, v62, v62
	v_fmac_f32_e32 v7, v63, v63
	v_fmac_f32_e32 v6, v64, v64
	v_fmac_f32_e32 v7, v65, v65
	v_fmac_f32_e32 v6, v66, v66
	v_fmac_f32_e32 v7, v67, v67
	v_fmac_f32_e32 v6, v68, v68
	v_fmac_f32_e32 v7, v69, v69
	v_fmac_f32_e32 v6, v70, v70
	v_fmac_f32_e32 v7, v71, v71
	v_fmac_f32_e32 v6, v72, v72
	v_fmac_f32_e32 v7, v73, v73
	v_add_f32_e32 v6, v6, v7
	s_nop 1
	v_add_f32_dpp v8, v6, v6 quad_perm:[1,0,3,2] row_mask:0xf bank_mask:0xf
	s_nop 1
	v_add_f32_dpp v8, v8, v8 quad_perm:[2,3,0,1] row_mask:0xf bank_mask:0xf
	s_nop 1
	v_add_f32_dpp v8, v8, v8 row_half_mirror row_mask:0xf bank_mask:0xf
	s_nop 1
	v_add_f32_dpp v8, v8, v8 row_mirror row_mask:0xf bank_mask:0xf
	s_nop 1
	v_add_f32_dpp v8, v8, v8 row_bcast:15 row_mask:0xa bank_mask:0xf
	s_nop 1
	v_add_f32_dpp v8, v8, v8 row_bcast:31 row_mask:0xc bank_mask:0xf
	s_nop 1
	v_readlane_b32 s84, v8, 63
	s_nop 1
	v_fma_f32 v4, s84, v2, v3
	v_rsq_f32_e32 v4, v4
	s_nop 0
	v_pk_mul_f32 v[34:35], v[58:59], v[4:5] op_sel_hi:[1,0]
	v_pk_mul_f32 v[36:37], v[60:61], v[4:5] op_sel_hi:[1,0]
	v_pk_mul_f32 v[38:39], v[62:63], v[4:5] op_sel_hi:[1,0]
	v_pk_mul_f32 v[40:41], v[64:65], v[4:5] op_sel_hi:[1,0]
	v_pk_mul_f32 v[42:43], v[66:67], v[4:5] op_sel_hi:[1,0]
	v_pk_mul_f32 v[44:45], v[68:69], v[4:5] op_sel_hi:[1,0]
	v_pk_mul_f32 v[46:47], v[70:71], v[4:5] op_sel_hi:[1,0]
	v_pk_mul_f32 v[48:49], v[72:73], v[4:5] op_sel_hi:[1,0]
	v_pk_mul_f32 v[34:35], v[34:35], v[192:193]
	v_pk_mul_f32 v[36:37], v[36:37], v[194:195]
	v_pk_mul_f32 v[38:39], v[38:39], v[196:197]
	v_pk_mul_f32 v[40:41], v[40:41], v[198:199]
	v_pk_mul_f32 v[42:43], v[42:43], v[200:201]
	v_pk_mul_f32 v[44:45], v[44:45], v[202:203]
	v_pk_mul_f32 v[46:47], v[46:47], v[204:205]
	v_pk_mul_f32 v[48:49], v[48:49], v[206:207]
	v_pk_fma_f32 v[34:35], v[34:35], v[208:209], v[228:229]
	v_pk_fma_f32 v[36:37], v[36:37], v[210:211], v[230:231]
	v_pk_fma_f32 v[38:39], v[38:39], v[212:213], v[232:233]
	v_pk_fma_f32 v[40:41], v[40:41], v[214:215], v[234:235]
	v_pk_fma_f32 v[42:43], v[42:43], v[220:221], v[236:237]
	v_pk_fma_f32 v[44:45], v[44:45], v[222:223], v[238:239]
	v_pk_fma_f32 v[46:47], v[46:47], v[224:225], v[26:27]
	v_pk_fma_f32 v[48:49], v[48:49], v[226:227], v[28:29]
	v_cvt_pk_bf16_f32 v50, v34, v35
	v_cvt_pk_bf16_f32 v51, v36, v37
	v_cvt_pk_bf16_f32 v52, v38, v39
	v_cvt_pk_bf16_f32 v53, v40, v41
	v_cvt_pk_bf16_f32 v54, v42, v43
	v_cvt_pk_bf16_f32 v55, v44, v45
	v_cvt_pk_bf16_f32 v56, v46, v47
	v_cvt_pk_bf16_f32 v57, v48, v49
	global_store_dwordx2 v1, v[50:51], s[16:17] offset:0
	global_store_dwordx2 v1, v[52:53], s[16:17] offset:512
	global_store_dwordx2 v1, v[54:55], s[16:17] offset:1024
	global_store_dwordx2 v1, v[56:57], s[16:17] offset:1536
	s_add_u32 s16, s16, 0x800
	s_addc_u32 s17, s17, 0
	s_waitcnt vmcnt(40)
; __device__ __forceinline__ unsigned cvt_pk_bf16(float lo, float hi) { unsigned r; asm volatile("v_cvt_pk_bf16_f32 %0, %1, %2" : "=v"(r) : "v"(lo), "v"(hi)); return r; }
; __device__ __forceinline__ float bflo(unsigned w) { return __uint_as_float(w << 16); }
; __device__ __forceinline__ float bfhi(unsigned w) { return __uint_as_float(w & 0xffff0000u); }
; template <bool BR, bool WH> ...
;     ...
;         if (BR) {
;             f32x4 m[4]; float s = 0.f;
; #pragma unroll
;             for (int j = 0; j < 4; ++j) { m[j] = (f32x4){bflo(bc[j].x), bfhi(bc[j].x), bflo(bc[j].y), bfhi(bc[j].y)};
;                 s += (m[j][0] * m[j][0] + m[j][1] * m[j][1]) + (m[j][2] * m[j][2] + m[j][3] * m[j][3]); }
;             const float rs = rsqrtf(wave_sum(s, lane) * (1.f / 1024.f) + EPS);
;             float* xo = row < ML ? xout_lat + (size_t)row * 1024 : xout_ctx + (size_t)(row - ML) * 1024;
; #pragma unroll
;             for (int j = 0; j < 4; ++j) { const f32x4 gp = *(const f32x4*)(g_post + 4 * lane + 256 * j), ga = *(const f32x4*)(mod_g + (size_t)mrow * 6144 + gate_off + 4 * lane + 256 * j);
;                 x[j] = x[j] + ga * ((m[j] * rs) * gp); __builtin_nontemporal_store(x[j], (f32x4*)(xo + 4 * lane + 256 * j)); }
;         }
;         if (WH) {
;             float s = 0.f;
; #pragma unroll
;             for (int j = 0; j < 4; ++j) s += (x[j][0] * x[j][0] + x[j][1] * x[j][1]) + (x[j][2] * x[j][2] + x[j][3] * x[j][3]);
;             const float rs = rsqrtf(wave_sum(s, lane) * (1.f / 1024.f) + EPS);
; #pragma unroll
;             for (int j = 0; j < 4; ++j) { const f32x4 gp = *(const f32x4*)(g_pre + 4 * lane + 256 * j), sc = *(const f32x4*)(mod_h + (size_t)mrow * 6144 + sc_off + 4 * lane + 256 * j),
;                     sh = *(const f32x4*)(mod_h + (size_t)mrow * 6144 + sh_off + 4 * lane + 256 * j);
;                 const f32x4 hv = ((x[j] * rs) * gp) * (sc + 1.0f) + sh;
;                 u32x2 w; w.x = cvt_pk_bf16(hv[0], hv[1]); w.y = cvt_pk_bf16(hv[2], hv[3]);
;                 *(u32x2*)(Hout + (size_t)row * 1024 + 4 * lane + 256 * j) = w; }
;         }
	v_lshlrev_b32_e32 v10, 16, v130
	v_and_b32_e32 v11, 0xffff0000, v130
	v_lshlrev_b32_e32 v12, 16, v131
	v_and_b32_e32 v13, 0xffff0000, v131
	v_lshlrev_b32_e32 v14, 16, v132
	v_and_b32_e32 v15, 0xffff0000, v132
	v_lshlrev_b32_e32 v16, 16, v133
	v_and_b32_e32 v17, 0xffff0000, v133
	v_lshlrev_b32_e32 v18, 16, v134
	v_and_b32_e32 v19, 0xffff0000, v134
	v_lshlrev_b32_e32 v20, 16, v135
	v_and_b32_e32 v21, 0xffff0000, v135
	v_lshlrev_b32_e32 v22, 16, v136
	v_and_b32_e32 v23, 0xffff0000, v136
	v_lshlrev_b32_e32 v24, 16, v137
	v_and_b32_e32 v25, 0xffff0000, v137
	v_mul_f32_e32 v6, v10, v10
	v_mul_f32_e32 v7, v11, v11
	v_fmac_f32_e32 v6, v12, v12
	v_fmac_f32_e32 v7, v13, v13
	v_fmac_f32_e32 v6, v14, v14
	v_fmac_f32_e32 v7, v15, v15
	v_fmac_f32_e32 v6, v16, v16
	v_fmac_f32_e32 v7, v17, v17
	v_fmac_f32_e32 v6, v18, v18
	v_fmac_f32_e32 v7, v19, v19
	v_fmac_f32_e32 v6, v20, v20
	v_fmac_f32_e32 v7, v21, v21
	v_fmac_f32_e32 v6, v22, v22
	v_fmac_f32_e32 v7, v23, v23
	v_fmac_f32_e32 v6, v24, v24
	v_fmac_f32_e32 v7, v25, v25
	v_add_f32_e32 v6, v6, v7
	s_nop 1
	v_add_f32_dpp v8, v6, v6 quad_perm:[1,0,3,2] row_mask:0xf bank_mask:0xf
	s_nop 1
	v_add_f32_dpp v8, v8, v8 quad_perm:[2,3,0,1] row_mask:0xf bank_mask:0xf
	s_nop 1
	v_add_f32_dpp v8, v8, v8 row_half_mirror row_mask:0xf bank_mask:0xf
	s_nop 1
	v_add_f32_dpp v8, v8, v8 row_mirror row_mask:0xf bank_mask:0xf
	s_nop 1
	v_add_f32_dpp v8, v8, v8 row_bcast:15 row_mask:0xa bank_mask:0xf
	s_nop 1
	v_add_f32_dpp v8, v8, v8 row_bcast:31 row_mask:0xc bank_mask:0xf
	s_nop 1
	v_readlane_b32 s84, v8, 63
	s_nop 1
	v_fma_f32 v4, s84, v2, v3
	v_rsq_f32_e32 v4, v4
	s_nop 0
	v_pk_mul_f32 v[34:35], v[10:11], v[4:5] op_sel_hi:[1,0]
	v_pk_mul_f32 v[36:37], v[12:13], v[4:5] op_sel_hi:[1,0]
	v_pk_mul_f32 v[38:39], v[14:15], v[4:5] op_sel_hi:[1,0]
	v_pk_mul_f32 v[40:41], v[16:17], v[4:5] op_sel_hi:[1,0]
	v_pk_mul_f32 v[42:43], v[18:19], v[4:5] op_sel_hi:[1,0]
	v_pk_mul_f32 v[44:45], v[20:21], v[4:5] op_sel_hi:[1,0]
	v_pk_mul_f32 v[46:47], v[22:23], v[4:5] op_sel_hi:[1,0]
	v_pk_mul_f32 v[48:49], v[24:25], v[4:5] op_sel_hi:[1,0]
	v_pk_mul_f32 v[34:35], v[34:35], v[154:155]
	v_pk_mul_f32 v[36:37], v[36:37], v[156:157]
	v_pk_mul_f32 v[38:39], v[38:39], v[158:159]
	v_pk_mul_f32 v[40:41], v[40:41], v[160:161]
	v_pk_mul_f32 v[42:43], v[42:43], v[162:163]
	v_pk_mul_f32 v[44:45], v[44:45], v[164:165]
	v_pk_mul_f32 v[46:47], v[46:47], v[166:167]
	v_pk_mul_f32 v[48:49], v[48:49], v[168:169]
	v_pk_fma_f32 v[74:75], v[176:177], v[34:35], v[74:75]
	v_pk_fma_f32 v[76:77], v[178:179], v[36:37], v[76:77]
	v_pk_fma_f32 v[78:79], v[180:181], v[38:39], v[78:79]
	v_pk_fma_f32 v[80:81], v[182:183], v[40:41], v[80:81]
	v_pk_fma_f32 v[82:83], v[184:185], v[42:43], v[82:83]
	v_pk_fma_f32 v[84:85], v[186:187], v[44:45], v[84:85]
	v_pk_fma_f32 v[86:87], v[188:189], v[46:47], v[86:87]
	v_pk_fma_f32 v[88:89], v[190:191], v[48:49], v[88:89]
	global_store_dwordx4 v0, v[74:77], s[14:15] offset:0 nt
	global_store_dwordx4 v0, v[78:81], s[14:15] offset:1024 nt
	global_store_dwordx4 v0, v[82:85], s[14:15] offset:2048 nt
	global_store_dwordx4 v0, v[86:89], s[14:15] offset:3072 nt
	s_add_u32 s14, s14, 0x1000
	s_addc_u32 s15, s15, 0
	v_mul_f32_e32 v6, v74, v74
	v_mul_f32_e32 v7, v75, v75
	v_fmac_f32_e32 v6, v76, v76
	v_fmac_f32_e32 v7, v77, v77
	v_fmac_f32_e32 v6, v78, v78
	v_fmac_f32_e32 v7, v79, v79
	v_fmac_f32_e32 v6, v80, v80
	v_fmac_f32_e32 v7, v81, v81
	v_fmac_f32_e32 v6, v82, v82
	v_fmac_f32_e32 v7, v83, v83
	v_fmac_f32_e32 v6, v84, v84
	v_fmac_f32_e32 v7, v85, v85
	v_fmac_f32_e32 v6, v86, v86
	v_fmac_f32_e32 v7, v87, v87
	v_fmac_f32_e32 v6, v88, v88
	v_fmac_f32_e32 v7, v89, v89
	v_add_f32_e32 v6, v6, v7
	s_nop 1
	v_add_f32_dpp v8, v6, v6 quad_perm:[1,0,3,2] row_mask:0xf bank_mask:0xf
	s_nop 1
	v_add_f32_dpp v8, v8, v8 quad_perm:[2,3,0,1] row_mask:0xf bank_mask:0xf
	s_nop 1
	v_add_f32_dpp v8, v8, v8 row_half_mirror row_mask:0xf bank_mask:0xf
	s_nop 1
	v_add_f32_dpp v8, v8, v8 row_mirror row_mask:0xf bank_mask:0xf
	s_nop 1
	v_add_f32_dpp v8, v8, v8 row_bcast:15 row_mask:0xa bank_mask:0xf
	s_nop 1
	v_add_f32_dpp v8, v8, v8 row_bcast:31 row_mask:0xc bank_mask:0xf
	s_nop 1
	v_readlane_b32 s84, v8, 63
	s_nop 1
	v_fma_f32 v4, s84, v2, v3
	v_rsq_f32_e32 v4, v4
	s_nop 0
	v_pk_mul_f32 v[34:35], v[74:75], v[4:5] op_sel_hi:[1,0]
	v_pk_mul_f32 v[36:37], v[76:77], v[4:5] op_sel_hi:[1,0]
	v_pk_mul_f32 v[38:39], v[78:79], v[4:5] op_sel_hi:[1,0]
	v_pk_mul_f32 v[40:41], v[80:81], v[4:5] op_sel_hi:[1,0]
	v_pk_mul_f32 v[42:43], v[82:83], v[4:5] op_sel_hi:[1,0]
	v_pk_mul_f32 v[44:45], v[84:85], v[4:5] op_sel_hi:[1,0]
	v_pk_mul_f32 v[46:47], v[86:87], v[4:5] op_sel_hi:[1,0]
	v_pk_mul_f32 v[48:49], v[88:89], v[4:5] op_sel_hi:[1,0]
	v_pk_mul_f32 v[34:35], v[34:35], v[192:193]
	v_pk_mul_f32 v[36:37], v[36:37], v[194:195]
	v_pk_mul_f32 v[38:39], v[38:39], v[196:197]
	v_pk_mul_f32 v[40:41], v[40:41], v[198:199]
	v_pk_mul_f32 v[42:43], v[42:43], v[200:201]
	v_pk_mul_f32 v[44:45], v[44:45], v[202:203]
	v_pk_mul_f32 v[46:47], v[46:47], v[204:205]
	v_pk_mul_f32 v[48:49], v[48:49], v[206:207]
	v_pk_fma_f32 v[34:35], v[34:35], v[208:209], v[228:229]
	v_pk_fma_f32 v[36:37], v[36:37], v[210:211], v[230:231]
	v_pk_fma_f32 v[38:39], v[38:39], v[212:213], v[232:233]
	v_pk_fma_f32 v[40:41], v[40:41], v[214:215], v[234:235]
	v_pk_fma_f32 v[42:43], v[42:43], v[220:221], v[236:237]
	v_pk_fma_f32 v[44:45], v[44:45], v[222:223], v[238:239]
	v_pk_fma_f32 v[46:47], v[46:47], v[224:225], v[26:27]
	v_pk_fma_f32 v[48:49], v[48:49], v[226:227], v[28:29]
	v_cvt_pk_bf16_f32 v50, v34, v35
	v_cvt_pk_bf16_f32 v51, v36, v37
	v_cvt_pk_bf16_f32 v52, v38, v39
	v_cvt_pk_bf16_f32 v53, v40, v41
	v_cvt_pk_bf16_f32 v54, v42, v43
	v_cvt_pk_bf16_f32 v55, v44, v45
	v_cvt_pk_bf16_f32 v56, v46, v47
	v_cvt_pk_bf16_f32 v57, v48, v49
	global_store_dwordx2 v1, v[50:51], s[16:17] offset:0
	global_store_dwordx2 v1, v[52:53], s[16:17] offset:512
	global_store_dwordx2 v1, v[54:55], s[16:17] offset:1024
	global_store_dwordx2 v1, v[56:57], s[16:17] offset:1536
	s_add_u32 s16, s16, 0x800
	s_addc_u32 s17, s17, 0
	s_waitcnt vmcnt(32)
; __device__ __forceinline__ unsigned cvt_pk_bf16(float lo, float hi) { unsigned r; asm volatile("v_cvt_pk_bf16_f32 %0, %1, %2" : "=v"(r) : "v"(lo), "v"(hi)); return r; }
; __device__ __forceinline__ float bflo(unsigned w) { return __uint_as_float(w << 16); }
; __device__ __forceinline__ float bfhi(unsigned w) { return __uint_as_float(w & 0xffff0000u); }
; template <bool BR, bool WH> ...
;     ...
;         if (BR) {
;             f32x4 m[4]; float s = 0.f;
; #pragma unroll
;             for (int j = 0; j < 4; ++j) { m[j] = (f32x4){bflo(bc[j].x), bfhi(bc[j].x), bflo(bc[j].y), bfhi(bc[j].y)};
;                 s += (m[j][0] * m[j][0] + m[j][1] * m[j][1]) + (m[j][2] * m[j][2] + m[j][3] * m[j][3]); }
;             const float rs = rsqrtf(wave_sum(s, lane) * (1.f / 1024.f) + EPS);
;             float* xo = row < ML ? xout_lat + (size_t)row * 1024 : xout_ctx + (size_t)(row - ML) * 1024;
; #pragma unroll
;             for (int j = 0; j < 4; ++j) { const f32x4 gp = *(const f32x4*)(g_post + 4 * lane + 256 * j), ga = *(const f32x4*)(mod_g + (size_t)mrow * 6144 + gate_off + 4 * lane + 256 * j);
;                 x[j] = x[j] + ga * ((m[j] * rs) * gp); __builtin_nontemporal_store(x[j], (f32x4*)(xo + 4 * lane + 256 * j)); }
;         }
;         if (WH) {
;             float s = 0.f;
; #pragma unroll
;             for (int j = 0; j < 4; ++j) s += (x[j][0] * x[j][0] + x[j][1] * x[j][1]) + (x[j][2] * x[j][2] + x[j][3] * x[j][3]);
;             const float rs = rsqrtf(wave_sum(s, lane) * (1.f / 1024.f) + EPS);
; #pragma unroll
;             for (int j = 0; j < 4; ++j) { const f32x4 gp = *(const f32x4*)(g_pre + 4 * lane + 256 * j), sc = *(const f32x4*)(mod_h + (size_t)mrow * 6144 + sc_off + 4 * lane + 256 * j),
;                     sh = *(const f32x4*)(mod_h + (size_t)mrow * 6144 + sh_off + 4 * lane + 256 * j);
;                 const f32x4 hv = ((x[j] * rs) * gp) * (sc + 1.0f) + sh;
;                 u32x2 w; w.x = cvt_pk_bf16(hv[0], hv[1]); w.y = cvt_pk_bf16(hv[2], hv[3]);
;                 *(u32x2*)(Hout + (size_t)row * 1024 + 4 * lane + 256 * j) = w; }
;         }
	v_lshlrev_b32_e32 v10, 16, v138
	v_and_b32_e32 v11, 0xffff0000, v138
	v_lshlrev_b32_e32 v12, 16, v139
	v_and_b32_e32 v13, 0xffff0000, v139
	v_lshlrev_b32_e32 v14, 16, v140
	v_and_b32_e32 v15, 0xffff0000, v140
	v_lshlrev_b32_e32 v16, 16, v141
	v_and_b32_e32 v17, 0xffff0000, v141
	v_lshlrev_b32_e32 v18, 16, v142
	v_and_b32_e32 v19, 0xffff0000, v142
	v_lshlrev_b32_e32 v20, 16, v143
	v_and_b32_e32 v21, 0xffff0000, v143
	v_lshlrev_b32_e32 v22, 16, v144
	v_and_b32_e32 v23, 0xffff0000, v144
	v_lshlrev_b32_e32 v24, 16, v145
	v_and_b32_e32 v25, 0xffff0000, v145
	v_mul_f32_e32 v6, v10, v10
	v_mul_f32_e32 v7, v11, v11
	v_fmac_f32_e32 v6, v12, v12
	v_fmac_f32_e32 v7, v13, v13
	v_fmac_f32_e32 v6, v14, v14
	v_fmac_f32_e32 v7, v15, v15
	v_fmac_f32_e32 v6, v16, v16
	v_fmac_f32_e32 v7, v17, v17
	v_fmac_f32_e32 v6, v18, v18
	v_fmac_f32_e32 v7, v19, v19
	v_fmac_f32_e32 v6, v20, v20
	v_fmac_f32_e32 v7, v21, v21
	v_fmac_f32_e32 v6, v22, v22
	v_fmac_f32_e32 v7, v23, v23
	v_fmac_f32_e32 v6, v24, v24
	v_fmac_f32_e32 v7, v25, v25
	v_add_f32_e32 v6, v6, v7
	s_nop 1
	v_add_f32_dpp v8, v6, v6 quad_perm:[1,0,3,2] row_mask:0xf bank_mask:0xf
	s_nop 1
	v_add_f32_dpp v8, v8, v8 quad_perm:[2,3,0,1] row_mask:0xf bank_mask:0xf
	s_nop 1
	v_add_f32_dpp v8, v8, v8 row_half_mirror row_mask:0xf bank_mask:0xf
	s_nop 1
	v_add_f32_dpp v8, v8, v8 row_mirror row_mask:0xf bank_mask:0xf
	s_nop 1
	v_add_f32_dpp v8, v8, v8 row_bcast:15 row_mask:0xa bank_mask:0xf
	s_nop 1
	v_add_f32_dpp v8, v8, v8 row_bcast:31 row_mask:0xc bank_mask:0xf
	s_nop 1
	v_readlane_b32 s84, v8, 63
	s_nop 1
	v_fma_f32 v4, s84, v2, v3
	v_rsq_f32_e32 v4, v4
	s_nop 0
	v_pk_mul_f32 v[34:35], v[10:11], v[4:5] op_sel_hi:[1,0]
	v_pk_mul_f32 v[36:37], v[12:13], v[4:5] op_sel_hi:[1,0]
	v_pk_mul_f32 v[38:39], v[14:15], v[4:5] op_sel_hi:[1,0]
	v_pk_mul_f32 v[40:41], v[16:17], v[4:5] op_sel_hi:[1,0]
	v_pk_mul_f32 v[42:43], v[18:19], v[4:5] op_sel_hi:[1,0]
	v_pk_mul_f32 v[44:45], v[20:21], v[4:5] op_sel_hi:[1,0]
	v_pk_mul_f32 v[46:47], v[22:23], v[4:5] op_sel_hi:[1,0]
	v_pk_mul_f32 v[48:49], v[24:25], v[4:5] op_sel_hi:[1,0]
	v_pk_mul_f32 v[34:35], v[34:35], v[154:155]
	v_pk_mul_f32 v[36:37], v[36:37], v[156:157]
	v_pk_mul_f32 v[38:39], v[38:39], v[158:159]
	v_pk_mul_f32 v[40:41], v[40:41], v[160:161]
	v_pk_mul_f32 v[42:43], v[42:43], v[162:163]
	v_pk_mul_f32 v[44:45], v[44:45], v[164:165]
	v_pk_mul_f32 v[46:47], v[46:47], v[166:167]
	v_pk_mul_f32 v[48:49], v[48:49], v[168:169]
	v_pk_fma_f32 v[90:91], v[176:177], v[34:35], v[90:91]
	v_pk_fma_f32 v[92:93], v[178:179], v[36:37], v[92:93]
	v_pk_fma_f32 v[94:95], v[180:181], v[38:39], v[94:95]
	v_pk_fma_f32 v[96:97], v[182:183], v[40:41], v[96:97]
	v_pk_fma_f32 v[98:99], v[184:185], v[42:43], v[98:99]
	v_pk_fma_f32 v[100:101], v[186:187], v[44:45], v[100:101]
	v_pk_fma_f32 v[102:103], v[188:189], v[46:47], v[102:103]
	v_pk_fma_f32 v[104:105], v[190:191], v[48:49], v[104:105]
	global_store_dwordx4 v0, v[90:93], s[14:15] offset:0 nt
	global_store_dwordx4 v0, v[94:97], s[14:15] offset:1024 nt
	global_store_dwordx4 v0, v[98:101], s[14:15] offset:2048 nt
	global_store_dwordx4 v0, v[102:105], s[14:15] offset:3072 nt
	s_add_u32 s14, s14, 0x1000
	s_addc_u32 s15, s15, 0
	v_mul_f32_e32 v6, v90, v90
	v_mul_f32_e32 v7, v91, v91
	v_fmac_f32_e32 v6, v92, v92
	v_fmac_f32_e32 v7, v93, v93
	v_fmac_f32_e32 v6, v94, v94
	v_fmac_f32_e32 v7, v95, v95
	v_fmac_f32_e32 v6, v96, v96
	v_fmac_f32_e32 v7, v97, v97
	v_fmac_f32_e32 v6, v98, v98
	v_fmac_f32_e32 v7, v99, v99
	v_fmac_f32_e32 v6, v100, v100
	v_fmac_f32_e32 v7, v101, v101
	v_fmac_f32_e32 v6, v102, v102
	v_fmac_f32_e32 v7, v103, v103
	v_fmac_f32_e32 v6, v104, v104
	v_fmac_f32_e32 v7, v105, v105
	v_add_f32_e32 v6, v6, v7
	s_nop 1
	v_add_f32_dpp v8, v6, v6 quad_perm:[1,0,3,2] row_mask:0xf bank_mask:0xf
	s_nop 1
	v_add_f32_dpp v8, v8, v8 quad_perm:[2,3,0,1] row_mask:0xf bank_mask:0xf
	s_nop 1
	v_add_f32_dpp v8, v8, v8 row_half_mirror row_mask:0xf bank_mask:0xf
	s_nop 1
	v_add_f32_dpp v8, v8, v8 row_mirror row_mask:0xf bank_mask:0xf
	s_nop 1
	v_add_f32_dpp v8, v8, v8 row_bcast:15 row_mask:0xa bank_mask:0xf
	s_nop 1
	v_add_f32_dpp v8, v8, v8 row_bcast:31 row_mask:0xc bank_mask:0xf
	s_nop 1
	v_readlane_b32 s84, v8, 63
	s_nop 1
	v_fma_f32 v4, s84, v2, v3
	v_rsq_f32_e32 v4, v4
	s_nop 0
	v_pk_mul_f32 v[34:35], v[90:91], v[4:5] op_sel_hi:[1,0]
	v_pk_mul_f32 v[36:37], v[92:93], v[4:5] op_sel_hi:[1,0]
	v_pk_mul_f32 v[38:39], v[94:95], v[4:5] op_sel_hi:[1,0]
	v_pk_mul_f32 v[40:41], v[96:97], v[4:5] op_sel_hi:[1,0]
	v_pk_mul_f32 v[42:43], v[98:99], v[4:5] op_sel_hi:[1,0]
	v_pk_mul_f32 v[44:45], v[100:101], v[4:5] op_sel_hi:[1,0]
	v_pk_mul_f32 v[46:47], v[102:103], v[4:5] op_sel_hi:[1,0]
	v_pk_mul_f32 v[48:49], v[104:105], v[4:5] op_sel_hi:[1,0]
	v_pk_mul_f32 v[34:35], v[34:35], v[192:193]
	v_pk_mul_f32 v[36:37], v[36:37], v[194:195]
	v_pk_mul_f32 v[38:39], v[38:39], v[196:197]
	v_pk_mul_f32 v[40:41], v[40:41], v[198:199]
	v_pk_mul_f32 v[42:43], v[42:43], v[200:201]
	v_pk_mul_f32 v[44:45], v[44:45], v[202:203]
	v_pk_mul_f32 v[46:47], v[46:47], v[204:205]
	v_pk_mul_f32 v[48:49], v[48:49], v[206:207]
	v_pk_fma_f32 v[34:35], v[34:35], v[208:209], v[228:229]
	v_pk_fma_f32 v[36:37], v[36:37], v[210:211], v[230:231]
	v_pk_fma_f32 v[38:39], v[38:39], v[212:213], v[232:233]
	v_pk_fma_f32 v[40:41], v[40:41], v[214:215], v[234:235]
	v_pk_fma_f32 v[42:43], v[42:43], v[220:221], v[236:237]
	v_pk_fma_f32 v[44:45], v[44:45], v[222:223], v[238:239]
	v_pk_fma_f32 v[46:47], v[46:47], v[224:225], v[26:27]
	v_pk_fma_f32 v[48:49], v[48:49], v[226:227], v[28:29]
	v_cvt_pk_bf16_f32 v50, v34, v35
	v_cvt_pk_bf16_f32 v51, v36, v37
	v_cvt_pk_bf16_f32 v52, v38, v39
	v_cvt_pk_bf16_f32 v53, v40, v41
	v_cvt_pk_bf16_f32 v54, v42, v43
	v_cvt_pk_bf16_f32 v55, v44, v45
	v_cvt_pk_bf16_f32 v56, v46, v47
	v_cvt_pk_bf16_f32 v57, v48, v49
	global_store_dwordx2 v1, v[50:51], s[16:17] offset:0
	global_store_dwordx2 v1, v[52:53], s[16:17] offset:512
	global_store_dwordx2 v1, v[54:55], s[16:17] offset:1024
	global_store_dwordx2 v1, v[56:57], s[16:17] offset:1536
	s_add_u32 s16, s16, 0x800
	s_addc_u32 s17, s17, 0
	s_waitcnt vmcnt(24)
; __device__ __forceinline__ unsigned cvt_pk_bf16(float lo, float hi) { unsigned r; asm volatile("v_cvt_pk_bf16_f32 %0, %1, %2" : "=v"(r) : "v"(lo), "v"(hi)); return r; }
; __device__ __forceinline__ float bflo(unsigned w) { return __uint_as_float(w << 16); }
; __device__ __forceinline__ float bfhi(unsigned w) { return __uint_as_float(w & 0xffff0000u); }
; template <bool BR, bool WH> ...
;     ...
;         if (BR) {
;             f32x4 m[4]; float s = 0.f;
; #pragma unroll
;             for (int j = 0; j < 4; ++j) { m[j] = (f32x4){bflo(bc[j].x), bfhi(bc[j].x), bflo(bc[j].y), bfhi(bc[j].y)};
;                 s += (m[j][0] * m[j][0] + m[j][1] * m[j][1]) + (m[j][2] * m[j][2] + m[j][3] * m[j][3]); }
;             const float rs = rsqrtf(wave_sum(s, lane) * (1.f / 1024.f) + EPS);
;             float* xo = row < ML ? xout_lat + (size_t)row * 1024 : xout_ctx + (size_t)(row - ML) * 1024;
; #pragma unroll
;             for (int j = 0; j < 4; ++j) { const f32x4 gp = *(const f32x4*)(g_post + 4 * lane + 256 * j), ga = *(const f32x4*)(mod_g + (size_t)mrow * 6144 + gate_off + 4 * lane + 256 * j);
;                 x[j] = x[j] + ga * ((m[j] * rs) * gp); __builtin_nontemporal_store(x[j], (f32x4*)(xo + 4 * lane + 256 * j)); }
;         }
;         if (WH) {
;             float s = 0.f;
; #pragma unroll
;             for (int j = 0; j < 4; ++j) s += (x[j][0] * x[j][0] + x[j][1] * x[j][1]) + (x[j][2] * x[j][2] + x[j][3] * x[j][3]);
;             const float rs = rsqrtf(wave_sum(s, lane) * (1.f / 1024.f) + EPS);
; #pragma unroll
;             for (int j = 0; j < 4; ++j) { const f32x4 gp = *(const f32x4*)(g_pre + 4 * lane + 256 * j), sc = *(const f32x4*)(mod_h + (size_t)mrow * 6144 + sc_off + 4 * lane + 256 * j),
;                     sh = *(const f32x4*)(mod_h + (size_t)mrow * 6144 + sh_off + 4 * lane + 256 * j);
;                 const f32x4 hv = ((x[j] * rs) * gp) * (sc + 1.0f) + sh;
;                 u32x2 w; w.x = cvt_pk_bf16(hv[0], hv[1]); w.y = cvt_pk_bf16(hv[2], hv[3]);
;                 *(u32x2*)(Hout + (size_t)row * 1024 + 4 * lane + 256 * j) = w; }
;         }
;         if (!hn) break;
; #pragma unroll
;         for (int j = 0; j < 4; ++j) { xc[j] = xn[j]; bc[j] = bn[j]; }
	v_lshlrev_b32_e32 v10, 16, v146
	v_and_b32_e32 v11, 0xffff0000, v146
	v_lshlrev_b32_e32 v12, 16, v147
	v_and_b32_e32 v13, 0xffff0000, v147
	v_lshlrev_b32_e32 v14, 16, v148
	v_and_b32_e32 v15, 0xffff0000, v148
	v_lshlrev_b32_e32 v16, 16, v149
	v_and_b32_e32 v17, 0xffff0000, v149
	v_lshlrev_b32_e32 v18, 16, v150
	v_and_b32_e32 v19, 0xffff0000, v150
	v_lshlrev_b32_e32 v20, 16, v151
	v_and_b32_e32 v21, 0xffff0000, v151
	v_lshlrev_b32_e32 v22, 16, v152
	v_and_b32_e32 v23, 0xffff0000, v152
	v_lshlrev_b32_e32 v24, 16, v153
	v_and_b32_e32 v25, 0xffff0000, v153
	v_mul_f32_e32 v6, v10, v10
	v_mul_f32_e32 v7, v11, v11
	v_fmac_f32_e32 v6, v12, v12
	v_fmac_f32_e32 v7, v13, v13
	v_fmac_f32_e32 v6, v14, v14
	v_fmac_f32_e32 v7, v15, v15
	v_fmac_f32_e32 v6, v16, v16
	v_fmac_f32_e32 v7, v17, v17
	v_fmac_f32_e32 v6, v18, v18
	v_fmac_f32_e32 v7, v19, v19
	v_fmac_f32_e32 v6, v20, v20
	v_fmac_f32_e32 v7, v21, v21
	v_fmac_f32_e32 v6, v22, v22
	v_fmac_f32_e32 v7, v23, v23
	v_fmac_f32_e32 v6, v24, v24
	v_fmac_f32_e32 v7, v25, v25
	v_add_f32_e32 v6, v6, v7
	s_nop 1
	v_add_f32_dpp v8, v6, v6 quad_perm:[1,0,3,2] row_mask:0xf bank_mask:0xf
	s_nop 1
	v_add_f32_dpp v8, v8, v8 quad_perm:[2,3,0,1] row_mask:0xf bank_mask:0xf
	s_nop 1
	v_add_f32_dpp v8, v8, v8 row_half_mirror row_mask:0xf bank_mask:0xf
	s_nop 1
	v_add_f32_dpp v8, v8, v8 row_mirror row_mask:0xf bank_mask:0xf
	s_nop 1
	v_add_f32_dpp v8, v8, v8 row_bcast:15 row_mask:0xa bank_mask:0xf
	s_nop 1
	v_add_f32_dpp v8, v8, v8 row_bcast:31 row_mask:0xc bank_mask:0xf
	s_nop 1
	v_readlane_b32 s84, v8, 63
	s_nop 1
	v_fma_f32 v4, s84, v2, v3
	v_rsq_f32_e32 v4, v4
	s_nop 0
	v_pk_mul_f32 v[34:35], v[10:11], v[4:5] op_sel_hi:[1,0]
	v_pk_mul_f32 v[36:37], v[12:13], v[4:5] op_sel_hi:[1,0]
	v_pk_mul_f32 v[38:39], v[14:15], v[4:5] op_sel_hi:[1,0]
	v_pk_mul_f32 v[40:41], v[16:17], v[4:5] op_sel_hi:[1,0]
	v_pk_mul_f32 v[42:43], v[18:19], v[4:5] op_sel_hi:[1,0]
	v_pk_mul_f32 v[44:45], v[20:21], v[4:5] op_sel_hi:[1,0]
	v_pk_mul_f32 v[46:47], v[22:23], v[4:5] op_sel_hi:[1,0]
	v_pk_mul_f32 v[48:49], v[24:25], v[4:5] op_sel_hi:[1,0]
	v_pk_mul_f32 v[34:35], v[34:35], v[154:155]
	v_pk_mul_f32 v[36:37], v[36:37], v[156:157]
	v_pk_mul_f32 v[38:39], v[38:39], v[158:159]
	v_pk_mul_f32 v[40:41], v[40:41], v[160:161]
	v_pk_mul_f32 v[42:43], v[42:43], v[162:163]
	v_pk_mul_f32 v[44:45], v[44:45], v[164:165]
	v_pk_mul_f32 v[46:47], v[46:47], v[166:167]
	v_pk_mul_f32 v[48:49], v[48:49], v[168:169]
	v_pk_fma_f32 v[106:107], v[176:177], v[34:35], v[106:107]
	v_pk_fma_f32 v[108:109], v[178:179], v[36:37], v[108:109]
	v_pk_fma_f32 v[110:111], v[180:181], v[38:39], v[110:111]
	v_pk_fma_f32 v[112:113], v[182:183], v[40:41], v[112:113]
	v_pk_fma_f32 v[114:115], v[184:185], v[42:43], v[114:115]
	v_pk_fma_f32 v[116:117], v[186:187], v[44:45], v[116:117]
	v_pk_fma_f32 v[118:119], v[188:189], v[46:47], v[118:119]
	v_pk_fma_f32 v[120:121], v[190:191], v[48:49], v[120:121]
	global_store_dwordx4 v0, v[106:109], s[14:15] offset:0 nt
	global_store_dwordx4 v0, v[110:113], s[14:15] offset:1024 nt
	global_store_dwordx4 v0, v[114:117], s[14:15] offset:2048 nt
	global_store_dwordx4 v0, v[118:121], s[14:15] offset:3072 nt
	s_add_u32 s14, s14, 0x1000
	s_addc_u32 s15, s15, 0
	v_mul_f32_e32 v6, v106, v106
	v_mul_f32_e32 v7, v107, v107
	v_fmac_f32_e32 v6, v108, v108
	v_fmac_f32_e32 v7, v109, v109
	v_fmac_f32_e32 v6, v110, v110
	v_fmac_f32_e32 v7, v111, v111
	v_fmac_f32_e32 v6, v112, v112
	v_fmac_f32_e32 v7, v113, v113
	v_fmac_f32_e32 v6, v114, v114
	v_fmac_f32_e32 v7, v115, v115
	v_fmac_f32_e32 v6, v116, v116
	v_fmac_f32_e32 v7, v117, v117
	v_fmac_f32_e32 v6, v118, v118
	v_fmac_f32_e32 v7, v119, v119
	v_fmac_f32_e32 v6, v120, v120
	v_fmac_f32_e32 v7, v121, v121
	v_add_f32_e32 v6, v6, v7
	s_nop 1
	v_add_f32_dpp v8, v6, v6 quad_perm:[1,0,3,2] row_mask:0xf bank_mask:0xf
	s_nop 1
	v_add_f32_dpp v8, v8, v8 quad_perm:[2,3,0,1] row_mask:0xf bank_mask:0xf
	s_nop 1
	v_add_f32_dpp v8, v8, v8 row_half_mirror row_mask:0xf bank_mask:0xf
	s_nop 1
	v_add_f32_dpp v8, v8, v8 row_mirror row_mask:0xf bank_mask:0xf
	s_nop 1
	v_add_f32_dpp v8, v8, v8 row_bcast:15 row_mask:0xa bank_mask:0xf
	s_nop 1
	v_add_f32_dpp v8, v8, v8 row_bcast:31 row_mask:0xc bank_mask:0xf
	s_nop 1
	v_readlane_b32 s84, v8, 63
	s_nop 1
	v_fma_f32 v4, s84, v2, v3
	v_rsq_f32_e32 v4, v4
	s_nop 0
	v_pk_mul_f32 v[34:35], v[106:107], v[4:5] op_sel_hi:[1,0]
	v_pk_mul_f32 v[36:37], v[108:109], v[4:5] op_sel_hi:[1,0]
	v_pk_mul_f32 v[38:39], v[110:111], v[4:5] op_sel_hi:[1,0]
	v_pk_mul_f32 v[40:41], v[112:113], v[4:5] op_sel_hi:[1,0]
	v_pk_mul_f32 v[42:43], v[114:115], v[4:5] op_sel_hi:[1,0]
	v_pk_mul_f32 v[44:45], v[116:117], v[4:5] op_sel_hi:[1,0]
	v_pk_mul_f32 v[46:47], v[118:119], v[4:5] op_sel_hi:[1,0]
	v_pk_mul_f32 v[48:49], v[120:121], v[4:5] op_sel_hi:[1,0]
	v_pk_mul_f32 v[34:35], v[34:35], v[192:193]
	v_pk_mul_f32 v[36:37], v[36:37], v[194:195]
	v_pk_mul_f32 v[38:39], v[38:39], v[196:197]
	v_pk_mul_f32 v[40:41], v[40:41], v[198:199]
	v_pk_mul_f32 v[42:43], v[42:43], v[200:201]
	v_pk_mul_f32 v[44:45], v[44:45], v[202:203]
	v_pk_mul_f32 v[46:47], v[46:47], v[204:205]
	v_pk_mul_f32 v[48:49], v[48:49], v[206:207]
	v_pk_fma_f32 v[34:35], v[34:35], v[208:209], v[228:229]
	v_pk_fma_f32 v[36:37], v[36:37], v[210:211], v[230:231]
	v_pk_fma_f32 v[38:39], v[38:39], v[212:213], v[232:233]
	v_pk_fma_f32 v[40:41], v[40:41], v[214:215], v[234:235]
	v_pk_fma_f32 v[42:43], v[42:43], v[220:221], v[236:237]
	v_pk_fma_f32 v[44:45], v[44:45], v[222:223], v[238:239]
	v_pk_fma_f32 v[46:47], v[46:47], v[224:225], v[26:27]
	v_pk_fma_f32 v[48:49], v[48:49], v[226:227], v[28:29]
	v_cvt_pk_bf16_f32 v50, v34, v35
	v_cvt_pk_bf16_f32 v51, v36, v37
	v_cvt_pk_bf16_f32 v52, v38, v39
	v_cvt_pk_bf16_f32 v53, v40, v41
	v_cvt_pk_bf16_f32 v54, v42, v43
	v_cvt_pk_bf16_f32 v55, v44, v45
	v_cvt_pk_bf16_f32 v56, v46, v47
	v_cvt_pk_bf16_f32 v57, v48, v49
	global_store_dwordx2 v1, v[50:51], s[16:17] offset:0
	global_store_dwordx2 v1, v[52:53], s[16:17] offset:512
	global_store_dwordx2 v1, v[54:55], s[16:17] offset:1024
	global_store_dwordx2 v1, v[56:57], s[16:17] offset:1536
	s_add_u32 s16, s16, 0x800
	s_addc_u32 s17, s17, 0
	s_add_u32 s32, s32, s27
	s_branch .Lnrm_B_lat_loop

; __device__ __forceinline__ unsigned xb_ld(unsigned* p)              { return __hip_atomic_load(p, __ATOMIC_RELAXED, __HIP_MEMORY_SCOPE_AGENT); }
; __device__ __forceinline__ unsigned xb_add(unsigned* p, unsigned v) { return __hip_atomic_fetch_add(p, v, __ATOMIC_RELAXED, __HIP_MEMORY_SCOPE_AGENT); }
; #define XB_SPIN(cond, bar) do { unsigned _sp = 0; while (cond) { __builtin_amdgcn_s_sleep(1); \
;     if ((++_sp & 255u) == 0u) { if (xb_ld(&(bar)[XB_TMO])) break; if (_sp > XB_SPIN_CAP) { atomicAdd(&(bar)[XB_TMO], 1u); break; } } } } while (0)
; __device__ __forceinline__ void xcd_barrier(const XcdBarrier& b) {
;     ...
;         const unsigned old = xb_add(&bar[XB_XSUB(b.x)], 1u);
;         const unsigned gen = old / nloc;
;         if (old + 1u == (gen + 1u) * nloc) {
;             __builtin_amdgcn_fence(__ATOMIC_RELEASE, "agent");
;             asm volatile("s_waitcnt vmcnt(0)" ::: "memory");
;             const unsigned og = xb_add(&bar[XB_TOP], 1u);
;             const unsigned tg = og / nx;
;             if (og + 1u == (tg + 1u) * nx) xb_add(&bar[XB_TOPGEN], 1u);
;             else XB_SPIN(xb_ld(&bar[XB_TOPGEN]) == tg, bar);
;             __builtin_amdgcn_fence(__ATOMIC_ACQUIRE, "agent");
;             xb_add(&bar[XB_XGEN(b.x)], 1u);
;             asm volatile("s_waitcnt vmcnt(0)" ::: "memory");
;         } else {
;             XB_SPIN(xb_ld(&bar[XB_XGEN(b.x)]) == gen, bar);
.LBB0_29:
	s_or_b64 exec, exec, s[12:13]
	v_cvt_f32_u32_e32 v4, v2
	s_waitcnt vmcnt(1)
	v_readfirstlane_b32 s0, v3
	v_sub_u32_e32 v3, 0, v2
	v_rcp_iflag_f32_e32 v4, v4
	v_add_u32_e32 v5, s0, v1
	v_mul_f32_e32 v4, 0x4f7ffffe, v4
	v_cvt_u32_f32_e32 v4, v4
	v_mul_lo_u32 v1, v3, v4
	v_mul_hi_u32 v1, v4, v1
	v_add_u32_e32 v1, v4, v1
	v_mul_hi_u32 v1, v5, v1
	v_mul_lo_u32 v3, v1, v2
	v_sub_u32_e32 v3, v5, v3
	v_add_u32_e32 v4, 1, v1
	v_cmp_ge_u32_e32 vcc, v3, v2
	s_nop 1
	v_cndmask_b32_e32 v1, v1, v4, vcc
	v_sub_u32_e32 v4, v3, v2
	v_cndmask_b32_e32 v3, v3, v4, vcc
	v_add_u32_e32 v4, 1, v1
	v_cmp_ge_u32_e32 vcc, v3, v2
	v_add_u32_e32 v3, 1, v5
	s_nop 0
	v_cndmask_b32_e32 v1, v1, v4, vcc
	v_mul_lo_u32 v4, v2, v1
	v_add_u32_e32 v2, v4, v2
	v_cmp_ne_u32_e32 vcc, v3, v2
	s_and_saveexec_b64 s[0:1], vcc
	s_xor_b64 s[12:13], exec, s[0:1]
	s_cbranch_execz .LBB0_43
	v_readlane_b32 s0, v253, 14
	v_readlane_b32 s1, v253, 15
	s_waitcnt lgkmcnt(0)
	s_nop 3
	global_load_dword v0, v33, s[0:1] sc1
	s_waitcnt vmcnt(0)
	v_cmp_eq_u32_e32 vcc, v0, v1
	s_and_saveexec_b64 s[14:15], vcc
	s_cbranch_execz .LBB0_42
	s_mov_b32 s0, 1
	s_mov_b64 s[16:17], 0
	s_branch .LBB0_33

; __device__ __forceinline__ unsigned xb_ld(unsigned* p)              { return __hip_atomic_load(p, __ATOMIC_RELAXED, __HIP_MEMORY_SCOPE_AGENT); }
; #define XB_SPIN(cond, bar) do { unsigned _sp = 0; while (cond) { __builtin_amdgcn_s_sleep(1); \
;     if ((++_sp & 255u) == 0u) { if (xb_ld(&(bar)[XB_TMO])) break; if (_sp > XB_SPIN_CAP) { atomicAdd(&(bar)[XB_TMO], 1u); break; } } } } while (0)
; __device__ __forceinline__ void xcd_barrier(const XcdBarrier& b) {
;     ...
;             XB_SPIN(xb_ld(&bar[XB_XGEN(b.x)]) == gen, bar);
;             __builtin_amdgcn_fence(__ATOMIC_ACQUIRE, "agent");
.LBB0_35:
	v_readlane_b32 s20, v253, 14
	v_readlane_b32 s21, v253, 15
	s_add_i32 s0, s0, 1
	s_mov_b64 s[22:23], -1
	s_nop 2
	global_load_dword v0, v33, s[20:21] sc1
	s_waitcnt vmcnt(0)
	v_cmp_ne_u32_e32 vcc, v0, v1
	s_orn2_b64 s[20:21], vcc, exec
	s_branch .LBB0_32

; __device__ __forceinline__ unsigned xb_ld(unsigned* p)              { return __hip_atomic_load(p, __ATOMIC_RELAXED, __HIP_MEMORY_SCOPE_AGENT); }
; __device__ __forceinline__ unsigned xb_add(unsigned* p, unsigned v) { return __hip_atomic_fetch_add(p, v, __ATOMIC_RELAXED, __HIP_MEMORY_SCOPE_AGENT); }
; #define XB_SPIN(cond, bar) do { unsigned _sp = 0; while (cond) { __builtin_amdgcn_s_sleep(1); \
;     if ((++_sp & 255u) == 0u) { if (xb_ld(&(bar)[XB_TMO])) break; if (_sp > XB_SPIN_CAP) { atomicAdd(&(bar)[XB_TMO], 1u); break; } } } } while (0)
; __device__ __forceinline__ void xcd_barrier(const XcdBarrier& b) {
;     ...
;         const unsigned old = xb_add(&bar[XB_XSUB(b.x)], 1u);
;         const unsigned gen = old / nloc;
;         if (old + 1u == (gen + 1u) * nloc) {
;             __builtin_amdgcn_fence(__ATOMIC_RELEASE, "agent");
;             asm volatile("s_waitcnt vmcnt(0)" ::: "memory");
;             const unsigned og = xb_add(&bar[XB_TOP], 1u);
;             const unsigned tg = og / nx;
;             if (og + 1u == (tg + 1u) * nx) xb_add(&bar[XB_TOPGEN], 1u);
;             else XB_SPIN(xb_ld(&bar[XB_TOPGEN]) == tg, bar);
;             __builtin_amdgcn_fence(__ATOMIC_ACQUIRE, "agent");
;             xb_add(&bar[XB_XGEN(b.x)], 1u);
;             asm volatile("s_waitcnt vmcnt(0)" ::: "memory");
;         } else {
;             XB_SPIN(xb_ld(&bar[XB_XGEN(b.x)]) == gen, bar);
.LBB0_276:
	s_or_b64 exec, exec, s[18:19]
	v_cvt_f32_u32_e32 v4, v2
	s_waitcnt vmcnt(1)
	v_readfirstlane_b32 s0, v3
	v_sub_u32_e32 v3, 0, v2
	v_rcp_iflag_f32_e32 v4, v4
	v_add_u32_e32 v5, s0, v1
	v_mul_f32_e32 v4, 0x4f7ffffe, v4
	v_cvt_u32_f32_e32 v4, v4
	v_mul_lo_u32 v1, v3, v4
	v_mul_hi_u32 v1, v4, v1
	v_add_u32_e32 v1, v4, v1
	v_mul_hi_u32 v1, v5, v1
	v_mul_lo_u32 v3, v1, v2
	v_sub_u32_e32 v3, v5, v3
	v_add_u32_e32 v4, 1, v1
	v_cmp_ge_u32_e32 vcc, v3, v2
	s_nop 1
	v_cndmask_b32_e32 v1, v1, v4, vcc
	v_sub_u32_e32 v4, v3, v2
	v_cndmask_b32_e32 v3, v3, v4, vcc
	v_add_u32_e32 v4, 1, v1
	v_cmp_ge_u32_e32 vcc, v3, v2
	v_add_u32_e32 v3, 1, v5
	s_nop 0
	v_cndmask_b32_e32 v1, v1, v4, vcc
	v_mul_lo_u32 v4, v2, v1
	v_add_u32_e32 v2, v4, v2
	v_cmp_ne_u32_e32 vcc, v3, v2
	s_and_saveexec_b64 s[0:1], vcc
	s_xor_b64 s[20:21], exec, s[0:1]
	s_cbranch_execz .LBB0_290
	v_readlane_b32 s0, v253, 14
	v_readlane_b32 s1, v253, 15
	s_waitcnt lgkmcnt(0)
	s_nop 3
	global_load_dword v0, v33, s[0:1] sc1
	s_waitcnt vmcnt(0)
	v_cmp_eq_u32_e32 vcc, v0, v1
	s_and_saveexec_b64 s[18:19], vcc
	s_cbranch_execz .LBB0_289
	s_mov_b32 s0, 1
	s_mov_b64 s[22:23], 0
	s_branch .LBB0_280

; __device__ __forceinline__ unsigned xb_ld(unsigned* p)              { return __hip_atomic_load(p, __ATOMIC_RELAXED, __HIP_MEMORY_SCOPE_AGENT); }
; #define XB_SPIN(cond, bar) do { unsigned _sp = 0; while (cond) { __builtin_amdgcn_s_sleep(1); \
;     if ((++_sp & 255u) == 0u) { if (xb_ld(&(bar)[XB_TMO])) break; if (_sp > XB_SPIN_CAP) { atomicAdd(&(bar)[XB_TMO], 1u); break; } } } } while (0)
; __device__ __forceinline__ void xcd_barrier(const XcdBarrier& b) {
;     ...
;             XB_SPIN(xb_ld(&bar[XB_XGEN(b.x)]) == gen, bar);
;             __builtin_amdgcn_fence(__ATOMIC_ACQUIRE, "agent");
.LBB0_282:
	v_readlane_b32 s12, v253, 14
	v_readlane_b32 s13, v253, 15
	s_add_i32 s0, s0, 1
	s_mov_b64 s[40:41], -1
	s_nop 2
	global_load_dword v0, v33, s[12:13] sc1
	s_waitcnt vmcnt(0)
	v_cmp_ne_u32_e32 vcc, v0, v1
	s_orn2_b64 s[26:27], vcc, exec
	s_branch .LBB0_279
